# k-inner+snake, no mid flip, redundant post-barrier s_waitcnt lgkmcnt(0) removed (MFMA stream starts one slot earlier)
# speedup vs baseline: 1.0070x; 1.0070x over previous
; #define PG8_STAGE(bufoff, gbase, voff) do { _Pragma("unroll") for (int _i = 0; _i < 2; ++_i) \
;         __builtin_amdgcn_global_load_lds((const unsigned*)((const char*)(gbase) + (voff)[_i]), (PG8_LAS unsigned*)(lds + (bufoff) + ldsw + _i * 8192), 16, 0, 0); } while (0)
; #define PG8_LDA(dst, b, h) do { _Pragma("unroll") for (int m = 0; m < 4; ++m) _Pragma("unroll") for (int k = 0; k < 2; ++k) dst[m][k] = *(const PG8_LAS bf16x8*)(lds + PG8_SA(b, h) + aoff + m * 2048 + k * 1024); } while (0)
; #define PG8_MMA(ai, bj, At, Bt) do { __builtin_amdgcn_s_setprio(3); _Pragma("unroll") for (int m = 0; m < 4; ++m) _Pragma("unroll") for (int n = 0; n < 2; ++n) _Pragma("unroll") for (int k = 0; k < 2; ++k) \
;         acc[ai][bj][m][n] = __builtin_amdgcn_mfma_f32_16x16x32_bf16(Bt[n][k], At[m][k], acc[ai][bj][m][n], 0, 0, 0); __builtin_amdgcn_s_setprio(0); } while (0)
; #define PG8_WAIT_V(n) asm volatile("s_waitcnt vmcnt(" #n ")" ::: "memory")
; #define PG8_WAIT_L(n) asm volatile("s_waitcnt lgkmcnt(" #n ")" ::: "memory")
; #define PG8_BAR __builtin_amdgcn_s_barrier()
; #define PG8_SCHED __builtin_amdgcn_sched_barrier(0)
; template <class Epi, class Sched, bool ALIGN_EPI = false, bool SP2 = false>
; __device__ __forceinline__ void gemm_phase(PG8_LAS unsigned char* lds, const Gemm g, const Sched& S, const Epi& E) {
;     ...
;             PG8_WAIT_V(8); PG8_WAIT_L(0); PG8_BAR; PG8_MMA(0, 0, At, B0); PG8_MMA(0, 1, At, B1); PG8_BAR; PG8_SCHED;
;             PG8_LDA(At, 0, 1); PG8_STAGE(PG8_SB(0, 0), b2, voffB); PG8_STAGE(PG8_SB(0, 1), b2 + hstepB, voffB); PG8_STAGE(PG8_SA(0, 0), a2, voffA);
;             PG8_WAIT_V(8); PG8_WAIT_L(0); PG8_BAR; PG8_MMA(1, 0, At, B0); PG8_MMA(1, 1, At, B1); PG8_BAR; PG8_SCHED;
.Lengw1_e:
	s_waitcnt lgkmcnt(0)
	s_barrier
	s_setprio 3
	v_mfma_f32_16x16x32_bf16 v[126:129], v[130:133], v[192:195], v[126:129]
	v_mfma_f32_16x16x32_bf16 v[126:129], v[134:137], v[196:199], v[126:129]
	v_mfma_f32_16x16x32_bf16 v[118:121], v[156:159], v[192:195], v[118:121]
	v_mfma_f32_16x16x32_bf16 v[118:121], v[172:175], v[196:199], v[118:121]
	v_mfma_f32_16x16x32_bf16 v[102:105], v[156:159], v[200:203], v[102:105]
	v_mfma_f32_16x16x32_bf16 v[102:105], v[172:175], v[204:207], v[102:105]
	v_mfma_f32_16x16x32_bf16 v[110:113], v[130:133], v[200:203], v[110:113]
	v_mfma_f32_16x16x32_bf16 v[110:113], v[134:137], v[204:207], v[110:113]
	v_mfma_f32_16x16x32_bf16 v[94:97], v[130:133], v[208:211], v[94:97]
	v_mfma_f32_16x16x32_bf16 v[94:97], v[134:137], v[212:215], v[94:97]
	v_mfma_f32_16x16x32_bf16 v[86:89], v[156:159], v[208:211], v[86:89]
	v_mfma_f32_16x16x32_bf16 v[86:89], v[172:175], v[212:215], v[86:89]
	v_mfma_f32_16x16x32_bf16 v[70:73], v[156:159], v[216:219], v[70:73]
	v_mfma_f32_16x16x32_bf16 v[70:73], v[172:175], v[220:223], v[70:73]
	v_mfma_f32_16x16x32_bf16 v[78:81], v[130:133], v[216:219], v[78:81]
	v_mfma_f32_16x16x32_bf16 v[78:81], v[134:137], v[220:223], v[78:81]
	v_mfma_f32_16x16x32_bf16 v[122:125], v[176:179], v[192:195], v[122:125]
	v_mfma_f32_16x16x32_bf16 v[122:125], v[180:183], v[196:199], v[122:125]
	v_mfma_f32_16x16x32_bf16 v[114:117], v[184:187], v[192:195], v[114:117]
	v_mfma_f32_16x16x32_bf16 v[114:117], v[188:191], v[196:199], v[114:117]
	v_mfma_f32_16x16x32_bf16 v[98:101], v[184:187], v[200:203], v[98:101]
	v_mfma_f32_16x16x32_bf16 v[98:101], v[188:191], v[204:207], v[98:101]
	v_mfma_f32_16x16x32_bf16 v[106:109], v[176:179], v[200:203], v[106:109]
	v_mfma_f32_16x16x32_bf16 v[106:109], v[180:183], v[204:207], v[106:109]
	v_mfma_f32_16x16x32_bf16 v[90:93], v[176:179], v[208:211], v[90:93]
	v_mfma_f32_16x16x32_bf16 v[90:93], v[180:183], v[212:215], v[90:93]
	v_mfma_f32_16x16x32_bf16 v[82:85], v[184:187], v[208:211], v[82:85]
	v_mfma_f32_16x16x32_bf16 v[82:85], v[188:191], v[212:215], v[82:85]
	v_mfma_f32_16x16x32_bf16 v[66:69], v[184:187], v[216:219], v[66:69]
	v_mfma_f32_16x16x32_bf16 v[66:69], v[188:191], v[220:223], v[66:69]
	v_mfma_f32_16x16x32_bf16 v[74:77], v[176:179], v[216:219], v[74:77]
	v_mfma_f32_16x16x32_bf16 v[74:77], v[180:183], v[220:223], v[74:77]
	s_setprio 0
	s_barrier
	s_add_i32 s56, s83, s66
	v_lshl_add_u64 v[160:161], s[8:9], 0, v[140:141]
	s_mov_b32 m0, s56
	ds_read_b128 v[192:195], v169 offset:16384
	ds_read_b128 v[196:199], v169 offset:17408
	ds_read_b128 v[200:203], v169 offset:18432
	ds_read_b128 v[204:207], v169 offset:19456
	ds_read_b128 v[208:211], v169 offset:20480
	ds_read_b128 v[212:215], v169 offset:21504
	ds_read_b128 v[216:219], v169 offset:22528
	ds_read_b128 v[220:223], v169 offset:23552
	global_load_lds_dwordx4 v[160:161], off
	s_add_i32 m0, s56, 0x2000
	s_add_u32 s56, s8, 0x100000
	v_lshl_add_u64 v[224:225], s[8:9], 0, v[144:145]
	s_addc_u32 s57, s9, 0
	s_add_i32 s58, s89, s66
	global_load_lds_dwordx4 v[224:225], off
	v_lshl_add_u64 v[226:227], s[56:57], 0, v[140:141]
	s_mov_b32 m0, s58
	v_lshl_add_u64 v[228:229], s[36:37], 0, v[142:143]
	global_load_lds_dwordx4 v[226:227], off
	v_lshl_add_u64 v[226:227], s[56:57], 0, v[144:145]
	s_add_i32 m0, s58, 0x2000
	s_nop 0
	global_load_lds_dwordx4 v[226:227], off
	v_lshl_add_u64 v[226:227], s[36:37], 0, v[138:139]
	s_mov_b32 m0, s55
	s_nop 0
	global_load_lds_dwordx4 v[226:227], off
	s_mov_b32 m0, s67
	s_nop 0
	global_load_lds_dwordx4 v[228:229], off
	s_cmp_eq_u32 s97, 0
	s_cbranch_scc1 .Lengw2_a
	s_cmp_eq_u32 s97, 2
	s_cbranch_scc1 .Lengw2_b
	s_cmp_eq_u32 s97, 4
	s_cbranch_scc1 .Lengw2_c
	s_waitcnt vmcnt(16)
	s_branch .Lengw2_e

; #define PG8_STAGE(bufoff, gbase, voff) do { _Pragma("unroll") for (int _i = 0; _i < 2; ++_i) \
;         __builtin_amdgcn_global_load_lds((const unsigned*)((const char*)(gbase) + (voff)[_i]), (PG8_LAS unsigned*)(lds + (bufoff) + ldsw + _i * 8192), 16, 0, 0); } while (0)
; #define PG8_LDA(dst, b, h) do { _Pragma("unroll") for (int m = 0; m < 4; ++m) _Pragma("unroll") for (int k = 0; k < 2; ++k) dst[m][k] = *(const PG8_LAS bf16x8*)(lds + PG8_SA(b, h) + aoff + m * 2048 + k * 1024); } while (0)
; #define PG8_LDB(dst, b, h) do { _Pragma("unroll") for (int n = 0; n < 2; ++n) _Pragma("unroll") for (int k = 0; k < 2; ++k) dst[n][k] = *(const PG8_LAS bf16x8*)(lds + PG8_SB(b, h) + boff + n * 2048 + k * 1024); } while (0)
; #define PG8_MMA(ai, bj, At, Bt) do { __builtin_amdgcn_s_setprio(3); _Pragma("unroll") for (int m = 0; m < 4; ++m) _Pragma("unroll") for (int n = 0; n < 2; ++n) _Pragma("unroll") for (int k = 0; k < 2; ++k) \
;         acc[ai][bj][m][n] = __builtin_amdgcn_mfma_f32_16x16x32_bf16(Bt[n][k], At[m][k], acc[ai][bj][m][n], 0, 0, 0); __builtin_amdgcn_s_setprio(0); } while (0)
; #define PG8_WAIT_V(n) asm volatile("s_waitcnt vmcnt(" #n ")" ::: "memory")
; #define PG8_WAIT_L(n) asm volatile("s_waitcnt lgkmcnt(" #n ")" ::: "memory")
; #define PG8_BAR __builtin_amdgcn_s_barrier()
; #define PG8_SCHED __builtin_amdgcn_sched_barrier(0)
; template <class Epi, class Sched, bool ALIGN_EPI = false, bool SP2 = false>
; __device__ __forceinline__ void gemm_phase(PG8_LAS unsigned char* lds, const Gemm g, const Sched& S, const Epi& E) {
;     ...
;             PG8_WAIT_V(8); PG8_WAIT_L(0); PG8_BAR; PG8_MMA(1, 0, At, B0); PG8_MMA(1, 1, At, B1); PG8_BAR; PG8_SCHED;
;             PG8_LDB(B0, 1, 0); PG8_LDB(B1, 1, 1); PG8_SCHED; PG8_LDA(At, 1, 0); PG8_STAGE(PG8_SA(0, 1), a2 + hstepA, voffA);
;             PG8_WAIT_V(8); PG8_WAIT_L(0); PG8_BAR; PG8_MMA(0, 0, At, B0); PG8_MMA(0, 1, At, B1); PG8_BAR; PG8_SCHED;
.Lengw2_e:
	s_waitcnt lgkmcnt(0)
	s_barrier
	s_setprio 3
	v_mfma_f32_16x16x32_bf16 v[62:65], v[130:133], v[192:195], v[62:65]
	v_mfma_f32_16x16x32_bf16 v[62:65], v[134:137], v[196:199], v[62:65]
	v_mfma_f32_16x16x32_bf16 v[54:57], v[156:159], v[192:195], v[54:57]
	v_mfma_f32_16x16x32_bf16 v[54:57], v[172:175], v[196:199], v[54:57]
	v_mfma_f32_16x16x32_bf16 v[38:41], v[156:159], v[200:203], v[38:41]
	v_mfma_f32_16x16x32_bf16 v[38:41], v[172:175], v[204:207], v[38:41]
	v_mfma_f32_16x16x32_bf16 v[46:49], v[130:133], v[200:203], v[46:49]
	v_mfma_f32_16x16x32_bf16 v[46:49], v[134:137], v[204:207], v[46:49]
	v_mfma_f32_16x16x32_bf16 v[30:33], v[130:133], v[208:211], v[30:33]
	v_mfma_f32_16x16x32_bf16 v[30:33], v[134:137], v[212:215], v[30:33]
	v_mfma_f32_16x16x32_bf16 v[22:25], v[156:159], v[208:211], v[22:25]
	v_mfma_f32_16x16x32_bf16 v[22:25], v[172:175], v[212:215], v[22:25]
	v_mfma_f32_16x16x32_bf16 v[6:9], v[156:159], v[216:219], v[6:9]
	v_mfma_f32_16x16x32_bf16 v[6:9], v[172:175], v[220:223], v[6:9]
	v_mfma_f32_16x16x32_bf16 v[14:17], v[130:133], v[216:219], v[14:17]
	v_mfma_f32_16x16x32_bf16 v[14:17], v[134:137], v[220:223], v[14:17]
	v_mfma_f32_16x16x32_bf16 v[58:61], v[176:179], v[192:195], v[58:61]
	v_mfma_f32_16x16x32_bf16 v[58:61], v[180:183], v[196:199], v[58:61]
	v_mfma_f32_16x16x32_bf16 v[50:53], v[184:187], v[192:195], v[50:53]
	v_mfma_f32_16x16x32_bf16 v[50:53], v[188:191], v[196:199], v[50:53]
	v_mfma_f32_16x16x32_bf16 v[34:37], v[184:187], v[200:203], v[34:37]
	v_mfma_f32_16x16x32_bf16 v[34:37], v[188:191], v[204:207], v[34:37]
	v_mfma_f32_16x16x32_bf16 v[42:45], v[176:179], v[200:203], v[42:45]
	v_mfma_f32_16x16x32_bf16 v[42:45], v[180:183], v[204:207], v[42:45]
	v_mfma_f32_16x16x32_bf16 v[26:29], v[176:179], v[208:211], v[26:29]
	v_mfma_f32_16x16x32_bf16 v[26:29], v[180:183], v[212:215], v[26:29]
	v_mfma_f32_16x16x32_bf16 v[18:21], v[184:187], v[208:211], v[18:21]
	v_mfma_f32_16x16x32_bf16 v[18:21], v[188:191], v[212:215], v[18:21]
	v_mfma_f32_16x16x32_bf16 v[2:5], v[184:187], v[216:219], v[2:5]
	v_mfma_f32_16x16x32_bf16 v[2:5], v[188:191], v[220:223], v[2:5]
	v_mfma_f32_16x16x32_bf16 v[10:13], v[176:179], v[216:219], v[10:13]
	v_mfma_f32_16x16x32_bf16 v[10:13], v[180:183], v[220:223], v[10:13]
	s_setprio 0
	s_barrier
	s_add_i32 s56, 0, 0x18000
	v_add_u32_e32 v146, s56, v164
	s_add_i32 s57, 0, 0x1c000
	ds_read_b128 v[130:133], v146
	ds_read_b128 v[134:137], v146 offset:1024
	ds_read_b128 v[156:159], v146 offset:2048
	ds_read_b128 v[172:175], v146 offset:3072
	v_add_u32_e32 v146, s57, v164
	ds_read_b128 v[176:179], v146
	ds_read_b128 v[180:183], v146 offset:1024
	ds_read_b128 v[184:187], v146 offset:2048
	ds_read_b128 v[188:191], v146 offset:3072
	s_add_u32 s36, s36, 0x100000
	s_addc_u32 s37, s37, 0
	s_mov_b32 m0, s72
	v_lshl_add_u64 v[230:231], s[36:37], 0, v[138:139]
	ds_read_b128 v[192:195], v169 offset:32768
	ds_read_b128 v[196:199], v169 offset:33792
	ds_read_b128 v[200:203], v169 offset:34816
	ds_read_b128 v[204:207], v169 offset:35840
	ds_read_b128 v[208:211], v169 offset:36864
	ds_read_b128 v[212:215], v169 offset:37888
	ds_read_b128 v[216:219], v169 offset:38912
	ds_read_b128 v[220:223], v169 offset:39936
	global_load_lds_dwordx4 v[230:231], off
	v_lshl_add_u64 v[230:231], s[36:37], 0, v[142:143]
	s_mov_b32 m0, s73
	s_nop 0
	global_load_lds_dwordx4 v[230:231], off
	s_cmp_eq_u32 s97, 4
	s_cbranch_scc1 .Lengw3_c
	s_cmp_eq_u32 s97, 8
	s_cbranch_scc1 .Lengw3_d
	s_waitcnt vmcnt(8)
	s_branch .Lengw3_e

; #define PG8_STAGE(bufoff, gbase, voff) do { _Pragma("unroll") for (int _i = 0; _i < 2; ++_i) \
;         __builtin_amdgcn_global_load_lds((const unsigned*)((const char*)(gbase) + (voff)[_i]), (PG8_LAS unsigned*)(lds + (bufoff) + ldsw + _i * 8192), 16, 0, 0); } while (0)
; #define PG8_LDA(dst, b, h) do { _Pragma("unroll") for (int m = 0; m < 4; ++m) _Pragma("unroll") for (int k = 0; k < 2; ++k) dst[m][k] = *(const PG8_LAS bf16x8*)(lds + PG8_SA(b, h) + aoff + m * 2048 + k * 1024); } while (0)
; #define PG8_MMA(ai, bj, At, Bt) do { __builtin_amdgcn_s_setprio(3); _Pragma("unroll") for (int m = 0; m < 4; ++m) _Pragma("unroll") for (int n = 0; n < 2; ++n) _Pragma("unroll") for (int k = 0; k < 2; ++k) \
;         acc[ai][bj][m][n] = __builtin_amdgcn_mfma_f32_16x16x32_bf16(Bt[n][k], At[m][k], acc[ai][bj][m][n], 0, 0, 0); __builtin_amdgcn_s_setprio(0); } while (0)
; #define PG8_WAIT_V(n) asm volatile("s_waitcnt vmcnt(" #n ")" ::: "memory")
; #define PG8_WAIT_L(n) asm volatile("s_waitcnt lgkmcnt(" #n ")" ::: "memory")
; #define PG8_BAR __builtin_amdgcn_s_barrier()
; #define PG8_SCHED __builtin_amdgcn_sched_barrier(0)
; template <class Epi, class Sched, bool ALIGN_EPI = false, bool SP2 = false>
; __device__ __forceinline__ void gemm_phase(PG8_LAS unsigned char* lds, const Gemm g, const Sched& S, const Epi& E) {
;     ...
;             PG8_WAIT_V(8); PG8_WAIT_L(0); PG8_BAR; PG8_MMA(0, 0, At, B0); PG8_MMA(0, 1, At, B1); PG8_BAR; PG8_SCHED;
;             PG8_LDA(At, 1, 1); PG8_STAGE(PG8_SB(1, 0), b3, voffB); PG8_STAGE(PG8_SB(1, 1), b3 + hstepB, voffB); PG8_STAGE(PG8_SA(1, 0), a3, voffA);
;             PG8_WAIT_V(8); PG8_WAIT_L(0); PG8_BAR; PG8_MMA(1, 0, At, B0); PG8_MMA(1, 1, At, B1); PG8_BAR; PG8_SCHED;
;     ...
;         if constexpr (ALIGN_EPI) { if (wr == 0) PG8_BAR; }
;         if constexpr (!Epi::AFTER_DRAIN) { E(acc, cur, wr, wc, fr, fq); S.done(cur); }
.Lengw3_e:
	s_waitcnt lgkmcnt(0)
	s_barrier
	s_setprio 3
	v_mfma_f32_16x16x32_bf16 v[126:129], v[130:133], v[192:195], v[126:129]
	v_mfma_f32_16x16x32_bf16 v[126:129], v[134:137], v[196:199], v[126:129]
	v_mfma_f32_16x16x32_bf16 v[118:121], v[156:159], v[192:195], v[118:121]
	v_mfma_f32_16x16x32_bf16 v[118:121], v[172:175], v[196:199], v[118:121]
	v_mfma_f32_16x16x32_bf16 v[102:105], v[156:159], v[200:203], v[102:105]
	v_mfma_f32_16x16x32_bf16 v[102:105], v[172:175], v[204:207], v[102:105]
	v_mfma_f32_16x16x32_bf16 v[110:113], v[130:133], v[200:203], v[110:113]
	v_mfma_f32_16x16x32_bf16 v[110:113], v[134:137], v[204:207], v[110:113]
	v_mfma_f32_16x16x32_bf16 v[94:97], v[130:133], v[208:211], v[94:97]
	v_mfma_f32_16x16x32_bf16 v[94:97], v[134:137], v[212:215], v[94:97]
	v_mfma_f32_16x16x32_bf16 v[86:89], v[156:159], v[208:211], v[86:89]
	v_mfma_f32_16x16x32_bf16 v[86:89], v[172:175], v[212:215], v[86:89]
	v_mfma_f32_16x16x32_bf16 v[70:73], v[156:159], v[216:219], v[70:73]
	v_mfma_f32_16x16x32_bf16 v[70:73], v[172:175], v[220:223], v[70:73]
	v_mfma_f32_16x16x32_bf16 v[78:81], v[130:133], v[216:219], v[78:81]
	v_mfma_f32_16x16x32_bf16 v[78:81], v[134:137], v[220:223], v[78:81]
	v_mfma_f32_16x16x32_bf16 v[122:125], v[176:179], v[192:195], v[122:125]
	v_mfma_f32_16x16x32_bf16 v[122:125], v[180:183], v[196:199], v[122:125]
	v_mfma_f32_16x16x32_bf16 v[114:117], v[184:187], v[192:195], v[114:117]
	v_mfma_f32_16x16x32_bf16 v[114:117], v[188:191], v[196:199], v[114:117]
	v_mfma_f32_16x16x32_bf16 v[98:101], v[184:187], v[200:203], v[98:101]
	v_mfma_f32_16x16x32_bf16 v[98:101], v[188:191], v[204:207], v[98:101]
	v_mfma_f32_16x16x32_bf16 v[106:109], v[176:179], v[200:203], v[106:109]
	v_mfma_f32_16x16x32_bf16 v[106:109], v[180:183], v[204:207], v[106:109]
	v_mfma_f32_16x16x32_bf16 v[90:93], v[176:179], v[208:211], v[90:93]
	v_mfma_f32_16x16x32_bf16 v[90:93], v[180:183], v[212:215], v[90:93]
	v_mfma_f32_16x16x32_bf16 v[82:85], v[184:187], v[208:211], v[82:85]
	v_mfma_f32_16x16x32_bf16 v[82:85], v[188:191], v[212:215], v[82:85]
	v_mfma_f32_16x16x32_bf16 v[66:69], v[184:187], v[216:219], v[66:69]
	v_mfma_f32_16x16x32_bf16 v[66:69], v[188:191], v[220:223], v[66:69]
	v_mfma_f32_16x16x32_bf16 v[74:77], v[176:179], v[216:219], v[74:77]
	v_mfma_f32_16x16x32_bf16 v[74:77], v[180:183], v[220:223], v[74:77]
	s_setprio 0
	s_barrier
	s_add_i32 s36, s56, s66
	v_lshl_add_u64 v[160:161], v[160:161], 0, s[18:19]
	s_mov_b32 m0, s36
	ds_read_b128 v[192:195], v169 offset:49152
	ds_read_b128 v[196:199], v169 offset:50176
	ds_read_b128 v[200:203], v169 offset:51200
	ds_read_b128 v[204:207], v169 offset:52224
	ds_read_b128 v[208:211], v169 offset:53248
	ds_read_b128 v[212:215], v169 offset:54272
	ds_read_b128 v[216:219], v169 offset:55296
	ds_read_b128 v[220:223], v169 offset:56320
	global_load_lds_dwordx4 v[160:161], off
	s_add_i32 m0, s36, 0x2000
	s_add_u32 s8, s8, 0x100080
	v_lshl_add_u64 v[160:161], v[224:225], 0, s[18:19]
	s_addc_u32 s9, s9, 0
	s_add_i32 s36, s57, s66
	global_load_lds_dwordx4 v[160:161], off
	v_lshl_add_u64 v[160:161], s[8:9], 0, v[140:141]
	s_mov_b32 m0, s36
	s_nop 0
	global_load_lds_dwordx4 v[160:161], off
	v_lshl_add_u64 v[160:161], s[8:9], 0, v[144:145]
	s_add_i32 m0, s36, 0x2000
	s_nop 0
	global_load_lds_dwordx4 v[160:161], off
	v_lshl_add_u64 v[160:161], v[226:227], 0, s[18:19]
	s_mov_b32 m0, s75
	s_nop 0
	global_load_lds_dwordx4 v[160:161], off
	v_lshl_add_u64 v[160:161], v[228:229], 0, s[18:19]
	s_mov_b32 m0, s76
	s_nop 0
	global_load_lds_dwordx4 v[160:161], off
	s_waitcnt vmcnt(8)
	s_waitcnt lgkmcnt(0)
	s_barrier
	s_setprio 3
	v_mfma_f32_16x16x32_bf16 v[62:65], v[130:133], v[192:195], v[62:65]
	v_mfma_f32_16x16x32_bf16 v[62:65], v[134:137], v[196:199], v[62:65]
	v_mfma_f32_16x16x32_bf16 v[54:57], v[156:159], v[192:195], v[54:57]
	v_mfma_f32_16x16x32_bf16 v[54:57], v[172:175], v[196:199], v[54:57]
	v_mfma_f32_16x16x32_bf16 v[38:41], v[156:159], v[200:203], v[38:41]
	v_mfma_f32_16x16x32_bf16 v[38:41], v[172:175], v[204:207], v[38:41]
	v_mfma_f32_16x16x32_bf16 v[46:49], v[130:133], v[200:203], v[46:49]
	v_mfma_f32_16x16x32_bf16 v[46:49], v[134:137], v[204:207], v[46:49]
	v_mfma_f32_16x16x32_bf16 v[30:33], v[130:133], v[208:211], v[30:33]
	v_mfma_f32_16x16x32_bf16 v[30:33], v[134:137], v[212:215], v[30:33]
	v_mfma_f32_16x16x32_bf16 v[22:25], v[156:159], v[208:211], v[22:25]
	v_mfma_f32_16x16x32_bf16 v[22:25], v[172:175], v[212:215], v[22:25]
	v_mfma_f32_16x16x32_bf16 v[6:9], v[156:159], v[216:219], v[6:9]
	v_mfma_f32_16x16x32_bf16 v[6:9], v[172:175], v[220:223], v[6:9]
	v_mfma_f32_16x16x32_bf16 v[14:17], v[130:133], v[216:219], v[14:17]
	v_mfma_f32_16x16x32_bf16 v[14:17], v[134:137], v[220:223], v[14:17]
	v_mfma_f32_16x16x32_bf16 v[58:61], v[176:179], v[192:195], v[58:61]
	v_mfma_f32_16x16x32_bf16 v[58:61], v[180:183], v[196:199], v[58:61]
	v_mfma_f32_16x16x32_bf16 v[50:53], v[184:187], v[192:195], v[50:53]
	v_mfma_f32_16x16x32_bf16 v[50:53], v[188:191], v[196:199], v[50:53]
	v_mfma_f32_16x16x32_bf16 v[34:37], v[184:187], v[200:203], v[34:37]
	v_mfma_f32_16x16x32_bf16 v[34:37], v[188:191], v[204:207], v[34:37]
	v_mfma_f32_16x16x32_bf16 v[42:45], v[176:179], v[200:203], v[42:45]
	v_mfma_f32_16x16x32_bf16 v[42:45], v[180:183], v[204:207], v[42:45]
	v_mfma_f32_16x16x32_bf16 v[26:29], v[176:179], v[208:211], v[26:29]
	v_mfma_f32_16x16x32_bf16 v[26:29], v[180:183], v[212:215], v[26:29]
	v_mfma_f32_16x16x32_bf16 v[18:21], v[184:187], v[208:211], v[18:21]
	v_mfma_f32_16x16x32_bf16 v[18:21], v[188:191], v[212:215], v[18:21]
	v_mfma_f32_16x16x32_bf16 v[2:5], v[184:187], v[216:219], v[2:5]
	v_mfma_f32_16x16x32_bf16 v[2:5], v[188:191], v[220:223], v[2:5]
	v_mfma_f32_16x16x32_bf16 v[10:13], v[176:179], v[216:219], v[10:13]
	v_mfma_f32_16x16x32_bf16 v[10:13], v[180:183], v[220:223], v[10:13]
	s_setprio 0
	s_barrier
	s_add_i32 s45, s45, 2
	s_add_u32 s6, s6, 0x100
	s_addc_u32 s7, s7, 0
	s_add_u32 s33, s33, 0x100
	s_addc_u32 s44, s44, 0
	s_cmp_gt_u32 s45, 61
	s_cbranch_scc0 .LBB0_143
	s_and_b64 vcc, exec, s[20:21]
	s_cbranch_vccz .LBB0_148
	s_barrier
	v_lshl_add_u32 v156, s0, 8, v163
	s_cmp_lt_i32 s54, 40
	s_mov_b64 s[0:1], -1
	s_cbranch_scc1 .LBB0_149

; #define PG8_STAGE(bufoff, gbase, voff) do { _Pragma("unroll") for (int _i = 0; _i < 2; ++_i) \
;         __builtin_amdgcn_global_load_lds((const unsigned*)((const char*)(gbase) + (voff)[_i]), (PG8_LAS unsigned*)(lds + (bufoff) + ldsw + _i * 8192), 16, 0, 0); } while (0)
; #define PG8_LDA(dst, b, h) do { _Pragma("unroll") for (int m = 0; m < 4; ++m) _Pragma("unroll") for (int k = 0; k < 2; ++k) dst[m][k] = *(const PG8_LAS bf16x8*)(lds + PG8_SA(b, h) + aoff + m * 2048 + k * 1024); } while (0)
; #define PG8_LDB(dst, b, h) do { _Pragma("unroll") for (int n = 0; n < 2; ++n) _Pragma("unroll") for (int k = 0; k < 2; ++k) dst[n][k] = *(const PG8_LAS bf16x8*)(lds + PG8_SB(b, h) + boff + n * 2048 + k * 1024); } while (0)
; #define PG8_MMA(ai, bj, At, Bt) do { __builtin_amdgcn_s_setprio(3); _Pragma("unroll") for (int m = 0; m < 4; ++m) _Pragma("unroll") for (int n = 0; n < 2; ++n) _Pragma("unroll") for (int k = 0; k < 2; ++k) \
;         acc[ai][bj][m][n] = __builtin_amdgcn_mfma_f32_16x16x32_bf16(Bt[n][k], At[m][k], acc[ai][bj][m][n], 0, 0, 0); __builtin_amdgcn_s_setprio(0); } while (0)
; #define PG8_WAIT_V(n) asm volatile("s_waitcnt vmcnt(" #n ")" ::: "memory")
; template <class Epi, class Sched, bool ALIGN_EPI = false, bool SP2 = false>
; __device__ __forceinline__ void gemm_phase(PG8_LAS unsigned char* lds, const Gemm g, const Sched& S, const Epi& E) {
;     ...
;             const bool last = (t == nt - 2);
;             const char* a1 = cA + (size_t)(t + 1) * kstep;
;             const char* a2 = last ? nA : cA + (size_t)(t + 2) * kstep; const char* b2 = last ? nB : cB + (size_t)(t + 2) * kstep;
;             const char* a3 = a2 + kstep; const char* b3 = b2 + kstep;
;             if (last && has_next) S.a_ready(nxt);
;             if constexpr (Epi::MIDK) { if (t == E.midk_step(nt)) E.midk(acc, cur, wr, wc, fr, fq); }
;             if constexpr (SP2) {
;             PG8_LDB(B0, 0, 0); PG8_LDB(B1, 0, 1); PG8_SCHED; PG8_LDA(At, 0, 0); PG8_STAGE(PG8_SA(1, 1), a1 + hstepA, voffA);
;             PG8_WAIT_V(8); PG8_WAIT_L(0); PG8_BAR; PG8_MMA(0, 0, At, B0); PG8_MMA(0, 1, At, B1); PG8_BAR; PG8_SCHED;
;             PG8_LDA(At, 0, 1); PG8_STAGE(PG8_SB(0, 0), b2, voffB); PG8_STAGE(PG8_SB(0, 1), b2 + hstepB, voffB); PG8_STAGE(PG8_SA(0, 0), a2, voffA);
;             PG8_WAIT_V(8); PG8_WAIT_L(0); PG8_BAR; PG8_MMA(1, 0, At, B0); PG8_MMA(1, 1, At, B1); PG8_BAR; PG8_SCHED;
.LBB0_478:
	ds_read_b128 v[130:133], v170
	ds_read_b128 v[134:137], v170 offset:1024
	ds_read_b128 v[138:141], v170 offset:2048
	ds_read_b128 v[142:145], v170 offset:3072
	ds_read_b128 v[164:167], v171
	ds_read_b128 v[174:177], v171 offset:1024
	ds_read_b128 v[178:181], v171 offset:2048
	ds_read_b128 v[182:185], v171 offset:3072
	s_add_u32 s36, s6, 0xfff80080
	s_addc_u32 s37, s7, -1
	s_cmp_eq_u32 s79, 4
	s_cselect_b32 s59, s27, s37
	s_cselect_b32 s58, s26, s36
	s_cselect_b32 s37, s23, s78
	s_cselect_b32 s36, s25, s77
	v_lshl_add_u64 v[218:219], s[6:7], 0, v[154:155]
	s_add_i32 m0, s31, 0xc000
	ds_read_b128 v[186:189], v172
	ds_read_b128 v[190:193], v172 offset:1024
	ds_read_b128 v[194:197], v172 offset:2048
	ds_read_b128 v[198:201], v172 offset:3072
	ds_read_b128 v[202:205], v172 offset:4096
	ds_read_b128 v[206:209], v172 offset:5120
	ds_read_b128 v[210:213], v172 offset:6144
	ds_read_b128 v[214:217], v172 offset:7168
	global_load_lds_dwordx4 v[218:219], off
	v_lshl_add_u64 v[218:219], s[6:7], 0, v[156:157]
	s_add_i32 m0, s31, 0xe000
	s_nop 0
	global_load_lds_dwordx4 v[218:219], off
	s_waitcnt vmcnt(8)
	s_waitcnt lgkmcnt(0)
	s_barrier
	s_setprio 3
	v_mfma_f32_16x16x32_bf16 v[126:129], v[130:133], v[186:189], v[126:129]
	v_mfma_f32_16x16x32_bf16 v[126:129], v[134:137], v[190:193], v[126:129]
	v_mfma_f32_16x16x32_bf16 v[122:125], v[138:141], v[186:189], v[122:125]
	v_mfma_f32_16x16x32_bf16 v[122:125], v[142:145], v[190:193], v[122:125]
	v_mfma_f32_16x16x32_bf16 v[114:117], v[138:141], v[194:197], v[114:117]
	v_mfma_f32_16x16x32_bf16 v[114:117], v[142:145], v[198:201], v[114:117]
	v_mfma_f32_16x16x32_bf16 v[118:121], v[130:133], v[194:197], v[118:121]
	v_mfma_f32_16x16x32_bf16 v[118:121], v[134:137], v[198:201], v[118:121]
	v_mfma_f32_16x16x32_bf16 v[110:113], v[130:133], v[202:205], v[110:113]
	v_mfma_f32_16x16x32_bf16 v[110:113], v[134:137], v[206:209], v[110:113]
	v_mfma_f32_16x16x32_bf16 v[102:105], v[138:141], v[202:205], v[102:105]
	v_mfma_f32_16x16x32_bf16 v[102:105], v[142:145], v[206:209], v[102:105]
	v_mfma_f32_16x16x32_bf16 v[74:77], v[138:141], v[210:213], v[74:77]
	v_mfma_f32_16x16x32_bf16 v[74:77], v[142:145], v[214:217], v[74:77]
	v_mfma_f32_16x16x32_bf16 v[78:81], v[130:133], v[210:213], v[78:81]
	v_mfma_f32_16x16x32_bf16 v[78:81], v[134:137], v[214:217], v[78:81]
	v_mfma_f32_16x16x32_bf16 v[106:109], v[164:167], v[186:189], v[106:109]
	v_mfma_f32_16x16x32_bf16 v[106:109], v[174:177], v[190:193], v[106:109]
	v_mfma_f32_16x16x32_bf16 v[98:101], v[178:181], v[186:189], v[98:101]
	v_mfma_f32_16x16x32_bf16 v[98:101], v[182:185], v[190:193], v[98:101]
	v_mfma_f32_16x16x32_bf16 v[90:93], v[178:181], v[194:197], v[90:93]
	v_mfma_f32_16x16x32_bf16 v[90:93], v[182:185], v[198:201], v[90:93]
	v_mfma_f32_16x16x32_bf16 v[94:97], v[164:167], v[194:197], v[94:97]
	v_mfma_f32_16x16x32_bf16 v[94:97], v[174:177], v[198:201], v[94:97]
	v_mfma_f32_16x16x32_bf16 v[86:89], v[164:167], v[202:205], v[86:89]
	v_mfma_f32_16x16x32_bf16 v[86:89], v[174:177], v[206:209], v[86:89]
	v_mfma_f32_16x16x32_bf16 v[82:85], v[178:181], v[202:205], v[82:85]
	v_mfma_f32_16x16x32_bf16 v[82:85], v[182:185], v[206:209], v[82:85]
	v_mfma_f32_16x16x32_bf16 v[66:69], v[178:181], v[210:213], v[66:69]
	v_mfma_f32_16x16x32_bf16 v[66:69], v[182:185], v[214:217], v[66:69]
	v_mfma_f32_16x16x32_bf16 v[70:73], v[164:167], v[210:213], v[70:73]
	v_mfma_f32_16x16x32_bf16 v[70:73], v[174:177], v[214:217], v[70:73]
	s_setprio 0
	s_barrier
	s_add_i32 s83, s72, s44
	v_lshl_add_u64 v[218:219], s[36:37], 0, v[148:149]
	s_mov_b32 m0, s83
	ds_read_b128 v[186:189], v172 offset:16384
	ds_read_b128 v[190:193], v172 offset:17408
	ds_read_b128 v[194:197], v172 offset:18432
	ds_read_b128 v[198:201], v172 offset:19456
	ds_read_b128 v[202:205], v172 offset:20480
	ds_read_b128 v[206:209], v172 offset:21504
	ds_read_b128 v[210:213], v172 offset:22528
	ds_read_b128 v[214:217], v172 offset:23552
	global_load_lds_dwordx4 v[218:219], off
	s_add_i32 m0, s83, 0x2000
	s_add_u32 s84, s36, 0x20000
	v_lshl_add_u64 v[220:221], s[36:37], 0, v[152:153]
	s_addc_u32 s85, s37, 0
	s_add_i32 s83, s73, s44
	global_load_lds_dwordx4 v[220:221], off
	v_lshl_add_u64 v[222:223], s[84:85], 0, v[148:149]
	s_mov_b32 m0, s83
	v_lshl_add_u64 v[224:225], s[58:59], 0, v[150:151]
	global_load_lds_dwordx4 v[222:223], off
	v_lshl_add_u64 v[222:223], s[84:85], 0, v[152:153]
	s_add_i32 m0, s83, 0x2000
	s_nop 0
	global_load_lds_dwordx4 v[222:223], off
	v_lshl_add_u64 v[222:223], s[58:59], 0, v[146:147]
	s_mov_b32 m0, s31
	s_nop 0
	global_load_lds_dwordx4 v[222:223], off
	s_mov_b32 m0, s45
	s_nop 0
	global_load_lds_dwordx4 v[224:225], off
	s_waitcnt vmcnt(8)
	s_waitcnt lgkmcnt(0)
	s_barrier
; #define PG8_STAGE(bufoff, gbase, voff) do { _Pragma("unroll") for (int _i = 0; _i < 2; ++_i) \
;         __builtin_amdgcn_global_load_lds((const unsigned*)((const char*)(gbase) + (voff)[_i]), (PG8_LAS unsigned*)(lds + (bufoff) + ldsw + _i * 8192), 16, 0, 0); } while (0)
; #define PG8_LDA(dst, b, h) do { _Pragma("unroll") for (int m = 0; m < 4; ++m) _Pragma("unroll") for (int k = 0; k < 2; ++k) dst[m][k] = *(const PG8_LAS bf16x8*)(lds + PG8_SA(b, h) + aoff + m * 2048 + k * 1024); } while (0)
; #define PG8_LDB(dst, b, h) do { _Pragma("unroll") for (int n = 0; n < 2; ++n) _Pragma("unroll") for (int k = 0; k < 2; ++k) dst[n][k] = *(const PG8_LAS bf16x8*)(lds + PG8_SB(b, h) + boff + n * 2048 + k * 1024); } while (0)
; #define PG8_MMA(ai, bj, At, Bt) do { __builtin_amdgcn_s_setprio(3); _Pragma("unroll") for (int m = 0; m < 4; ++m) _Pragma("unroll") for (int n = 0; n < 2; ++n) _Pragma("unroll") for (int k = 0; k < 2; ++k) \
;         acc[ai][bj][m][n] = __builtin_amdgcn_mfma_f32_16x16x32_bf16(Bt[n][k], At[m][k], acc[ai][bj][m][n], 0, 0, 0); __builtin_amdgcn_s_setprio(0); } while (0)
; #define PG8_WAIT_V(n) asm volatile("s_waitcnt vmcnt(" #n ")" ::: "memory")
; #define PG8_WAIT_L(n) asm volatile("s_waitcnt lgkmcnt(" #n ")" ::: "memory")
; #define PG8_BAR __builtin_amdgcn_s_barrier()
; #define PG8_SCHED __builtin_amdgcn_sched_barrier(0)
; template <class Epi, class Sched, bool ALIGN_EPI = false, bool SP2 = false>
; __device__ __forceinline__ void gemm_phase(PG8_LAS unsigned char* lds, const Gemm g, const Sched& S, const Epi& E) {
;     ...
;             PG8_WAIT_V(8); PG8_WAIT_L(0); PG8_BAR; PG8_MMA(1, 0, At, B0); PG8_MMA(1, 1, At, B1); PG8_BAR; PG8_SCHED;
;             PG8_LDB(B0, 1, 0); PG8_LDB(B1, 1, 1); PG8_SCHED; PG8_LDA(At, 1, 0); PG8_STAGE(PG8_SA(0, 1), a2 + hstepA, voffA);
;             PG8_WAIT_V(8); PG8_WAIT_L(0); PG8_BAR; PG8_MMA(0, 0, At, B0); PG8_MMA(0, 1, At, B1); PG8_BAR; PG8_SCHED;
	s_setprio 3
	v_mfma_f32_16x16x32_bf16 v[62:65], v[130:133], v[186:189], v[62:65]
	v_mfma_f32_16x16x32_bf16 v[62:65], v[134:137], v[190:193], v[62:65]
	v_mfma_f32_16x16x32_bf16 v[58:61], v[138:141], v[186:189], v[58:61]
	v_mfma_f32_16x16x32_bf16 v[58:61], v[142:145], v[190:193], v[58:61]
	v_mfma_f32_16x16x32_bf16 v[46:49], v[138:141], v[194:197], v[46:49]
	v_mfma_f32_16x16x32_bf16 v[46:49], v[142:145], v[198:201], v[46:49]
	v_mfma_f32_16x16x32_bf16 v[54:57], v[130:133], v[194:197], v[54:57]
	v_mfma_f32_16x16x32_bf16 v[54:57], v[134:137], v[198:201], v[54:57]
	v_mfma_f32_16x16x32_bf16 v[38:41], v[130:133], v[202:205], v[38:41]
	v_mfma_f32_16x16x32_bf16 v[38:41], v[134:137], v[206:209], v[38:41]
	v_mfma_f32_16x16x32_bf16 v[30:33], v[138:141], v[202:205], v[30:33]
	v_mfma_f32_16x16x32_bf16 v[30:33], v[142:145], v[206:209], v[30:33]
	v_mfma_f32_16x16x32_bf16 v[14:17], v[138:141], v[210:213], v[14:17]
	v_mfma_f32_16x16x32_bf16 v[14:17], v[142:145], v[214:217], v[14:17]
	v_mfma_f32_16x16x32_bf16 v[22:25], v[130:133], v[210:213], v[22:25]
	v_mfma_f32_16x16x32_bf16 v[22:25], v[134:137], v[214:217], v[22:25]
	v_mfma_f32_16x16x32_bf16 v[50:53], v[164:167], v[186:189], v[50:53]
	v_mfma_f32_16x16x32_bf16 v[50:53], v[174:177], v[190:193], v[50:53]
	v_mfma_f32_16x16x32_bf16 v[42:45], v[178:181], v[186:189], v[42:45]
	v_mfma_f32_16x16x32_bf16 v[42:45], v[182:185], v[190:193], v[42:45]
	v_mfma_f32_16x16x32_bf16 v[26:29], v[178:181], v[194:197], v[26:29]
	v_mfma_f32_16x16x32_bf16 v[26:29], v[182:185], v[198:201], v[26:29]
	v_mfma_f32_16x16x32_bf16 v[34:37], v[164:167], v[194:197], v[34:37]
	v_mfma_f32_16x16x32_bf16 v[34:37], v[174:177], v[198:201], v[34:37]
	v_mfma_f32_16x16x32_bf16 v[18:21], v[164:167], v[202:205], v[18:21]
	v_mfma_f32_16x16x32_bf16 v[18:21], v[174:177], v[206:209], v[18:21]
	v_mfma_f32_16x16x32_bf16 v[10:13], v[178:181], v[202:205], v[10:13]
	v_mfma_f32_16x16x32_bf16 v[10:13], v[182:185], v[206:209], v[10:13]
	v_mfma_f32_16x16x32_bf16 v[2:5], v[178:181], v[210:213], v[2:5]
	v_mfma_f32_16x16x32_bf16 v[2:5], v[182:185], v[214:217], v[2:5]
	v_mfma_f32_16x16x32_bf16 v[6:9], v[164:167], v[210:213], v[6:9]
	v_mfma_f32_16x16x32_bf16 v[6:9], v[174:177], v[214:217], v[6:9]
	s_setprio 0
	s_barrier
	s_add_i32 s83, 0, 0x18000
	s_add_i32 s84, 0, 0x1c000
	v_add_u32_e32 v142, s83, v168
	v_add_u32_e32 v173, s84, v168
	ds_read_b128 v[130:133], v142
	ds_read_b128 v[134:137], v142 offset:1024
	ds_read_b128 v[138:141], v142 offset:2048
	ds_read_b128 v[142:145], v142 offset:3072
	ds_read_b128 v[164:167], v173
	ds_read_b128 v[174:177], v173 offset:1024
	ds_read_b128 v[178:181], v173 offset:2048
	ds_read_b128 v[182:185], v173 offset:3072
	s_add_u32 s58, s58, 0x80000
	s_addc_u32 s59, s59, 0
	s_mov_b32 m0, s54
	v_lshl_add_u64 v[226:227], s[58:59], 0, v[146:147]
	ds_read_b128 v[186:189], v172 offset:32768
	ds_read_b128 v[190:193], v172 offset:33792
	ds_read_b128 v[194:197], v172 offset:34816
	ds_read_b128 v[198:201], v172 offset:35840
	ds_read_b128 v[202:205], v172 offset:36864
	ds_read_b128 v[206:209], v172 offset:37888
	ds_read_b128 v[210:213], v172 offset:38912
	ds_read_b128 v[214:217], v172 offset:39936
	global_load_lds_dwordx4 v[226:227], off
	v_lshl_add_u64 v[226:227], s[58:59], 0, v[150:151]
	s_mov_b32 m0, s55
	s_nop 0
	global_load_lds_dwordx4 v[226:227], off
	s_waitcnt vmcnt(8)
	s_waitcnt lgkmcnt(0)
	s_barrier
	s_setprio 3
	v_mfma_f32_16x16x32_bf16 v[126:129], v[130:133], v[186:189], v[126:129]
	v_mfma_f32_16x16x32_bf16 v[126:129], v[134:137], v[190:193], v[126:129]
	v_mfma_f32_16x16x32_bf16 v[122:125], v[138:141], v[186:189], v[122:125]
	v_mfma_f32_16x16x32_bf16 v[122:125], v[142:145], v[190:193], v[122:125]
	v_mfma_f32_16x16x32_bf16 v[114:117], v[138:141], v[194:197], v[114:117]
	v_mfma_f32_16x16x32_bf16 v[114:117], v[142:145], v[198:201], v[114:117]
	v_mfma_f32_16x16x32_bf16 v[118:121], v[130:133], v[194:197], v[118:121]
	v_mfma_f32_16x16x32_bf16 v[118:121], v[134:137], v[198:201], v[118:121]
	v_mfma_f32_16x16x32_bf16 v[110:113], v[130:133], v[202:205], v[110:113]
	v_mfma_f32_16x16x32_bf16 v[110:113], v[134:137], v[206:209], v[110:113]
	v_mfma_f32_16x16x32_bf16 v[102:105], v[138:141], v[202:205], v[102:105]
	v_mfma_f32_16x16x32_bf16 v[102:105], v[142:145], v[206:209], v[102:105]
	v_mfma_f32_16x16x32_bf16 v[74:77], v[138:141], v[210:213], v[74:77]
	v_mfma_f32_16x16x32_bf16 v[74:77], v[142:145], v[214:217], v[74:77]
	v_mfma_f32_16x16x32_bf16 v[78:81], v[130:133], v[210:213], v[78:81]
	v_mfma_f32_16x16x32_bf16 v[78:81], v[134:137], v[214:217], v[78:81]
	v_mfma_f32_16x16x32_bf16 v[106:109], v[164:167], v[186:189], v[106:109]
	v_mfma_f32_16x16x32_bf16 v[106:109], v[174:177], v[190:193], v[106:109]
	v_mfma_f32_16x16x32_bf16 v[98:101], v[178:181], v[186:189], v[98:101]
	v_mfma_f32_16x16x32_bf16 v[98:101], v[182:185], v[190:193], v[98:101]
	v_mfma_f32_16x16x32_bf16 v[90:93], v[178:181], v[194:197], v[90:93]
	v_mfma_f32_16x16x32_bf16 v[90:93], v[182:185], v[198:201], v[90:93]
	v_mfma_f32_16x16x32_bf16 v[94:97], v[164:167], v[194:197], v[94:97]
	v_mfma_f32_16x16x32_bf16 v[94:97], v[174:177], v[198:201], v[94:97]
	v_mfma_f32_16x16x32_bf16 v[86:89], v[164:167], v[202:205], v[86:89]
	v_mfma_f32_16x16x32_bf16 v[86:89], v[174:177], v[206:209], v[86:89]
	v_mfma_f32_16x16x32_bf16 v[82:85], v[178:181], v[202:205], v[82:85]
	v_mfma_f32_16x16x32_bf16 v[82:85], v[182:185], v[206:209], v[82:85]
	v_mfma_f32_16x16x32_bf16 v[66:69], v[178:181], v[210:213], v[66:69]
	v_mfma_f32_16x16x32_bf16 v[66:69], v[182:185], v[214:217], v[66:69]
	v_mfma_f32_16x16x32_bf16 v[70:73], v[164:167], v[210:213], v[70:73]
	v_mfma_f32_16x16x32_bf16 v[70:73], v[174:177], v[214:217], v[70:73]
	s_setprio 0
	s_barrier
; #define PG8_STAGE(bufoff, gbase, voff) do { _Pragma("unroll") for (int _i = 0; _i < 2; ++_i) \
;         __builtin_amdgcn_global_load_lds((const unsigned*)((const char*)(gbase) + (voff)[_i]), (PG8_LAS unsigned*)(lds + (bufoff) + ldsw + _i * 8192), 16, 0, 0); } while (0)
; #define PG8_LDA(dst, b, h) do { _Pragma("unroll") for (int m = 0; m < 4; ++m) _Pragma("unroll") for (int k = 0; k < 2; ++k) dst[m][k] = *(const PG8_LAS bf16x8*)(lds + PG8_SA(b, h) + aoff + m * 2048 + k * 1024); } while (0)
; #define PG8_MMA(ai, bj, At, Bt) do { __builtin_amdgcn_s_setprio(3); _Pragma("unroll") for (int m = 0; m < 4; ++m) _Pragma("unroll") for (int n = 0; n < 2; ++n) _Pragma("unroll") for (int k = 0; k < 2; ++k) \
;         acc[ai][bj][m][n] = __builtin_amdgcn_mfma_f32_16x16x32_bf16(Bt[n][k], At[m][k], acc[ai][bj][m][n], 0, 0, 0); __builtin_amdgcn_s_setprio(0); } while (0)
; #define PG8_WAIT_V(n) asm volatile("s_waitcnt vmcnt(" #n ")" ::: "memory")
; #define PG8_WAIT_L(n) asm volatile("s_waitcnt lgkmcnt(" #n ")" ::: "memory")
; #define PG8_BAR __builtin_amdgcn_s_barrier()
; #define PG8_SCHED __builtin_amdgcn_sched_barrier(0)
; template <class Epi, class Sched, bool ALIGN_EPI = false, bool SP2 = false>
; __device__ __forceinline__ void gemm_phase(PG8_LAS unsigned char* lds, const Gemm g, const Sched& S, const Epi& E) {
;     ...
;             PG8_LDA(At, 1, 1); PG8_STAGE(PG8_SB(1, 0), b3, voffB); PG8_STAGE(PG8_SB(1, 1), b3 + hstepB, voffB); PG8_STAGE(PG8_SA(1, 0), a3, voffA);
;             PG8_WAIT_V(8); PG8_WAIT_L(0); PG8_BAR; PG8_MMA(1, 0, At, B0); PG8_MMA(1, 1, At, B1); PG8_BAR; PG8_SCHED;
	s_add_i32 s58, s83, s44
	v_lshl_add_u64 v[218:219], v[218:219], 0, s[18:19]
	s_mov_b32 m0, s58
	ds_read_b128 v[186:189], v172 offset:49152
	ds_read_b128 v[190:193], v172 offset:50176
	ds_read_b128 v[194:197], v172 offset:51200
	ds_read_b128 v[198:201], v172 offset:52224
	ds_read_b128 v[202:205], v172 offset:53248
	ds_read_b128 v[206:209], v172 offset:54272
	ds_read_b128 v[210:213], v172 offset:55296
	ds_read_b128 v[214:217], v172 offset:56320
	global_load_lds_dwordx4 v[218:219], off
	s_add_i32 m0, s58, 0x2000
	s_add_u32 s36, s36, 0x20080
	v_lshl_add_u64 v[218:219], v[220:221], 0, s[18:19]
	s_addc_u32 s37, s37, 0
	s_add_i32 s58, s84, s44
	global_load_lds_dwordx4 v[218:219], off
	v_lshl_add_u64 v[218:219], s[36:37], 0, v[148:149]
	s_mov_b32 m0, s58
	s_nop 0
	global_load_lds_dwordx4 v[218:219], off
	v_lshl_add_u64 v[218:219], s[36:37], 0, v[152:153]
	s_add_i32 m0, s58, 0x2000
	s_nop 0
	global_load_lds_dwordx4 v[218:219], off
	v_lshl_add_u64 v[218:219], v[222:223], 0, s[18:19]
	s_mov_b32 m0, s63
	s_nop 0
	global_load_lds_dwordx4 v[218:219], off
	v_lshl_add_u64 v[218:219], v[224:225], 0, s[18:19]
	s_mov_b32 m0, s66
	s_nop 0
	global_load_lds_dwordx4 v[218:219], off
	s_waitcnt vmcnt(8)
	s_waitcnt lgkmcnt(0)
	s_barrier
	s_setprio 3
	v_mfma_f32_16x16x32_bf16 v[62:65], v[130:133], v[186:189], v[62:65]
	v_mfma_f32_16x16x32_bf16 v[62:65], v[134:137], v[190:193], v[62:65]
	v_mfma_f32_16x16x32_bf16 v[58:61], v[138:141], v[186:189], v[58:61]
	v_mfma_f32_16x16x32_bf16 v[58:61], v[142:145], v[190:193], v[58:61]
	v_mfma_f32_16x16x32_bf16 v[46:49], v[138:141], v[194:197], v[46:49]
	v_mfma_f32_16x16x32_bf16 v[46:49], v[142:145], v[198:201], v[46:49]
	v_mfma_f32_16x16x32_bf16 v[54:57], v[130:133], v[194:197], v[54:57]
	v_mfma_f32_16x16x32_bf16 v[54:57], v[134:137], v[198:201], v[54:57]
	v_mfma_f32_16x16x32_bf16 v[38:41], v[130:133], v[202:205], v[38:41]
	v_mfma_f32_16x16x32_bf16 v[38:41], v[134:137], v[206:209], v[38:41]
	v_mfma_f32_16x16x32_bf16 v[30:33], v[138:141], v[202:205], v[30:33]
	v_mfma_f32_16x16x32_bf16 v[30:33], v[142:145], v[206:209], v[30:33]
	v_mfma_f32_16x16x32_bf16 v[14:17], v[138:141], v[210:213], v[14:17]
	v_mfma_f32_16x16x32_bf16 v[14:17], v[142:145], v[214:217], v[14:17]
	v_mfma_f32_16x16x32_bf16 v[22:25], v[130:133], v[210:213], v[22:25]
	v_mfma_f32_16x16x32_bf16 v[22:25], v[134:137], v[214:217], v[22:25]
	v_mfma_f32_16x16x32_bf16 v[50:53], v[164:167], v[186:189], v[50:53]
	v_mfma_f32_16x16x32_bf16 v[50:53], v[174:177], v[190:193], v[50:53]
	v_mfma_f32_16x16x32_bf16 v[42:45], v[178:181], v[186:189], v[42:45]
	v_mfma_f32_16x16x32_bf16 v[42:45], v[182:185], v[190:193], v[42:45]
	v_mfma_f32_16x16x32_bf16 v[26:29], v[178:181], v[194:197], v[26:29]
	v_mfma_f32_16x16x32_bf16 v[26:29], v[182:185], v[198:201], v[26:29]
	v_mfma_f32_16x16x32_bf16 v[34:37], v[164:167], v[194:197], v[34:37]
	v_mfma_f32_16x16x32_bf16 v[34:37], v[174:177], v[198:201], v[34:37]
	v_mfma_f32_16x16x32_bf16 v[18:21], v[164:167], v[202:205], v[18:21]
	v_mfma_f32_16x16x32_bf16 v[18:21], v[174:177], v[206:209], v[18:21]
	v_mfma_f32_16x16x32_bf16 v[10:13], v[178:181], v[202:205], v[10:13]
	v_mfma_f32_16x16x32_bf16 v[10:13], v[182:185], v[206:209], v[10:13]
	v_mfma_f32_16x16x32_bf16 v[2:5], v[178:181], v[210:213], v[2:5]
	v_mfma_f32_16x16x32_bf16 v[2:5], v[182:185], v[214:217], v[2:5]
	v_mfma_f32_16x16x32_bf16 v[6:9], v[164:167], v[210:213], v[6:9]
	v_mfma_f32_16x16x32_bf16 v[6:9], v[174:177], v[214:217], v[6:9]
	s_setprio 0
	s_barrier
	s_add_i32 s79, s79, 2
	s_add_u32 s6, s6, 0x100
	s_addc_u32 s7, s7, 0
	s_add_u32 s77, s77, 0x100
	s_addc_u32 s78, s78, 0
	s_cmp_gt_u32 s79, 5
	s_cbranch_scc0 .LBB0_478
	s_and_b64 vcc, exec, s[20:21]
	s_cbranch_vccz .LBB0_481
	s_barrier

; #define PG8_STAGE(bufoff, gbase, voff) do { _Pragma("unroll") for (int _i = 0; _i < 2; ++_i) \
;         __builtin_amdgcn_global_load_lds((const unsigned*)((const char*)(gbase) + (voff)[_i]), (PG8_LAS unsigned*)(lds + (bufoff) + ldsw + _i * 8192), 16, 0, 0); } while (0)
; #define PG8_LDA(dst, b, h) do { _Pragma("unroll") for (int m = 0; m < 4; ++m) _Pragma("unroll") for (int k = 0; k < 2; ++k) dst[m][k] = *(const PG8_LAS bf16x8*)(lds + PG8_SA(b, h) + aoff + m * 2048 + k * 1024); } while (0)
; #define PG8_LDB(dst, b, h) do { _Pragma("unroll") for (int n = 0; n < 2; ++n) _Pragma("unroll") for (int k = 0; k < 2; ++k) dst[n][k] = *(const PG8_LAS bf16x8*)(lds + PG8_SB(b, h) + boff + n * 2048 + k * 1024); } while (0)
; #define PG8_MMA(ai, bj, At, Bt) do { __builtin_amdgcn_s_setprio(3); _Pragma("unroll") for (int m = 0; m < 4; ++m) _Pragma("unroll") for (int n = 0; n < 2; ++n) _Pragma("unroll") for (int k = 0; k < 2; ++k) \
;         acc[ai][bj][m][n] = __builtin_amdgcn_mfma_f32_16x16x32_bf16(Bt[n][k], At[m][k], acc[ai][bj][m][n], 0, 0, 0); __builtin_amdgcn_s_setprio(0); } while (0)
; #define PG8_WAIT_V(n) asm volatile("s_waitcnt vmcnt(" #n ")" ::: "memory")
; template <class Epi, class Sched, bool ALIGN_EPI = false, bool SP2 = false>
; __device__ __forceinline__ void gemm_phase(PG8_LAS unsigned char* lds, const Gemm g, const Sched& S, const Epi& E) {
;     ...
;             const bool last = (t == nt - 2);
;             const char* a1 = cA + (size_t)(t + 1) * kstep;
;             const char* a2 = last ? nA : cA + (size_t)(t + 2) * kstep; const char* b2 = last ? nB : cB + (size_t)(t + 2) * kstep;
;             const char* a3 = a2 + kstep; const char* b3 = b2 + kstep;
;             if (last && has_next) S.a_ready(nxt);
;             if constexpr (Epi::MIDK) { if (t == E.midk_step(nt)) E.midk(acc, cur, wr, wc, fr, fq); }
;             if constexpr (SP2) {
;             PG8_LDB(B0, 0, 0); PG8_LDB(B1, 0, 1); PG8_SCHED; PG8_LDA(At, 0, 0); PG8_STAGE(PG8_SA(1, 1), a1 + hstepA, voffA);
;             PG8_WAIT_V(8); PG8_WAIT_L(0); PG8_BAR; PG8_MMA(0, 0, At, B0); PG8_MMA(0, 1, At, B1); PG8_BAR; PG8_SCHED;
;             PG8_LDA(At, 0, 1); PG8_STAGE(PG8_SB(0, 0), b2, voffB); PG8_STAGE(PG8_SB(0, 1), b2 + hstepB, voffB); PG8_STAGE(PG8_SA(0, 0), a2, voffA);
;             PG8_WAIT_V(8); PG8_WAIT_L(0); PG8_BAR; PG8_MMA(1, 0, At, B0); PG8_MMA(1, 1, At, B1); PG8_BAR; PG8_SCHED;
.LBB0_727:
	v_add_u32_e32 v160, s66, v157
	ds_read_b128 v[130:133], v160
	ds_read_b128 v[164:167], v160 offset:1024
	ds_read_b128 v[168:171], v160 offset:2048
	ds_read_b128 v[172:175], v160 offset:3072
	v_add_u32_e32 v160, s67, v157
	s_add_u32 s0, s28, s30
	ds_read_b128 v[176:179], v160
	ds_read_b128 v[180:183], v160 offset:1024
	ds_read_b128 v[184:187], v160 offset:2048
	ds_read_b128 v[188:191], v160 offset:3072
	s_addc_u32 s1, s29, s31
	s_add_u32 s0, s0, 0x100
	s_addc_u32 s1, s1, 0
	s_add_u32 s84, s79, s30
	s_addc_u32 s85, s81, s31
	s_cmpk_eq_i32 s30, 0x1f00
	s_cselect_b32 s37, s23, s1
	s_cselect_b32 s36, s72, s0
	s_cselect_b32 s1, s75, s85
	s_cselect_b32 s0, s76, s84
	v_lshl_add_u64 v[160:161], v[150:151], 0, s[30:31]
	s_add_i32 m0, s44, 0xc000
	ds_read_b128 v[192:195], v159
	ds_read_b128 v[196:199], v159 offset:1024
	ds_read_b128 v[200:203], v159 offset:2048
	ds_read_b128 v[204:207], v159 offset:3072
	ds_read_b128 v[208:211], v159 offset:4096
	ds_read_b128 v[212:215], v159 offset:5120
	ds_read_b128 v[216:219], v159 offset:6144
	ds_read_b128 v[220:223], v159 offset:7168
	global_load_lds_dwordx4 v[160:161], off
	v_lshl_add_u64 v[160:161], v[152:153], 0, s[30:31]
	s_add_i32 m0, s44, 0xe000
	s_nop 0
	global_load_lds_dwordx4 v[160:161], off
	s_waitcnt vmcnt(8)
	s_waitcnt lgkmcnt(0)
	s_barrier
	s_setprio 3
	v_mfma_f32_16x16x32_bf16 v[126:129], v[130:133], v[192:195], v[126:129]
	v_mfma_f32_16x16x32_bf16 v[126:129], v[164:167], v[196:199], v[126:129]
	v_mfma_f32_16x16x32_bf16 v[122:125], v[168:171], v[192:195], v[122:125]
	v_mfma_f32_16x16x32_bf16 v[122:125], v[172:175], v[196:199], v[122:125]
	v_mfma_f32_16x16x32_bf16 v[106:109], v[168:171], v[200:203], v[106:109]
	v_mfma_f32_16x16x32_bf16 v[106:109], v[172:175], v[204:207], v[106:109]
	v_mfma_f32_16x16x32_bf16 v[110:113], v[130:133], v[200:203], v[110:113]
	v_mfma_f32_16x16x32_bf16 v[110:113], v[164:167], v[204:207], v[110:113]
	v_mfma_f32_16x16x32_bf16 v[94:97], v[130:133], v[208:211], v[94:97]
	v_mfma_f32_16x16x32_bf16 v[94:97], v[164:167], v[212:215], v[94:97]
	v_mfma_f32_16x16x32_bf16 v[90:93], v[168:171], v[208:211], v[90:93]
	v_mfma_f32_16x16x32_bf16 v[90:93], v[172:175], v[212:215], v[90:93]
	v_mfma_f32_16x16x32_bf16 v[74:77], v[168:171], v[216:219], v[74:77]
	v_mfma_f32_16x16x32_bf16 v[74:77], v[172:175], v[220:223], v[74:77]
	v_mfma_f32_16x16x32_bf16 v[78:81], v[130:133], v[216:219], v[78:81]
	v_mfma_f32_16x16x32_bf16 v[78:81], v[164:167], v[220:223], v[78:81]
	v_mfma_f32_16x16x32_bf16 v[118:121], v[176:179], v[192:195], v[118:121]
	v_mfma_f32_16x16x32_bf16 v[118:121], v[180:183], v[196:199], v[118:121]
	v_mfma_f32_16x16x32_bf16 v[114:117], v[184:187], v[192:195], v[114:117]
	v_mfma_f32_16x16x32_bf16 v[114:117], v[188:191], v[196:199], v[114:117]
	v_mfma_f32_16x16x32_bf16 v[98:101], v[184:187], v[200:203], v[98:101]
	v_mfma_f32_16x16x32_bf16 v[98:101], v[188:191], v[204:207], v[98:101]
	v_mfma_f32_16x16x32_bf16 v[102:105], v[176:179], v[200:203], v[102:105]
	v_mfma_f32_16x16x32_bf16 v[102:105], v[180:183], v[204:207], v[102:105]
	v_mfma_f32_16x16x32_bf16 v[86:89], v[176:179], v[208:211], v[86:89]
	v_mfma_f32_16x16x32_bf16 v[86:89], v[180:183], v[212:215], v[86:89]
	v_mfma_f32_16x16x32_bf16 v[82:85], v[184:187], v[208:211], v[82:85]
	v_mfma_f32_16x16x32_bf16 v[82:85], v[188:191], v[212:215], v[82:85]
	v_mfma_f32_16x16x32_bf16 v[66:69], v[184:187], v[216:219], v[66:69]
	v_mfma_f32_16x16x32_bf16 v[66:69], v[188:191], v[220:223], v[66:69]
	v_mfma_f32_16x16x32_bf16 v[70:73], v[176:179], v[216:219], v[70:73]
	v_mfma_f32_16x16x32_bf16 v[70:73], v[180:183], v[220:223], v[70:73]
	s_setprio 0
	s_barrier
	s_add_i32 s84, s66, s33
	v_lshl_add_u64 v[160:161], s[0:1], 0, v[136:137]
	s_mov_b32 m0, s84
	ds_read_b128 v[192:195], v159 offset:16384
	ds_read_b128 v[196:199], v159 offset:17408
	ds_read_b128 v[200:203], v159 offset:18432
	ds_read_b128 v[204:207], v159 offset:19456
	ds_read_b128 v[208:211], v159 offset:20480
	ds_read_b128 v[212:215], v159 offset:21504
	ds_read_b128 v[216:219], v159 offset:22528
	ds_read_b128 v[220:223], v159 offset:23552
	global_load_lds_dwordx4 v[160:161], off
	s_add_i32 m0, s84, 0x2000
	s_add_u32 s84, s0, 0x100000
	v_lshl_add_u64 v[224:225], s[0:1], 0, v[140:141]
	s_addc_u32 s85, s1, 0
	s_add_i32 s86, s67, s33
	global_load_lds_dwordx4 v[224:225], off
	v_lshl_add_u64 v[226:227], s[84:85], 0, v[136:137]
	s_mov_b32 m0, s86
	v_lshl_add_u64 v[228:229], s[36:37], 0, v[138:139]
	global_load_lds_dwordx4 v[226:227], off
	v_lshl_add_u64 v[226:227], s[84:85], 0, v[140:141]
	s_add_i32 m0, s86, 0x2000
	s_nop 0
	global_load_lds_dwordx4 v[226:227], off
	v_lshl_add_u64 v[226:227], s[36:37], 0, v[134:135]
	s_mov_b32 m0, s44
	s_nop 0
	global_load_lds_dwordx4 v[226:227], off
	s_mov_b32 m0, s45
	s_nop 0
	global_load_lds_dwordx4 v[228:229], off
	s_waitcnt vmcnt(8)
	s_waitcnt lgkmcnt(0)
	s_barrier
; #define PG8_STAGE(bufoff, gbase, voff) do { _Pragma("unroll") for (int _i = 0; _i < 2; ++_i) \
;         __builtin_amdgcn_global_load_lds((const unsigned*)((const char*)(gbase) + (voff)[_i]), (PG8_LAS unsigned*)(lds + (bufoff) + ldsw + _i * 8192), 16, 0, 0); } while (0)
; #define PG8_LDA(dst, b, h) do { _Pragma("unroll") for (int m = 0; m < 4; ++m) _Pragma("unroll") for (int k = 0; k < 2; ++k) dst[m][k] = *(const PG8_LAS bf16x8*)(lds + PG8_SA(b, h) + aoff + m * 2048 + k * 1024); } while (0)
; #define PG8_LDB(dst, b, h) do { _Pragma("unroll") for (int n = 0; n < 2; ++n) _Pragma("unroll") for (int k = 0; k < 2; ++k) dst[n][k] = *(const PG8_LAS bf16x8*)(lds + PG8_SB(b, h) + boff + n * 2048 + k * 1024); } while (0)
; #define PG8_MMA(ai, bj, At, Bt) do { __builtin_amdgcn_s_setprio(3); _Pragma("unroll") for (int m = 0; m < 4; ++m) _Pragma("unroll") for (int n = 0; n < 2; ++n) _Pragma("unroll") for (int k = 0; k < 2; ++k) \
;         acc[ai][bj][m][n] = __builtin_amdgcn_mfma_f32_16x16x32_bf16(Bt[n][k], At[m][k], acc[ai][bj][m][n], 0, 0, 0); __builtin_amdgcn_s_setprio(0); } while (0)
; #define PG8_WAIT_V(n) asm volatile("s_waitcnt vmcnt(" #n ")" ::: "memory")
; #define PG8_WAIT_L(n) asm volatile("s_waitcnt lgkmcnt(" #n ")" ::: "memory")
; #define PG8_BAR __builtin_amdgcn_s_barrier()
; #define PG8_SCHED __builtin_amdgcn_sched_barrier(0)
; template <class Epi, class Sched, bool ALIGN_EPI = false, bool SP2 = false>
; __device__ __forceinline__ void gemm_phase(PG8_LAS unsigned char* lds, const Gemm g, const Sched& S, const Epi& E) {
;     ...
;             PG8_WAIT_V(8); PG8_WAIT_L(0); PG8_BAR; PG8_MMA(1, 0, At, B0); PG8_MMA(1, 1, At, B1); PG8_BAR; PG8_SCHED;
;             PG8_LDB(B0, 1, 0); PG8_LDB(B1, 1, 1); PG8_SCHED; PG8_LDA(At, 1, 0); PG8_STAGE(PG8_SA(0, 1), a2 + hstepA, voffA);
;             PG8_WAIT_V(8); PG8_WAIT_L(0); PG8_BAR; PG8_MMA(0, 0, At, B0); PG8_MMA(0, 1, At, B1); PG8_BAR; PG8_SCHED;
	s_setprio 3
	v_mfma_f32_16x16x32_bf16 v[62:65], v[130:133], v[192:195], v[62:65]
	v_mfma_f32_16x16x32_bf16 v[62:65], v[164:167], v[196:199], v[62:65]
	v_mfma_f32_16x16x32_bf16 v[58:61], v[168:171], v[192:195], v[58:61]
	v_mfma_f32_16x16x32_bf16 v[58:61], v[172:175], v[196:199], v[58:61]
	v_mfma_f32_16x16x32_bf16 v[42:45], v[168:171], v[200:203], v[42:45]
	v_mfma_f32_16x16x32_bf16 v[42:45], v[172:175], v[204:207], v[42:45]
	v_mfma_f32_16x16x32_bf16 v[46:49], v[130:133], v[200:203], v[46:49]
	v_mfma_f32_16x16x32_bf16 v[46:49], v[164:167], v[204:207], v[46:49]
	v_mfma_f32_16x16x32_bf16 v[30:33], v[130:133], v[208:211], v[30:33]
	v_mfma_f32_16x16x32_bf16 v[30:33], v[164:167], v[212:215], v[30:33]
	v_mfma_f32_16x16x32_bf16 v[26:29], v[168:171], v[208:211], v[26:29]
	v_mfma_f32_16x16x32_bf16 v[26:29], v[172:175], v[212:215], v[26:29]
	v_mfma_f32_16x16x32_bf16 v[10:13], v[168:171], v[216:219], v[10:13]
	v_mfma_f32_16x16x32_bf16 v[10:13], v[172:175], v[220:223], v[10:13]
	v_mfma_f32_16x16x32_bf16 v[14:17], v[130:133], v[216:219], v[14:17]
	v_mfma_f32_16x16x32_bf16 v[14:17], v[164:167], v[220:223], v[14:17]
	v_mfma_f32_16x16x32_bf16 v[54:57], v[176:179], v[192:195], v[54:57]
	v_mfma_f32_16x16x32_bf16 v[54:57], v[180:183], v[196:199], v[54:57]
	v_mfma_f32_16x16x32_bf16 v[50:53], v[184:187], v[192:195], v[50:53]
	v_mfma_f32_16x16x32_bf16 v[50:53], v[188:191], v[196:199], v[50:53]
	v_mfma_f32_16x16x32_bf16 v[34:37], v[184:187], v[200:203], v[34:37]
	v_mfma_f32_16x16x32_bf16 v[34:37], v[188:191], v[204:207], v[34:37]
	v_mfma_f32_16x16x32_bf16 v[38:41], v[176:179], v[200:203], v[38:41]
	v_mfma_f32_16x16x32_bf16 v[38:41], v[180:183], v[204:207], v[38:41]
	v_mfma_f32_16x16x32_bf16 v[22:25], v[176:179], v[208:211], v[22:25]
	v_mfma_f32_16x16x32_bf16 v[22:25], v[180:183], v[212:215], v[22:25]
	v_mfma_f32_16x16x32_bf16 v[18:21], v[184:187], v[208:211], v[18:21]
	v_mfma_f32_16x16x32_bf16 v[18:21], v[188:191], v[212:215], v[18:21]
	v_mfma_f32_16x16x32_bf16 v[2:5], v[184:187], v[216:219], v[2:5]
	v_mfma_f32_16x16x32_bf16 v[2:5], v[188:191], v[220:223], v[2:5]
	v_mfma_f32_16x16x32_bf16 v[6:9], v[176:179], v[216:219], v[6:9]
	v_mfma_f32_16x16x32_bf16 v[6:9], v[180:183], v[220:223], v[6:9]
	s_setprio 0
	s_barrier
	s_add_i32 s84, 0, 0x18000
	v_add_u32_e32 v163, s84, v157
	s_add_i32 s85, 0, 0x1c000
	ds_read_b128 v[130:133], v163
	ds_read_b128 v[164:167], v163 offset:1024
	ds_read_b128 v[168:171], v163 offset:2048
	ds_read_b128 v[172:175], v163 offset:3072
	v_add_u32_e32 v163, s85, v157
	ds_read_b128 v[176:179], v163
	ds_read_b128 v[180:183], v163 offset:1024
	ds_read_b128 v[184:187], v163 offset:2048
	ds_read_b128 v[188:191], v163 offset:3072
	s_add_u32 s36, s36, 0x100000
	s_addc_u32 s37, s37, 0
	s_mov_b32 m0, s54
	v_lshl_add_u64 v[230:231], s[36:37], 0, v[134:135]
	ds_read_b128 v[192:195], v159 offset:32768
	ds_read_b128 v[196:199], v159 offset:33792
	ds_read_b128 v[200:203], v159 offset:34816
	ds_read_b128 v[204:207], v159 offset:35840
	ds_read_b128 v[208:211], v159 offset:36864
	ds_read_b128 v[212:215], v159 offset:37888
	ds_read_b128 v[216:219], v159 offset:38912
	ds_read_b128 v[220:223], v159 offset:39936
	global_load_lds_dwordx4 v[230:231], off
	v_lshl_add_u64 v[230:231], s[36:37], 0, v[138:139]
	s_mov_b32 m0, s55
	s_nop 0
	global_load_lds_dwordx4 v[230:231], off
	s_waitcnt vmcnt(8)
	s_waitcnt lgkmcnt(0)
	s_barrier
	s_setprio 3
	v_mfma_f32_16x16x32_bf16 v[126:129], v[130:133], v[192:195], v[126:129]
	v_mfma_f32_16x16x32_bf16 v[126:129], v[164:167], v[196:199], v[126:129]
	v_mfma_f32_16x16x32_bf16 v[122:125], v[168:171], v[192:195], v[122:125]
	v_mfma_f32_16x16x32_bf16 v[122:125], v[172:175], v[196:199], v[122:125]
	v_mfma_f32_16x16x32_bf16 v[106:109], v[168:171], v[200:203], v[106:109]
	v_mfma_f32_16x16x32_bf16 v[106:109], v[172:175], v[204:207], v[106:109]
	v_mfma_f32_16x16x32_bf16 v[110:113], v[130:133], v[200:203], v[110:113]
	v_mfma_f32_16x16x32_bf16 v[110:113], v[164:167], v[204:207], v[110:113]
	v_mfma_f32_16x16x32_bf16 v[94:97], v[130:133], v[208:211], v[94:97]
	v_mfma_f32_16x16x32_bf16 v[94:97], v[164:167], v[212:215], v[94:97]
	v_mfma_f32_16x16x32_bf16 v[90:93], v[168:171], v[208:211], v[90:93]
	v_mfma_f32_16x16x32_bf16 v[90:93], v[172:175], v[212:215], v[90:93]
	v_mfma_f32_16x16x32_bf16 v[74:77], v[168:171], v[216:219], v[74:77]
	v_mfma_f32_16x16x32_bf16 v[74:77], v[172:175], v[220:223], v[74:77]
	v_mfma_f32_16x16x32_bf16 v[78:81], v[130:133], v[216:219], v[78:81]
	v_mfma_f32_16x16x32_bf16 v[78:81], v[164:167], v[220:223], v[78:81]
	v_mfma_f32_16x16x32_bf16 v[118:121], v[176:179], v[192:195], v[118:121]
	v_mfma_f32_16x16x32_bf16 v[118:121], v[180:183], v[196:199], v[118:121]
	v_mfma_f32_16x16x32_bf16 v[114:117], v[184:187], v[192:195], v[114:117]
	v_mfma_f32_16x16x32_bf16 v[114:117], v[188:191], v[196:199], v[114:117]
	v_mfma_f32_16x16x32_bf16 v[98:101], v[184:187], v[200:203], v[98:101]
	v_mfma_f32_16x16x32_bf16 v[98:101], v[188:191], v[204:207], v[98:101]
	v_mfma_f32_16x16x32_bf16 v[102:105], v[176:179], v[200:203], v[102:105]
	v_mfma_f32_16x16x32_bf16 v[102:105], v[180:183], v[204:207], v[102:105]
	v_mfma_f32_16x16x32_bf16 v[86:89], v[176:179], v[208:211], v[86:89]
	v_mfma_f32_16x16x32_bf16 v[86:89], v[180:183], v[212:215], v[86:89]
	v_mfma_f32_16x16x32_bf16 v[82:85], v[184:187], v[208:211], v[82:85]
	v_mfma_f32_16x16x32_bf16 v[82:85], v[188:191], v[212:215], v[82:85]
	v_mfma_f32_16x16x32_bf16 v[66:69], v[184:187], v[216:219], v[66:69]
	v_mfma_f32_16x16x32_bf16 v[66:69], v[188:191], v[220:223], v[66:69]
	v_mfma_f32_16x16x32_bf16 v[70:73], v[176:179], v[216:219], v[70:73]
	v_mfma_f32_16x16x32_bf16 v[70:73], v[180:183], v[220:223], v[70:73]
	s_setprio 0
	s_barrier
; #define PG8_STAGE(bufoff, gbase, voff) do { _Pragma("unroll") for (int _i = 0; _i < 2; ++_i) \
;         __builtin_amdgcn_global_load_lds((const unsigned*)((const char*)(gbase) + (voff)[_i]), (PG8_LAS unsigned*)(lds + (bufoff) + ldsw + _i * 8192), 16, 0, 0); } while (0)
; #define PG8_LDA(dst, b, h) do { _Pragma("unroll") for (int m = 0; m < 4; ++m) _Pragma("unroll") for (int k = 0; k < 2; ++k) dst[m][k] = *(const PG8_LAS bf16x8*)(lds + PG8_SA(b, h) + aoff + m * 2048 + k * 1024); } while (0)
; #define PG8_MMA(ai, bj, At, Bt) do { __builtin_amdgcn_s_setprio(3); _Pragma("unroll") for (int m = 0; m < 4; ++m) _Pragma("unroll") for (int n = 0; n < 2; ++n) _Pragma("unroll") for (int k = 0; k < 2; ++k) \
;         acc[ai][bj][m][n] = __builtin_amdgcn_mfma_f32_16x16x32_bf16(Bt[n][k], At[m][k], acc[ai][bj][m][n], 0, 0, 0); __builtin_amdgcn_s_setprio(0); } while (0)
; #define PG8_WAIT_V(n) asm volatile("s_waitcnt vmcnt(" #n ")" ::: "memory")
; #define PG8_WAIT_L(n) asm volatile("s_waitcnt lgkmcnt(" #n ")" ::: "memory")
; #define PG8_BAR __builtin_amdgcn_s_barrier()
; #define PG8_SCHED __builtin_amdgcn_sched_barrier(0)
; template <class Epi, class Sched, bool ALIGN_EPI = false, bool SP2 = false>
; __device__ __forceinline__ void gemm_phase(PG8_LAS unsigned char* lds, const Gemm g, const Sched& S, const Epi& E) {
;     ...
;             PG8_LDA(At, 1, 1); PG8_STAGE(PG8_SB(1, 0), b3, voffB); PG8_STAGE(PG8_SB(1, 1), b3 + hstepB, voffB); PG8_STAGE(PG8_SA(1, 0), a3, voffA);
;             PG8_WAIT_V(8); PG8_WAIT_L(0); PG8_BAR; PG8_MMA(1, 0, At, B0); PG8_MMA(1, 1, At, B1); PG8_BAR; PG8_SCHED;
	s_add_i32 s36, s84, s33
	v_lshl_add_u64 v[160:161], v[160:161], 0, s[10:11]
	s_mov_b32 m0, s36
	ds_read_b128 v[192:195], v159 offset:49152
	ds_read_b128 v[196:199], v159 offset:50176
	ds_read_b128 v[200:203], v159 offset:51200
	ds_read_b128 v[204:207], v159 offset:52224
	ds_read_b128 v[208:211], v159 offset:53248
	ds_read_b128 v[212:215], v159 offset:54272
	ds_read_b128 v[216:219], v159 offset:55296
	ds_read_b128 v[220:223], v159 offset:56320
	global_load_lds_dwordx4 v[160:161], off
	s_add_i32 m0, s36, 0x2000
	s_add_u32 s0, s0, 0x100080
	v_lshl_add_u64 v[160:161], v[224:225], 0, s[10:11]
	s_addc_u32 s1, s1, 0
	s_add_i32 s36, s85, s33
	global_load_lds_dwordx4 v[160:161], off
	v_lshl_add_u64 v[160:161], s[0:1], 0, v[136:137]
	s_mov_b32 m0, s36
	s_nop 0
	global_load_lds_dwordx4 v[160:161], off
	v_lshl_add_u64 v[160:161], s[0:1], 0, v[140:141]
	s_add_i32 m0, s36, 0x2000
	s_nop 0
	global_load_lds_dwordx4 v[160:161], off
	v_lshl_add_u64 v[160:161], v[226:227], 0, s[10:11]
	s_mov_b32 m0, s61
	s_nop 0
	global_load_lds_dwordx4 v[160:161], off
	v_lshl_add_u64 v[160:161], v[228:229], 0, s[10:11]
	s_mov_b32 m0, s62
	s_nop 0
	global_load_lds_dwordx4 v[160:161], off
	s_waitcnt vmcnt(8)
	s_waitcnt lgkmcnt(0)
	s_barrier
	s_setprio 3
	v_mfma_f32_16x16x32_bf16 v[62:65], v[130:133], v[192:195], v[62:65]
	v_mfma_f32_16x16x32_bf16 v[62:65], v[164:167], v[196:199], v[62:65]
	v_mfma_f32_16x16x32_bf16 v[58:61], v[168:171], v[192:195], v[58:61]
	v_mfma_f32_16x16x32_bf16 v[58:61], v[172:175], v[196:199], v[58:61]
	v_mfma_f32_16x16x32_bf16 v[42:45], v[168:171], v[200:203], v[42:45]
	v_mfma_f32_16x16x32_bf16 v[42:45], v[172:175], v[204:207], v[42:45]
	v_mfma_f32_16x16x32_bf16 v[46:49], v[130:133], v[200:203], v[46:49]
	v_mfma_f32_16x16x32_bf16 v[46:49], v[164:167], v[204:207], v[46:49]
	v_mfma_f32_16x16x32_bf16 v[30:33], v[130:133], v[208:211], v[30:33]
	v_mfma_f32_16x16x32_bf16 v[30:33], v[164:167], v[212:215], v[30:33]
	v_mfma_f32_16x16x32_bf16 v[26:29], v[168:171], v[208:211], v[26:29]
	v_mfma_f32_16x16x32_bf16 v[26:29], v[172:175], v[212:215], v[26:29]
	v_mfma_f32_16x16x32_bf16 v[10:13], v[168:171], v[216:219], v[10:13]
	v_mfma_f32_16x16x32_bf16 v[10:13], v[172:175], v[220:223], v[10:13]
	v_mfma_f32_16x16x32_bf16 v[14:17], v[130:133], v[216:219], v[14:17]
	v_mfma_f32_16x16x32_bf16 v[14:17], v[164:167], v[220:223], v[14:17]
	v_mfma_f32_16x16x32_bf16 v[54:57], v[176:179], v[192:195], v[54:57]
	v_mfma_f32_16x16x32_bf16 v[54:57], v[180:183], v[196:199], v[54:57]
	v_mfma_f32_16x16x32_bf16 v[50:53], v[184:187], v[192:195], v[50:53]
	v_mfma_f32_16x16x32_bf16 v[50:53], v[188:191], v[196:199], v[50:53]
	v_mfma_f32_16x16x32_bf16 v[34:37], v[184:187], v[200:203], v[34:37]
	v_mfma_f32_16x16x32_bf16 v[34:37], v[188:191], v[204:207], v[34:37]
	v_mfma_f32_16x16x32_bf16 v[38:41], v[176:179], v[200:203], v[38:41]
	v_mfma_f32_16x16x32_bf16 v[38:41], v[180:183], v[204:207], v[38:41]
	v_mfma_f32_16x16x32_bf16 v[22:25], v[176:179], v[208:211], v[22:25]
	v_mfma_f32_16x16x32_bf16 v[22:25], v[180:183], v[212:215], v[22:25]
	v_mfma_f32_16x16x32_bf16 v[18:21], v[184:187], v[208:211], v[18:21]
	v_mfma_f32_16x16x32_bf16 v[18:21], v[188:191], v[212:215], v[18:21]
	v_mfma_f32_16x16x32_bf16 v[2:5], v[184:187], v[216:219], v[2:5]
	v_mfma_f32_16x16x32_bf16 v[2:5], v[188:191], v[220:223], v[2:5]
	v_mfma_f32_16x16x32_bf16 v[6:9], v[176:179], v[216:219], v[6:9]
	v_mfma_f32_16x16x32_bf16 v[6:9], v[180:183], v[220:223], v[6:9]
	s_setprio 0
	s_barrier
	s_add_i32 s83, s83, 2
	s_add_u32 s30, s30, 0x100
	s_addc_u32 s31, s31, 0
	s_cmp_gt_u32 s83, 61
	s_cbranch_scc1 .LBB0_730

; #define PG8_STAGE(bufoff, gbase, voff) do { _Pragma("unroll") for (int _i = 0; _i < 2; ++_i) \
;         __builtin_amdgcn_global_load_lds((const unsigned*)((const char*)(gbase) + (voff)[_i]), (PG8_LAS unsigned*)(lds + (bufoff) + ldsw + _i * 8192), 16, 0, 0); } while (0)
; #define PG8_LDA(dst, b, h) do { _Pragma("unroll") for (int m = 0; m < 4; ++m) _Pragma("unroll") for (int k = 0; k < 2; ++k) dst[m][k] = *(const PG8_LAS bf16x8*)(lds + PG8_SA(b, h) + aoff + m * 2048 + k * 1024); } while (0)
; #define PG8_LDB(dst, b, h) do { _Pragma("unroll") for (int n = 0; n < 2; ++n) _Pragma("unroll") for (int k = 0; k < 2; ++k) dst[n][k] = *(const PG8_LAS bf16x8*)(lds + PG8_SB(b, h) + boff + n * 2048 + k * 1024); } while (0)
; #define PG8_MMA(ai, bj, At, Bt) do { __builtin_amdgcn_s_setprio(3); _Pragma("unroll") for (int m = 0; m < 4; ++m) _Pragma("unroll") for (int n = 0; n < 2; ++n) _Pragma("unroll") for (int k = 0; k < 2; ++k) \
;         acc[ai][bj][m][n] = __builtin_amdgcn_mfma_f32_16x16x32_bf16(Bt[n][k], At[m][k], acc[ai][bj][m][n], 0, 0, 0); __builtin_amdgcn_s_setprio(0); } while (0)
; #define PG8_WAIT_V(n) asm volatile("s_waitcnt vmcnt(" #n ")" ::: "memory")
; template <class Epi, class Sched, bool ALIGN_EPI = false, bool SP2 = false>
; __device__ __forceinline__ void gemm_phase(PG8_LAS unsigned char* lds, const Gemm g, const Sched& S, const Epi& E) {
;     ...
;             const bool last = (t == nt - 2);
;             const char* a1 = cA + (size_t)(t + 1) * kstep;
;             const char* a2 = last ? nA : cA + (size_t)(t + 2) * kstep; const char* b2 = last ? nB : cB + (size_t)(t + 2) * kstep;
;             const char* a3 = a2 + kstep; const char* b3 = b2 + kstep;
;             if (last && has_next) S.a_ready(nxt);
;             if constexpr (Epi::MIDK) { if (t == E.midk_step(nt)) E.midk(acc, cur, wr, wc, fr, fq); }
;             if constexpr (SP2) {
;             PG8_LDB(B0, 0, 0); PG8_LDB(B1, 0, 1); PG8_SCHED; PG8_LDA(At, 0, 0); PG8_STAGE(PG8_SA(1, 1), a1 + hstepA, voffA);
;             PG8_WAIT_V(8); PG8_WAIT_L(0); PG8_BAR; PG8_MMA(0, 0, At, B0); PG8_MMA(0, 1, At, B1); PG8_BAR; PG8_SCHED;
;             PG8_LDA(At, 0, 1); PG8_STAGE(PG8_SB(0, 0), b2, voffB); PG8_STAGE(PG8_SB(0, 1), b2 + hstepB, voffB); PG8_STAGE(PG8_SA(0, 0), a2, voffA);
;             PG8_WAIT_V(8); PG8_WAIT_L(0); PG8_BAR; PG8_MMA(1, 0, At, B0); PG8_MMA(1, 1, At, B1); PG8_BAR; PG8_SCHED;
.LBB0_808:
	v_add_u32_e32 v3, s65, v186
	ds_read_b128 v[134:137], v3
	ds_read_b128 v[138:141], v3 offset:1024
	ds_read_b128 v[142:145], v3 offset:2048
	ds_read_b128 v[146:149], v3 offset:3072
	v_add_u32_e32 v3, s66, v186
	s_add_u32 s36, s28, s30
	ds_read_b128 v[150:153], v3
	ds_read_b128 v[154:157], v3 offset:1024
	ds_read_b128 v[158:161], v3 offset:2048
	ds_read_b128 v[190:193], v3 offset:3072
	s_addc_u32 s37, s29, s31
	s_add_u32 s36, s36, 0x100
	s_addc_u32 s37, s37, 0
	s_add_u32 s86, s83, s30
	s_addc_u32 s87, s84, s31
	s_cmpk_eq_i32 s30, 0x1f00
	s_cselect_b32 s41, s23, s37
	s_cselect_b32 s40, s75, s36
	s_cselect_b32 s37, s77, s87
	s_cselect_b32 s36, s78, s86
	v_lshl_add_u64 v[4:5], v[180:181], 0, s[30:31]
	s_add_i32 m0, s42, 0xc000
	ds_read_b128 v[194:197], v188
	ds_read_b128 v[198:201], v188 offset:1024
	ds_read_b128 v[202:205], v188 offset:2048
	ds_read_b128 v[206:209], v188 offset:3072
	ds_read_b128 v[210:213], v188 offset:4096
	ds_read_b128 v[214:217], v188 offset:5120
	ds_read_b128 v[218:221], v188 offset:6144
	ds_read_b128 v[222:225], v188 offset:7168
	global_load_lds_dwordx4 v[4:5], off
	v_lshl_add_u64 v[4:5], v[182:183], 0, s[30:31]
	s_add_i32 m0, s42, 0xe000
	s_nop 0
	global_load_lds_dwordx4 v[4:5], off
	s_waitcnt vmcnt(8)
	s_waitcnt lgkmcnt(0)
	s_barrier
	s_setprio 3
	v_mfma_f32_16x16x32_bf16 v[130:133], v[134:137], v[194:197], v[130:133]
	v_mfma_f32_16x16x32_bf16 v[130:133], v[138:141], v[198:201], v[130:133]
	v_mfma_f32_16x16x32_bf16 v[126:129], v[142:145], v[194:197], v[126:129]
	v_mfma_f32_16x16x32_bf16 v[126:129], v[146:149], v[198:201], v[126:129]
	v_mfma_f32_16x16x32_bf16 v[110:113], v[142:145], v[202:205], v[110:113]
	v_mfma_f32_16x16x32_bf16 v[110:113], v[146:149], v[206:209], v[110:113]
	v_mfma_f32_16x16x32_bf16 v[114:117], v[134:137], v[202:205], v[114:117]
	v_mfma_f32_16x16x32_bf16 v[114:117], v[138:141], v[206:209], v[114:117]
	v_mfma_f32_16x16x32_bf16 v[98:101], v[134:137], v[210:213], v[98:101]
	v_mfma_f32_16x16x32_bf16 v[98:101], v[138:141], v[214:217], v[98:101]
	v_mfma_f32_16x16x32_bf16 v[94:97], v[142:145], v[210:213], v[94:97]
	v_mfma_f32_16x16x32_bf16 v[94:97], v[146:149], v[214:217], v[94:97]
	v_mfma_f32_16x16x32_bf16 v[78:81], v[142:145], v[218:221], v[78:81]
	v_mfma_f32_16x16x32_bf16 v[78:81], v[146:149], v[222:225], v[78:81]
	v_mfma_f32_16x16x32_bf16 v[82:85], v[134:137], v[218:221], v[82:85]
	v_mfma_f32_16x16x32_bf16 v[82:85], v[138:141], v[222:225], v[82:85]
	v_mfma_f32_16x16x32_bf16 v[122:125], v[150:153], v[194:197], v[122:125]
	v_mfma_f32_16x16x32_bf16 v[122:125], v[154:157], v[198:201], v[122:125]
	v_mfma_f32_16x16x32_bf16 v[118:121], v[158:161], v[194:197], v[118:121]
	v_mfma_f32_16x16x32_bf16 v[118:121], v[190:193], v[198:201], v[118:121]
	v_mfma_f32_16x16x32_bf16 v[102:105], v[158:161], v[202:205], v[102:105]
	v_mfma_f32_16x16x32_bf16 v[102:105], v[190:193], v[206:209], v[102:105]
	v_mfma_f32_16x16x32_bf16 v[106:109], v[150:153], v[202:205], v[106:109]
	v_mfma_f32_16x16x32_bf16 v[106:109], v[154:157], v[206:209], v[106:109]
	v_mfma_f32_16x16x32_bf16 v[90:93], v[150:153], v[210:213], v[90:93]
	v_mfma_f32_16x16x32_bf16 v[90:93], v[154:157], v[214:217], v[90:93]
	v_mfma_f32_16x16x32_bf16 v[86:89], v[158:161], v[210:213], v[86:89]
	v_mfma_f32_16x16x32_bf16 v[86:89], v[190:193], v[214:217], v[86:89]
	v_mfma_f32_16x16x32_bf16 v[70:73], v[158:161], v[218:221], v[70:73]
	v_mfma_f32_16x16x32_bf16 v[70:73], v[190:193], v[222:225], v[70:73]
	v_mfma_f32_16x16x32_bf16 v[74:77], v[150:153], v[218:221], v[74:77]
	v_mfma_f32_16x16x32_bf16 v[74:77], v[154:157], v[222:225], v[74:77]
	s_setprio 0
	s_barrier
	s_add_i32 s86, s65, s33
	v_lshl_add_u64 v[226:227], s[36:37], 0, v[166:167]
	s_mov_b32 m0, s86
	ds_read_b128 v[194:197], v188 offset:16384
	ds_read_b128 v[198:201], v188 offset:17408
	ds_read_b128 v[202:205], v188 offset:18432
	ds_read_b128 v[206:209], v188 offset:19456
	ds_read_b128 v[210:213], v188 offset:20480
	ds_read_b128 v[214:217], v188 offset:21504
	ds_read_b128 v[218:221], v188 offset:22528
	ds_read_b128 v[222:225], v188 offset:23552
	global_load_lds_dwordx4 v[226:227], off
	s_add_i32 m0, s86, 0x2000
	s_add_u32 s86, s36, 0x100000
	v_lshl_add_u64 v[228:229], s[36:37], 0, v[170:171]
	s_addc_u32 s87, s37, 0
	s_add_i32 s88, s66, s33
	global_load_lds_dwordx4 v[228:229], off
	v_lshl_add_u64 v[4:5], s[86:87], 0, v[166:167]
	s_mov_b32 m0, s88
	v_lshl_add_u64 v[230:231], s[40:41], 0, v[164:165]
	global_load_lds_dwordx4 v[4:5], off
	v_lshl_add_u64 v[4:5], s[86:87], 0, v[170:171]
	s_add_i32 m0, s88, 0x2000
	v_lshl_add_u64 v[232:233], s[40:41], 0, v[168:169]
	global_load_lds_dwordx4 v[4:5], off
	s_mov_b32 m0, s42
	s_nop 0
	global_load_lds_dwordx4 v[230:231], off
	s_mov_b32 m0, s43
	s_nop 0
	global_load_lds_dwordx4 v[232:233], off
	s_waitcnt vmcnt(8)
	s_waitcnt lgkmcnt(0)
	s_barrier
; #define PG8_STAGE(bufoff, gbase, voff) do { _Pragma("unroll") for (int _i = 0; _i < 2; ++_i) \
;         __builtin_amdgcn_global_load_lds((const unsigned*)((const char*)(gbase) + (voff)[_i]), (PG8_LAS unsigned*)(lds + (bufoff) + ldsw + _i * 8192), 16, 0, 0); } while (0)
; #define PG8_LDA(dst, b, h) do { _Pragma("unroll") for (int m = 0; m < 4; ++m) _Pragma("unroll") for (int k = 0; k < 2; ++k) dst[m][k] = *(const PG8_LAS bf16x8*)(lds + PG8_SA(b, h) + aoff + m * 2048 + k * 1024); } while (0)
; #define PG8_LDB(dst, b, h) do { _Pragma("unroll") for (int n = 0; n < 2; ++n) _Pragma("unroll") for (int k = 0; k < 2; ++k) dst[n][k] = *(const PG8_LAS bf16x8*)(lds + PG8_SB(b, h) + boff + n * 2048 + k * 1024); } while (0)
; #define PG8_MMA(ai, bj, At, Bt) do { __builtin_amdgcn_s_setprio(3); _Pragma("unroll") for (int m = 0; m < 4; ++m) _Pragma("unroll") for (int n = 0; n < 2; ++n) _Pragma("unroll") for (int k = 0; k < 2; ++k) \
;         acc[ai][bj][m][n] = __builtin_amdgcn_mfma_f32_16x16x32_bf16(Bt[n][k], At[m][k], acc[ai][bj][m][n], 0, 0, 0); __builtin_amdgcn_s_setprio(0); } while (0)
; #define PG8_WAIT_V(n) asm volatile("s_waitcnt vmcnt(" #n ")" ::: "memory")
; #define PG8_WAIT_L(n) asm volatile("s_waitcnt lgkmcnt(" #n ")" ::: "memory")
; #define PG8_BAR __builtin_amdgcn_s_barrier()
; #define PG8_SCHED __builtin_amdgcn_sched_barrier(0)
; template <class Epi, class Sched, bool ALIGN_EPI = false, bool SP2 = false>
; __device__ __forceinline__ void gemm_phase(PG8_LAS unsigned char* lds, const Gemm g, const Sched& S, const Epi& E) {
;     ...
;             PG8_WAIT_V(8); PG8_WAIT_L(0); PG8_BAR; PG8_MMA(1, 0, At, B0); PG8_MMA(1, 1, At, B1); PG8_BAR; PG8_SCHED;
;             PG8_LDB(B0, 1, 0); PG8_LDB(B1, 1, 1); PG8_SCHED; PG8_LDA(At, 1, 0); PG8_STAGE(PG8_SA(0, 1), a2 + hstepA, voffA);
;             PG8_WAIT_V(8); PG8_WAIT_L(0); PG8_BAR; PG8_MMA(0, 0, At, B0); PG8_MMA(0, 1, At, B1); PG8_BAR; PG8_SCHED;
	s_setprio 3
	v_mfma_f32_16x16x32_bf16 v[66:69], v[134:137], v[194:197], v[66:69]
	v_mfma_f32_16x16x32_bf16 v[66:69], v[138:141], v[198:201], v[66:69]
	v_mfma_f32_16x16x32_bf16 v[62:65], v[142:145], v[194:197], v[62:65]
	v_mfma_f32_16x16x32_bf16 v[62:65], v[146:149], v[198:201], v[62:65]
	v_mfma_f32_16x16x32_bf16 v[46:49], v[142:145], v[202:205], v[46:49]
	v_mfma_f32_16x16x32_bf16 v[46:49], v[146:149], v[206:209], v[46:49]
	v_mfma_f32_16x16x32_bf16 v[50:53], v[134:137], v[202:205], v[50:53]
	v_mfma_f32_16x16x32_bf16 v[50:53], v[138:141], v[206:209], v[50:53]
	v_mfma_f32_16x16x32_bf16 v[34:37], v[134:137], v[210:213], v[34:37]
	v_mfma_f32_16x16x32_bf16 v[34:37], v[138:141], v[214:217], v[34:37]
	v_mfma_f32_16x16x32_bf16 v[30:33], v[142:145], v[210:213], v[30:33]
	v_mfma_f32_16x16x32_bf16 v[30:33], v[146:149], v[214:217], v[30:33]
	v_mfma_f32_16x16x32_bf16 v[14:17], v[142:145], v[218:221], v[14:17]
	v_mfma_f32_16x16x32_bf16 v[14:17], v[146:149], v[222:225], v[14:17]
	v_mfma_f32_16x16x32_bf16 v[18:21], v[134:137], v[218:221], v[18:21]
	v_mfma_f32_16x16x32_bf16 v[18:21], v[138:141], v[222:225], v[18:21]
	v_mfma_f32_16x16x32_bf16 v[58:61], v[150:153], v[194:197], v[58:61]
	v_mfma_f32_16x16x32_bf16 v[58:61], v[154:157], v[198:201], v[58:61]
	v_mfma_f32_16x16x32_bf16 v[54:57], v[158:161], v[194:197], v[54:57]
	v_mfma_f32_16x16x32_bf16 v[54:57], v[190:193], v[198:201], v[54:57]
	v_mfma_f32_16x16x32_bf16 v[38:41], v[158:161], v[202:205], v[38:41]
	v_mfma_f32_16x16x32_bf16 v[38:41], v[190:193], v[206:209], v[38:41]
	v_mfma_f32_16x16x32_bf16 v[42:45], v[150:153], v[202:205], v[42:45]
	v_mfma_f32_16x16x32_bf16 v[42:45], v[154:157], v[206:209], v[42:45]
	v_mfma_f32_16x16x32_bf16 v[26:29], v[150:153], v[210:213], v[26:29]
	v_mfma_f32_16x16x32_bf16 v[26:29], v[154:157], v[214:217], v[26:29]
	v_mfma_f32_16x16x32_bf16 v[22:25], v[158:161], v[210:213], v[22:25]
	v_mfma_f32_16x16x32_bf16 v[22:25], v[190:193], v[214:217], v[22:25]
	v_mfma_f32_16x16x32_bf16 v[4:7], v[158:161], v[218:221], v[6:9]
	v_mfma_f32_16x16x32_bf16 v[4:7], v[190:193], v[222:225], v[4:7]
	v_mfma_f32_16x16x32_bf16 v[10:13], v[150:153], v[218:221], v[10:13]
	v_mfma_f32_16x16x32_bf16 v[10:13], v[154:157], v[222:225], v[10:13]
	s_setprio 0
	s_barrier
	s_add_i32 s86, 0, 0x18000
	v_add_u32_e32 v3, s86, v186
	s_add_i32 s87, 0, 0x1c000
	ds_read_b128 v[134:137], v3
	ds_read_b128 v[138:141], v3 offset:1024
	ds_read_b128 v[142:145], v3 offset:2048
	ds_read_b128 v[146:149], v3 offset:3072
	v_add_u32_e32 v3, s87, v186
	ds_read_b128 v[150:153], v3
	ds_read_b128 v[154:157], v3 offset:1024
	ds_read_b128 v[158:161], v3 offset:2048
	ds_read_b128 v[190:193], v3 offset:3072
	s_add_u32 s40, s40, 0x100000
	s_addc_u32 s41, s41, 0
	s_mov_b32 m0, s44
	v_lshl_add_u64 v[8:9], s[40:41], 0, v[164:165]
	ds_read_b128 v[194:197], v188 offset:32768
	ds_read_b128 v[198:201], v188 offset:33792
	ds_read_b128 v[202:205], v188 offset:34816
	ds_read_b128 v[206:209], v188 offset:35840
	ds_read_b128 v[210:213], v188 offset:36864
	ds_read_b128 v[214:217], v188 offset:37888
	ds_read_b128 v[218:221], v188 offset:38912
	ds_read_b128 v[222:225], v188 offset:39936
	global_load_lds_dwordx4 v[8:9], off
	v_lshl_add_u64 v[8:9], s[40:41], 0, v[168:169]
	s_mov_b32 m0, s45
	s_nop 0
	global_load_lds_dwordx4 v[8:9], off
	s_waitcnt vmcnt(8)
	s_waitcnt lgkmcnt(0)
	s_barrier
	s_setprio 3
	v_mfma_f32_16x16x32_bf16 v[130:133], v[134:137], v[194:197], v[130:133]
	v_mfma_f32_16x16x32_bf16 v[130:133], v[138:141], v[198:201], v[130:133]
	v_mfma_f32_16x16x32_bf16 v[126:129], v[142:145], v[194:197], v[126:129]
	v_mfma_f32_16x16x32_bf16 v[126:129], v[146:149], v[198:201], v[126:129]
	v_mfma_f32_16x16x32_bf16 v[110:113], v[142:145], v[202:205], v[110:113]
	v_mfma_f32_16x16x32_bf16 v[110:113], v[146:149], v[206:209], v[110:113]
	v_mfma_f32_16x16x32_bf16 v[114:117], v[134:137], v[202:205], v[114:117]
	v_mfma_f32_16x16x32_bf16 v[114:117], v[138:141], v[206:209], v[114:117]
	v_mfma_f32_16x16x32_bf16 v[98:101], v[134:137], v[210:213], v[98:101]
	v_mfma_f32_16x16x32_bf16 v[98:101], v[138:141], v[214:217], v[98:101]
	v_mfma_f32_16x16x32_bf16 v[94:97], v[142:145], v[210:213], v[94:97]
	v_mfma_f32_16x16x32_bf16 v[94:97], v[146:149], v[214:217], v[94:97]
	v_mfma_f32_16x16x32_bf16 v[78:81], v[142:145], v[218:221], v[78:81]
	v_mfma_f32_16x16x32_bf16 v[78:81], v[146:149], v[222:225], v[78:81]
	v_mfma_f32_16x16x32_bf16 v[82:85], v[134:137], v[218:221], v[82:85]
	v_mfma_f32_16x16x32_bf16 v[82:85], v[138:141], v[222:225], v[82:85]
	v_mfma_f32_16x16x32_bf16 v[122:125], v[150:153], v[194:197], v[122:125]
	v_mfma_f32_16x16x32_bf16 v[122:125], v[154:157], v[198:201], v[122:125]
	v_mfma_f32_16x16x32_bf16 v[118:121], v[158:161], v[194:197], v[118:121]
	v_mfma_f32_16x16x32_bf16 v[118:121], v[190:193], v[198:201], v[118:121]
	v_mfma_f32_16x16x32_bf16 v[102:105], v[158:161], v[202:205], v[102:105]
	v_mfma_f32_16x16x32_bf16 v[102:105], v[190:193], v[206:209], v[102:105]
	v_mfma_f32_16x16x32_bf16 v[106:109], v[150:153], v[202:205], v[106:109]
	v_mfma_f32_16x16x32_bf16 v[106:109], v[154:157], v[206:209], v[106:109]
	v_mfma_f32_16x16x32_bf16 v[90:93], v[150:153], v[210:213], v[90:93]
	v_mfma_f32_16x16x32_bf16 v[90:93], v[154:157], v[214:217], v[90:93]
	v_mfma_f32_16x16x32_bf16 v[86:89], v[158:161], v[210:213], v[86:89]
	v_mfma_f32_16x16x32_bf16 v[86:89], v[190:193], v[214:217], v[86:89]
	v_mfma_f32_16x16x32_bf16 v[70:73], v[158:161], v[218:221], v[70:73]
	v_mfma_f32_16x16x32_bf16 v[70:73], v[190:193], v[222:225], v[70:73]
	v_mfma_f32_16x16x32_bf16 v[74:77], v[150:153], v[218:221], v[74:77]
	v_mfma_f32_16x16x32_bf16 v[74:77], v[154:157], v[222:225], v[74:77]
	s_setprio 0
	s_barrier
; #define PG8_STAGE(bufoff, gbase, voff) do { _Pragma("unroll") for (int _i = 0; _i < 2; ++_i) \
;         __builtin_amdgcn_global_load_lds((const unsigned*)((const char*)(gbase) + (voff)[_i]), (PG8_LAS unsigned*)(lds + (bufoff) + ldsw + _i * 8192), 16, 0, 0); } while (0)
; #define PG8_LDA(dst, b, h) do { _Pragma("unroll") for (int m = 0; m < 4; ++m) _Pragma("unroll") for (int k = 0; k < 2; ++k) dst[m][k] = *(const PG8_LAS bf16x8*)(lds + PG8_SA(b, h) + aoff + m * 2048 + k * 1024); } while (0)
; #define PG8_MMA(ai, bj, At, Bt) do { __builtin_amdgcn_s_setprio(3); _Pragma("unroll") for (int m = 0; m < 4; ++m) _Pragma("unroll") for (int n = 0; n < 2; ++n) _Pragma("unroll") for (int k = 0; k < 2; ++k) \
;         acc[ai][bj][m][n] = __builtin_amdgcn_mfma_f32_16x16x32_bf16(Bt[n][k], At[m][k], acc[ai][bj][m][n], 0, 0, 0); __builtin_amdgcn_s_setprio(0); } while (0)
; #define PG8_WAIT_V(n) asm volatile("s_waitcnt vmcnt(" #n ")" ::: "memory")
; #define PG8_WAIT_L(n) asm volatile("s_waitcnt lgkmcnt(" #n ")" ::: "memory")
; #define PG8_BAR __builtin_amdgcn_s_barrier()
; #define PG8_SCHED __builtin_amdgcn_sched_barrier(0)
; template <class Epi, class Sched, bool ALIGN_EPI = false, bool SP2 = false>
; __device__ __forceinline__ void gemm_phase(PG8_LAS unsigned char* lds, const Gemm g, const Sched& S, const Epi& E) {
;     ...
;             PG8_LDA(At, 1, 1); PG8_STAGE(PG8_SB(1, 0), b3, voffB); PG8_STAGE(PG8_SB(1, 1), b3 + hstepB, voffB); PG8_STAGE(PG8_SA(1, 0), a3, voffA);
;             PG8_WAIT_V(8); PG8_WAIT_L(0); PG8_BAR; PG8_MMA(1, 0, At, B0); PG8_MMA(1, 1, At, B1); PG8_BAR; PG8_SCHED;
	s_add_i32 s40, s86, s33
	v_lshl_add_u64 v[8:9], v[226:227], 0, s[10:11]
	s_mov_b32 m0, s40
	ds_read_b128 v[194:197], v188 offset:49152
	ds_read_b128 v[198:201], v188 offset:50176
	ds_read_b128 v[202:205], v188 offset:51200
	ds_read_b128 v[206:209], v188 offset:52224
	ds_read_b128 v[210:213], v188 offset:53248
	ds_read_b128 v[214:217], v188 offset:54272
	ds_read_b128 v[218:221], v188 offset:55296
	ds_read_b128 v[222:225], v188 offset:56320
	global_load_lds_dwordx4 v[8:9], off
	s_add_i32 m0, s40, 0x2000
	s_add_u32 s36, s36, 0x100080
	v_lshl_add_u64 v[8:9], v[228:229], 0, s[10:11]
	s_addc_u32 s37, s37, 0
	s_add_i32 s40, s87, s33
	global_load_lds_dwordx4 v[8:9], off
	v_lshl_add_u64 v[8:9], s[36:37], 0, v[166:167]
	s_mov_b32 m0, s40
	s_nop 0
	global_load_lds_dwordx4 v[8:9], off
	v_lshl_add_u64 v[8:9], s[36:37], 0, v[170:171]
	s_add_i32 m0, s40, 0x2000
	s_nop 0
	global_load_lds_dwordx4 v[8:9], off
	v_lshl_add_u64 v[8:9], v[230:231], 0, s[10:11]
	s_mov_b32 m0, s60
	s_nop 0
	global_load_lds_dwordx4 v[8:9], off
	v_lshl_add_u64 v[8:9], v[232:233], 0, s[10:11]
	s_mov_b32 m0, s61
	s_nop 0
	global_load_lds_dwordx4 v[8:9], off
	s_waitcnt vmcnt(8)
	s_waitcnt lgkmcnt(0)
	s_barrier
	s_setprio 3
	v_mfma_f32_16x16x32_bf16 v[66:69], v[134:137], v[194:197], v[66:69]
	v_mfma_f32_16x16x32_bf16 v[66:69], v[138:141], v[198:201], v[66:69]
	v_mfma_f32_16x16x32_bf16 v[62:65], v[142:145], v[194:197], v[62:65]
	v_mfma_f32_16x16x32_bf16 v[62:65], v[146:149], v[198:201], v[62:65]
	v_mfma_f32_16x16x32_bf16 v[46:49], v[142:145], v[202:205], v[46:49]
	v_mfma_f32_16x16x32_bf16 v[46:49], v[146:149], v[206:209], v[46:49]
	v_mfma_f32_16x16x32_bf16 v[50:53], v[134:137], v[202:205], v[50:53]
	v_mfma_f32_16x16x32_bf16 v[50:53], v[138:141], v[206:209], v[50:53]
	v_mfma_f32_16x16x32_bf16 v[34:37], v[134:137], v[210:213], v[34:37]
	v_mfma_f32_16x16x32_bf16 v[34:37], v[138:141], v[214:217], v[34:37]
	v_mfma_f32_16x16x32_bf16 v[30:33], v[142:145], v[210:213], v[30:33]
	v_mfma_f32_16x16x32_bf16 v[30:33], v[146:149], v[214:217], v[30:33]
	v_mfma_f32_16x16x32_bf16 v[14:17], v[142:145], v[218:221], v[14:17]
	v_mfma_f32_16x16x32_bf16 v[14:17], v[146:149], v[222:225], v[14:17]
	v_mfma_f32_16x16x32_bf16 v[18:21], v[134:137], v[218:221], v[18:21]
	v_mfma_f32_16x16x32_bf16 v[18:21], v[138:141], v[222:225], v[18:21]
	v_mfma_f32_16x16x32_bf16 v[58:61], v[150:153], v[194:197], v[58:61]
	v_mfma_f32_16x16x32_bf16 v[54:57], v[158:161], v[194:197], v[54:57]
	v_mfma_f32_16x16x32_bf16 v[42:45], v[150:153], v[202:205], v[42:45]
	v_mfma_f32_16x16x32_bf16 v[38:41], v[158:161], v[202:205], v[38:41]
	v_mfma_f32_16x16x32_bf16 v[26:29], v[150:153], v[210:213], v[26:29]
	v_mfma_f32_16x16x32_bf16 v[22:25], v[158:161], v[210:213], v[22:25]
	v_mfma_f32_16x16x32_bf16 v[8:11], v[150:153], v[218:221], v[10:13]
	v_mfma_f32_16x16x32_bf16 v[4:7], v[158:161], v[218:221], v[4:7]
	v_mfma_f32_16x16x32_bf16 v[58:61], v[154:157], v[198:201], v[58:61]
	v_mfma_f32_16x16x32_bf16 v[54:57], v[190:193], v[198:201], v[54:57]
	v_mfma_f32_16x16x32_bf16 v[42:45], v[154:157], v[206:209], v[42:45]
	v_mfma_f32_16x16x32_bf16 v[38:41], v[190:193], v[206:209], v[38:41]
	v_mfma_f32_16x16x32_bf16 v[26:29], v[154:157], v[214:217], v[26:29]
	v_mfma_f32_16x16x32_bf16 v[22:25], v[190:193], v[214:217], v[22:25]
	v_mfma_f32_16x16x32_bf16 v[10:13], v[154:157], v[222:225], v[8:11]
	v_mfma_f32_16x16x32_bf16 v[6:9], v[190:193], v[222:225], v[4:7]
	s_setprio 0
	s_barrier
	s_add_i32 s85, s85, 2
	s_add_u32 s30, s30, 0x100
	s_addc_u32 s31, s31, 0
	s_cmp_gt_u32 s85, 61
	s_cbranch_scc1 .LBB0_811

; #define PG8_STAGE(bufoff, gbase, voff) do { _Pragma("unroll") for (int _i = 0; _i < 2; ++_i) \
;         __builtin_amdgcn_global_load_lds((const unsigned*)((const char*)(gbase) + (voff)[_i]), (PG8_LAS unsigned*)(lds + (bufoff) + ldsw + _i * 8192), 16, 0, 0); } while (0)
; #define PG8_LDA(dst, b, h) do { _Pragma("unroll") for (int m = 0; m < 4; ++m) _Pragma("unroll") for (int k = 0; k < 2; ++k) dst[m][k] = *(const PG8_LAS bf16x8*)(lds + PG8_SA(b, h) + aoff + m * 2048 + k * 1024); } while (0)
; #define PG8_LDB(dst, b, h) do { _Pragma("unroll") for (int n = 0; n < 2; ++n) _Pragma("unroll") for (int k = 0; k < 2; ++k) dst[n][k] = *(const PG8_LAS bf16x8*)(lds + PG8_SB(b, h) + boff + n * 2048 + k * 1024); } while (0)
; #define PG8_MMA(ai, bj, At, Bt) do { __builtin_amdgcn_s_setprio(3); _Pragma("unroll") for (int m = 0; m < 4; ++m) _Pragma("unroll") for (int n = 0; n < 2; ++n) _Pragma("unroll") for (int k = 0; k < 2; ++k) \
;         acc[ai][bj][m][n] = __builtin_amdgcn_mfma_f32_16x16x32_bf16(Bt[n][k], At[m][k], acc[ai][bj][m][n], 0, 0, 0); __builtin_amdgcn_s_setprio(0); } while (0)
; #define PG8_WAIT_V(n) asm volatile("s_waitcnt vmcnt(" #n ")" ::: "memory")
; template <class Epi, class Sched, bool ALIGN_EPI = false, bool SP2 = false>
; __device__ __forceinline__ void gemm_phase(PG8_LAS unsigned char* lds, const Gemm g, const Sched& S, const Epi& E) {
;     ...
;             const bool last = (t == nt - 2);
;             const char* a1 = cA + (size_t)(t + 1) * kstep;
;             const char* a2 = last ? nA : cA + (size_t)(t + 2) * kstep; const char* b2 = last ? nB : cB + (size_t)(t + 2) * kstep;
;             const char* a3 = a2 + kstep; const char* b3 = b2 + kstep;
;             if (last && has_next) S.a_ready(nxt);
;             if constexpr (Epi::MIDK) { if (t == E.midk_step(nt)) E.midk(acc, cur, wr, wc, fr, fq); }
;             if constexpr (SP2) {
;             PG8_LDB(B0, 0, 0); PG8_LDB(B1, 0, 1); PG8_SCHED; PG8_LDA(At, 0, 0); PG8_STAGE(PG8_SA(1, 1), a1 + hstepA, voffA);
;             PG8_WAIT_V(8); PG8_WAIT_L(0); PG8_BAR; PG8_MMA(0, 0, At, B0); PG8_MMA(0, 1, At, B1); PG8_BAR; PG8_SCHED;
;             PG8_LDA(At, 0, 1); PG8_STAGE(PG8_SB(0, 0), b2, voffB); PG8_STAGE(PG8_SB(0, 1), b2 + hstepB, voffB); PG8_STAGE(PG8_SA(0, 0), a2, voffA);
;             PG8_WAIT_V(8); PG8_WAIT_L(0); PG8_BAR; PG8_MMA(1, 0, At, B0); PG8_MMA(1, 1, At, B1); PG8_BAR; PG8_SCHED;
.LBB0_908:
	ds_read_b128 v[158:161], v155
	ds_read_b128 v[164:167], v155 offset:1024
	ds_read_b128 v[168:171], v155 offset:2048
	ds_read_b128 v[172:175], v155 offset:3072
	ds_read_b128 v[176:179], v156
	ds_read_b128 v[180:183], v156 offset:1024
	ds_read_b128 v[184:187], v156 offset:2048
	ds_read_b128 v[188:191], v156 offset:3072
	s_add_u32 s26, s24, 0xfff00080
	s_addc_u32 s27, s25, -1
	s_cmp_eq_u32 s55, 60
	s_cselect_b32 s29, s17, s27
	s_cselect_b32 s28, s47, s26
	s_cselect_b32 s27, s15, s54
	s_cselect_b32 s26, s52, s53
	v_lshl_add_u64 v[146:147], s[24:25], 0, v[138:139]
	s_add_i32 m0, s23, 0xc000
	ds_read_b128 v[192:195], v157
	ds_read_b128 v[196:199], v157 offset:1024
	ds_read_b128 v[200:203], v157 offset:2048
	ds_read_b128 v[204:207], v157 offset:3072
	ds_read_b128 v[208:211], v157 offset:4096
	ds_read_b128 v[212:215], v157 offset:5120
	ds_read_b128 v[216:219], v157 offset:6144
	ds_read_b128 v[220:223], v157 offset:7168
	global_load_lds_dwordx4 v[146:147], off
	v_lshl_add_u64 v[146:147], s[24:25], 0, v[140:141]
	s_add_i32 m0, s23, 0xe000
	s_nop 0
	global_load_lds_dwordx4 v[146:147], off
	s_waitcnt vmcnt(8)
	s_waitcnt lgkmcnt(0)
	s_barrier
	s_setprio 3
	v_mfma_f32_16x16x32_bf16 v[126:129], v[158:161], v[192:195], v[126:129]
	v_mfma_f32_16x16x32_bf16 v[126:129], v[164:167], v[196:199], v[126:129]
	v_mfma_f32_16x16x32_bf16 v[122:125], v[168:171], v[192:195], v[122:125]
	v_mfma_f32_16x16x32_bf16 v[122:125], v[172:175], v[196:199], v[122:125]
	v_mfma_f32_16x16x32_bf16 v[106:109], v[168:171], v[200:203], v[106:109]
	v_mfma_f32_16x16x32_bf16 v[106:109], v[172:175], v[204:207], v[106:109]
	v_mfma_f32_16x16x32_bf16 v[114:117], v[158:161], v[200:203], v[114:117]
	v_mfma_f32_16x16x32_bf16 v[114:117], v[164:167], v[204:207], v[114:117]
	v_mfma_f32_16x16x32_bf16 v[98:101], v[158:161], v[208:211], v[98:101]
	v_mfma_f32_16x16x32_bf16 v[98:101], v[164:167], v[212:215], v[98:101]
	v_mfma_f32_16x16x32_bf16 v[90:93], v[168:171], v[208:211], v[90:93]
	v_mfma_f32_16x16x32_bf16 v[90:93], v[172:175], v[212:215], v[90:93]
	v_mfma_f32_16x16x32_bf16 v[74:77], v[168:171], v[216:219], v[74:77]
	v_mfma_f32_16x16x32_bf16 v[74:77], v[172:175], v[220:223], v[74:77]
	v_mfma_f32_16x16x32_bf16 v[82:85], v[158:161], v[216:219], v[82:85]
	v_mfma_f32_16x16x32_bf16 v[82:85], v[164:167], v[220:223], v[82:85]
	v_mfma_f32_16x16x32_bf16 v[118:121], v[176:179], v[192:195], v[118:121]
	v_mfma_f32_16x16x32_bf16 v[118:121], v[180:183], v[196:199], v[118:121]
	v_mfma_f32_16x16x32_bf16 v[110:113], v[184:187], v[192:195], v[110:113]
	v_mfma_f32_16x16x32_bf16 v[110:113], v[188:191], v[196:199], v[110:113]
	v_mfma_f32_16x16x32_bf16 v[94:97], v[184:187], v[200:203], v[94:97]
	v_mfma_f32_16x16x32_bf16 v[94:97], v[188:191], v[204:207], v[94:97]
	v_mfma_f32_16x16x32_bf16 v[102:105], v[176:179], v[200:203], v[102:105]
	v_mfma_f32_16x16x32_bf16 v[102:105], v[180:183], v[204:207], v[102:105]
	v_mfma_f32_16x16x32_bf16 v[86:89], v[176:179], v[208:211], v[86:89]
	v_mfma_f32_16x16x32_bf16 v[86:89], v[180:183], v[212:215], v[86:89]
	v_mfma_f32_16x16x32_bf16 v[78:81], v[184:187], v[208:211], v[78:81]
	v_mfma_f32_16x16x32_bf16 v[78:81], v[188:191], v[212:215], v[78:81]
	v_mfma_f32_16x16x32_bf16 v[66:69], v[184:187], v[216:219], v[66:69]
	v_mfma_f32_16x16x32_bf16 v[66:69], v[188:191], v[220:223], v[66:69]
	v_mfma_f32_16x16x32_bf16 v[70:73], v[176:179], v[216:219], v[70:73]
	v_mfma_f32_16x16x32_bf16 v[70:73], v[180:183], v[220:223], v[70:73]
	s_setprio 0
	s_barrier
	s_add_i32 s56, s42, s30
	v_lshl_add_u64 v[146:147], s[26:27], 0, v[134:135]
	s_mov_b32 m0, s56
	ds_read_b128 v[192:195], v157 offset:16384
	ds_read_b128 v[196:199], v157 offset:17408
	ds_read_b128 v[200:203], v157 offset:18432
	ds_read_b128 v[204:207], v157 offset:19456
	ds_read_b128 v[208:211], v157 offset:20480
	ds_read_b128 v[212:215], v157 offset:21504
	ds_read_b128 v[216:219], v157 offset:22528
	ds_read_b128 v[220:223], v157 offset:23552
	global_load_lds_dwordx4 v[146:147], off
	s_add_i32 m0, s56, 0x2000
	s_add_u32 s56, s26, 0x100000
	v_lshl_add_u64 v[224:225], s[26:27], 0, v[130:131]
	s_addc_u32 s57, s27, 0
	s_add_i32 s58, s43, s30
	global_load_lds_dwordx4 v[224:225], off
	v_lshl_add_u64 v[226:227], s[56:57], 0, v[134:135]
	s_mov_b32 m0, s58
	v_lshl_add_u64 v[228:229], s[28:29], 0, v[132:133]
	global_load_lds_dwordx4 v[226:227], off
	v_lshl_add_u64 v[226:227], s[56:57], 0, v[130:131]
	s_add_i32 m0, s58, 0x2000
	s_nop 0
	global_load_lds_dwordx4 v[226:227], off
	v_lshl_add_u64 v[226:227], s[28:29], 0, v[136:137]
	s_mov_b32 m0, s23
	s_nop 0
	global_load_lds_dwordx4 v[226:227], off
	s_mov_b32 m0, s33
	s_nop 0
	global_load_lds_dwordx4 v[228:229], off
	s_waitcnt vmcnt(8)
	s_waitcnt lgkmcnt(0)
	s_barrier
; #define PG8_STAGE(bufoff, gbase, voff) do { _Pragma("unroll") for (int _i = 0; _i < 2; ++_i) \
;         __builtin_amdgcn_global_load_lds((const unsigned*)((const char*)(gbase) + (voff)[_i]), (PG8_LAS unsigned*)(lds + (bufoff) + ldsw + _i * 8192), 16, 0, 0); } while (0)
; #define PG8_LDA(dst, b, h) do { _Pragma("unroll") for (int m = 0; m < 4; ++m) _Pragma("unroll") for (int k = 0; k < 2; ++k) dst[m][k] = *(const PG8_LAS bf16x8*)(lds + PG8_SA(b, h) + aoff + m * 2048 + k * 1024); } while (0)
; #define PG8_LDB(dst, b, h) do { _Pragma("unroll") for (int n = 0; n < 2; ++n) _Pragma("unroll") for (int k = 0; k < 2; ++k) dst[n][k] = *(const PG8_LAS bf16x8*)(lds + PG8_SB(b, h) + boff + n * 2048 + k * 1024); } while (0)
; #define PG8_MMA(ai, bj, At, Bt) do { __builtin_amdgcn_s_setprio(3); _Pragma("unroll") for (int m = 0; m < 4; ++m) _Pragma("unroll") for (int n = 0; n < 2; ++n) _Pragma("unroll") for (int k = 0; k < 2; ++k) \
;         acc[ai][bj][m][n] = __builtin_amdgcn_mfma_f32_16x16x32_bf16(Bt[n][k], At[m][k], acc[ai][bj][m][n], 0, 0, 0); __builtin_amdgcn_s_setprio(0); } while (0)
; #define PG8_WAIT_V(n) asm volatile("s_waitcnt vmcnt(" #n ")" ::: "memory")
; #define PG8_WAIT_L(n) asm volatile("s_waitcnt lgkmcnt(" #n ")" ::: "memory")
; #define PG8_BAR __builtin_amdgcn_s_barrier()
; #define PG8_SCHED __builtin_amdgcn_sched_barrier(0)
; template <class Epi, class Sched, bool ALIGN_EPI = false, bool SP2 = false>
; __device__ __forceinline__ void gemm_phase(PG8_LAS unsigned char* lds, const Gemm g, const Sched& S, const Epi& E) {
;     ...
;             PG8_WAIT_V(8); PG8_WAIT_L(0); PG8_BAR; PG8_MMA(1, 0, At, B0); PG8_MMA(1, 1, At, B1); PG8_BAR; PG8_SCHED;
;             PG8_LDB(B0, 1, 0); PG8_LDB(B1, 1, 1); PG8_SCHED; PG8_LDA(At, 1, 0); PG8_STAGE(PG8_SA(0, 1), a2 + hstepA, voffA);
;             PG8_WAIT_V(8); PG8_WAIT_L(0); PG8_BAR; PG8_MMA(0, 0, At, B0); PG8_MMA(0, 1, At, B1); PG8_BAR; PG8_SCHED;
	s_setprio 3
	v_mfma_f32_16x16x32_bf16 v[62:65], v[158:161], v[192:195], v[62:65]
	v_mfma_f32_16x16x32_bf16 v[62:65], v[164:167], v[196:199], v[62:65]
	v_mfma_f32_16x16x32_bf16 v[58:61], v[168:171], v[192:195], v[58:61]
	v_mfma_f32_16x16x32_bf16 v[58:61], v[172:175], v[196:199], v[58:61]
	v_mfma_f32_16x16x32_bf16 v[42:45], v[168:171], v[200:203], v[42:45]
	v_mfma_f32_16x16x32_bf16 v[42:45], v[172:175], v[204:207], v[42:45]
	v_mfma_f32_16x16x32_bf16 v[50:53], v[158:161], v[200:203], v[50:53]
	v_mfma_f32_16x16x32_bf16 v[50:53], v[164:167], v[204:207], v[50:53]
	v_mfma_f32_16x16x32_bf16 v[34:37], v[158:161], v[208:211], v[34:37]
	v_mfma_f32_16x16x32_bf16 v[34:37], v[164:167], v[212:215], v[34:37]
	v_mfma_f32_16x16x32_bf16 v[26:29], v[168:171], v[208:211], v[26:29]
	v_mfma_f32_16x16x32_bf16 v[26:29], v[172:175], v[212:215], v[26:29]
	v_mfma_f32_16x16x32_bf16 v[10:13], v[168:171], v[216:219], v[10:13]
	v_mfma_f32_16x16x32_bf16 v[10:13], v[172:175], v[220:223], v[10:13]
	v_mfma_f32_16x16x32_bf16 v[14:17], v[158:161], v[216:219], v[14:17]
	v_mfma_f32_16x16x32_bf16 v[14:17], v[164:167], v[220:223], v[14:17]
	v_mfma_f32_16x16x32_bf16 v[54:57], v[176:179], v[192:195], v[54:57]
	v_mfma_f32_16x16x32_bf16 v[54:57], v[180:183], v[196:199], v[54:57]
	v_mfma_f32_16x16x32_bf16 v[46:49], v[184:187], v[192:195], v[46:49]
	v_mfma_f32_16x16x32_bf16 v[46:49], v[188:191], v[196:199], v[46:49]
	v_mfma_f32_16x16x32_bf16 v[30:33], v[184:187], v[200:203], v[30:33]
	v_mfma_f32_16x16x32_bf16 v[30:33], v[188:191], v[204:207], v[30:33]
	v_mfma_f32_16x16x32_bf16 v[38:41], v[176:179], v[200:203], v[38:41]
	v_mfma_f32_16x16x32_bf16 v[38:41], v[180:183], v[204:207], v[38:41]
	v_mfma_f32_16x16x32_bf16 v[22:25], v[176:179], v[208:211], v[22:25]
	v_mfma_f32_16x16x32_bf16 v[22:25], v[180:183], v[212:215], v[22:25]
	v_mfma_f32_16x16x32_bf16 v[18:21], v[184:187], v[208:211], v[18:21]
	v_mfma_f32_16x16x32_bf16 v[18:21], v[188:191], v[212:215], v[18:21]
	v_mfma_f32_16x16x32_bf16 v[2:5], v[184:187], v[216:219], v[2:5]
	v_mfma_f32_16x16x32_bf16 v[2:5], v[188:191], v[220:223], v[2:5]
	v_mfma_f32_16x16x32_bf16 v[6:9], v[176:179], v[216:219], v[6:9]
	v_mfma_f32_16x16x32_bf16 v[6:9], v[180:183], v[220:223], v[6:9]
	s_setprio 0
	s_barrier
	s_add_i32 s56, 0, 0x18000
	v_add_u32_e32 v148, s56, v151
	s_add_i32 s57, 0, 0x1c000
	ds_read_b128 v[158:161], v148
	ds_read_b128 v[164:167], v148 offset:1024
	ds_read_b128 v[168:171], v148 offset:2048
	ds_read_b128 v[172:175], v148 offset:3072
	v_add_u32_e32 v148, s57, v151
	ds_read_b128 v[176:179], v148
	ds_read_b128 v[180:183], v148 offset:1024
	ds_read_b128 v[184:187], v148 offset:2048
	ds_read_b128 v[188:191], v148 offset:3072
	s_add_u32 s28, s28, 0x100000
	s_addc_u32 s29, s29, 0
	s_mov_b32 m0, s36
	v_lshl_add_u64 v[230:231], s[28:29], 0, v[136:137]
	ds_read_b128 v[192:195], v157 offset:32768
	ds_read_b128 v[196:199], v157 offset:33792
	ds_read_b128 v[200:203], v157 offset:34816
	ds_read_b128 v[204:207], v157 offset:35840
	ds_read_b128 v[208:211], v157 offset:36864
	ds_read_b128 v[212:215], v157 offset:37888
	ds_read_b128 v[216:219], v157 offset:38912
	ds_read_b128 v[220:223], v157 offset:39936
	global_load_lds_dwordx4 v[230:231], off
	v_lshl_add_u64 v[230:231], s[28:29], 0, v[132:133]
	s_mov_b32 m0, s37
	s_nop 0
	global_load_lds_dwordx4 v[230:231], off
	s_waitcnt vmcnt(8)
	s_waitcnt lgkmcnt(0)
	s_barrier
	s_setprio 3
	v_mfma_f32_16x16x32_bf16 v[126:129], v[158:161], v[192:195], v[126:129]
	v_mfma_f32_16x16x32_bf16 v[126:129], v[164:167], v[196:199], v[126:129]
	v_mfma_f32_16x16x32_bf16 v[122:125], v[168:171], v[192:195], v[122:125]
	v_mfma_f32_16x16x32_bf16 v[122:125], v[172:175], v[196:199], v[122:125]
	v_mfma_f32_16x16x32_bf16 v[106:109], v[168:171], v[200:203], v[106:109]
	v_mfma_f32_16x16x32_bf16 v[106:109], v[172:175], v[204:207], v[106:109]
	v_mfma_f32_16x16x32_bf16 v[114:117], v[158:161], v[200:203], v[114:117]
	v_mfma_f32_16x16x32_bf16 v[114:117], v[164:167], v[204:207], v[114:117]
	v_mfma_f32_16x16x32_bf16 v[98:101], v[158:161], v[208:211], v[98:101]
	v_mfma_f32_16x16x32_bf16 v[98:101], v[164:167], v[212:215], v[98:101]
	v_mfma_f32_16x16x32_bf16 v[90:93], v[168:171], v[208:211], v[90:93]
	v_mfma_f32_16x16x32_bf16 v[90:93], v[172:175], v[212:215], v[90:93]
	v_mfma_f32_16x16x32_bf16 v[74:77], v[168:171], v[216:219], v[74:77]
	v_mfma_f32_16x16x32_bf16 v[74:77], v[172:175], v[220:223], v[74:77]
	v_mfma_f32_16x16x32_bf16 v[82:85], v[158:161], v[216:219], v[82:85]
	v_mfma_f32_16x16x32_bf16 v[82:85], v[164:167], v[220:223], v[82:85]
	v_mfma_f32_16x16x32_bf16 v[118:121], v[176:179], v[192:195], v[118:121]
	v_mfma_f32_16x16x32_bf16 v[118:121], v[180:183], v[196:199], v[118:121]
	v_mfma_f32_16x16x32_bf16 v[110:113], v[184:187], v[192:195], v[110:113]
	v_mfma_f32_16x16x32_bf16 v[110:113], v[188:191], v[196:199], v[110:113]
	v_mfma_f32_16x16x32_bf16 v[94:97], v[184:187], v[200:203], v[94:97]
	v_mfma_f32_16x16x32_bf16 v[94:97], v[188:191], v[204:207], v[94:97]
	v_mfma_f32_16x16x32_bf16 v[102:105], v[176:179], v[200:203], v[102:105]
	v_mfma_f32_16x16x32_bf16 v[102:105], v[180:183], v[204:207], v[102:105]
	v_mfma_f32_16x16x32_bf16 v[86:89], v[176:179], v[208:211], v[86:89]
	v_mfma_f32_16x16x32_bf16 v[86:89], v[180:183], v[212:215], v[86:89]
	v_mfma_f32_16x16x32_bf16 v[78:81], v[184:187], v[208:211], v[78:81]
	v_mfma_f32_16x16x32_bf16 v[78:81], v[188:191], v[212:215], v[78:81]
	v_mfma_f32_16x16x32_bf16 v[66:69], v[184:187], v[216:219], v[66:69]
	v_mfma_f32_16x16x32_bf16 v[66:69], v[188:191], v[220:223], v[66:69]
	v_mfma_f32_16x16x32_bf16 v[70:73], v[176:179], v[216:219], v[70:73]
	v_mfma_f32_16x16x32_bf16 v[70:73], v[180:183], v[220:223], v[70:73]
	s_setprio 0
	s_barrier
; #define PG8_STAGE(bufoff, gbase, voff) do { _Pragma("unroll") for (int _i = 0; _i < 2; ++_i) \
;         __builtin_amdgcn_global_load_lds((const unsigned*)((const char*)(gbase) + (voff)[_i]), (PG8_LAS unsigned*)(lds + (bufoff) + ldsw + _i * 8192), 16, 0, 0); } while (0)
; #define PG8_LDA(dst, b, h) do { _Pragma("unroll") for (int m = 0; m < 4; ++m) _Pragma("unroll") for (int k = 0; k < 2; ++k) dst[m][k] = *(const PG8_LAS bf16x8*)(lds + PG8_SA(b, h) + aoff + m * 2048 + k * 1024); } while (0)
; #define PG8_MMA(ai, bj, At, Bt) do { __builtin_amdgcn_s_setprio(3); _Pragma("unroll") for (int m = 0; m < 4; ++m) _Pragma("unroll") for (int n = 0; n < 2; ++n) _Pragma("unroll") for (int k = 0; k < 2; ++k) \
;         acc[ai][bj][m][n] = __builtin_amdgcn_mfma_f32_16x16x32_bf16(Bt[n][k], At[m][k], acc[ai][bj][m][n], 0, 0, 0); __builtin_amdgcn_s_setprio(0); } while (0)
; #define PG8_WAIT_V(n) asm volatile("s_waitcnt vmcnt(" #n ")" ::: "memory")
; #define PG8_WAIT_L(n) asm volatile("s_waitcnt lgkmcnt(" #n ")" ::: "memory")
; #define PG8_BAR __builtin_amdgcn_s_barrier()
; #define PG8_SCHED __builtin_amdgcn_sched_barrier(0)
; template <class Epi, class Sched, bool ALIGN_EPI = false, bool SP2 = false>
; __device__ __forceinline__ void gemm_phase(PG8_LAS unsigned char* lds, const Gemm g, const Sched& S, const Epi& E) {
;     ...
;             PG8_LDA(At, 1, 1); PG8_STAGE(PG8_SB(1, 0), b3, voffB); PG8_STAGE(PG8_SB(1, 1), b3 + hstepB, voffB); PG8_STAGE(PG8_SA(1, 0), a3, voffA);
;             PG8_WAIT_V(8); PG8_WAIT_L(0); PG8_BAR; PG8_MMA(1, 0, At, B0); PG8_MMA(1, 1, At, B1); PG8_BAR; PG8_SCHED;
;     ...
;         if constexpr (ALIGN_EPI) { if (wr == 0) PG8_BAR; }
;         if constexpr (!Epi::AFTER_DRAIN) { E(acc, cur, wr, wc, fr, fq); S.done(cur); }
;         if (!has_next) break;
	s_add_i32 s28, s56, s30
	v_lshl_add_u64 v[146:147], v[146:147], 0, s[12:13]
	s_mov_b32 m0, s28
	ds_read_b128 v[192:195], v157 offset:49152
	ds_read_b128 v[196:199], v157 offset:50176
	ds_read_b128 v[200:203], v157 offset:51200
	ds_read_b128 v[204:207], v157 offset:52224
	ds_read_b128 v[208:211], v157 offset:53248
	ds_read_b128 v[212:215], v157 offset:54272
	ds_read_b128 v[216:219], v157 offset:55296
	ds_read_b128 v[220:223], v157 offset:56320
	global_load_lds_dwordx4 v[146:147], off
	s_add_i32 m0, s28, 0x2000
	s_add_u32 s26, s26, 0x100080
	v_lshl_add_u64 v[146:147], v[224:225], 0, s[12:13]
	s_addc_u32 s27, s27, 0
	s_add_i32 s28, s57, s30
	global_load_lds_dwordx4 v[146:147], off
	v_lshl_add_u64 v[146:147], s[26:27], 0, v[134:135]
	s_mov_b32 m0, s28
	s_nop 0
	global_load_lds_dwordx4 v[146:147], off
	v_lshl_add_u64 v[146:147], s[26:27], 0, v[130:131]
	s_add_i32 m0, s28, 0x2000
	s_nop 0
	global_load_lds_dwordx4 v[146:147], off
	v_lshl_add_u64 v[146:147], v[226:227], 0, s[12:13]
	s_mov_b32 m0, s39
	s_nop 0
	global_load_lds_dwordx4 v[146:147], off
	v_lshl_add_u64 v[146:147], v[228:229], 0, s[12:13]
	s_mov_b32 m0, s40
	s_nop 0
	global_load_lds_dwordx4 v[146:147], off
	s_waitcnt vmcnt(8)
	s_waitcnt lgkmcnt(0)
	s_barrier
	s_setprio 3
	v_mfma_f32_16x16x32_bf16 v[62:65], v[158:161], v[192:195], v[62:65]
	v_mfma_f32_16x16x32_bf16 v[62:65], v[164:167], v[196:199], v[62:65]
	v_mfma_f32_16x16x32_bf16 v[58:61], v[168:171], v[192:195], v[58:61]
	v_mfma_f32_16x16x32_bf16 v[58:61], v[172:175], v[196:199], v[58:61]
	v_mfma_f32_16x16x32_bf16 v[42:45], v[168:171], v[200:203], v[42:45]
	v_mfma_f32_16x16x32_bf16 v[42:45], v[172:175], v[204:207], v[42:45]
	v_mfma_f32_16x16x32_bf16 v[50:53], v[158:161], v[200:203], v[50:53]
	v_mfma_f32_16x16x32_bf16 v[50:53], v[164:167], v[204:207], v[50:53]
	v_mfma_f32_16x16x32_bf16 v[34:37], v[158:161], v[208:211], v[34:37]
	v_mfma_f32_16x16x32_bf16 v[34:37], v[164:167], v[212:215], v[34:37]
	v_mfma_f32_16x16x32_bf16 v[26:29], v[168:171], v[208:211], v[26:29]
	v_mfma_f32_16x16x32_bf16 v[26:29], v[172:175], v[212:215], v[26:29]
	v_mfma_f32_16x16x32_bf16 v[10:13], v[168:171], v[216:219], v[10:13]
	v_mfma_f32_16x16x32_bf16 v[10:13], v[172:175], v[220:223], v[10:13]
	v_mfma_f32_16x16x32_bf16 v[14:17], v[158:161], v[216:219], v[14:17]
	v_mfma_f32_16x16x32_bf16 v[14:17], v[164:167], v[220:223], v[14:17]
	v_mfma_f32_16x16x32_bf16 v[54:57], v[176:179], v[192:195], v[54:57]
	v_mfma_f32_16x16x32_bf16 v[54:57], v[180:183], v[196:199], v[54:57]
	v_mfma_f32_16x16x32_bf16 v[46:49], v[184:187], v[192:195], v[46:49]
	v_mfma_f32_16x16x32_bf16 v[46:49], v[188:191], v[196:199], v[46:49]
	v_mfma_f32_16x16x32_bf16 v[30:33], v[184:187], v[200:203], v[30:33]
	v_mfma_f32_16x16x32_bf16 v[30:33], v[188:191], v[204:207], v[30:33]
	v_mfma_f32_16x16x32_bf16 v[38:41], v[176:179], v[200:203], v[38:41]
	v_mfma_f32_16x16x32_bf16 v[38:41], v[180:183], v[204:207], v[38:41]
	v_mfma_f32_16x16x32_bf16 v[22:25], v[176:179], v[208:211], v[22:25]
	v_mfma_f32_16x16x32_bf16 v[22:25], v[180:183], v[212:215], v[22:25]
	v_mfma_f32_16x16x32_bf16 v[18:21], v[184:187], v[208:211], v[18:21]
	v_mfma_f32_16x16x32_bf16 v[18:21], v[188:191], v[212:215], v[18:21]
	v_mfma_f32_16x16x32_bf16 v[2:5], v[184:187], v[216:219], v[2:5]
	v_mfma_f32_16x16x32_bf16 v[2:5], v[188:191], v[220:223], v[2:5]
	v_mfma_f32_16x16x32_bf16 v[6:9], v[176:179], v[216:219], v[6:9]
	v_mfma_f32_16x16x32_bf16 v[6:9], v[180:183], v[220:223], v[6:9]
	s_setprio 0
	s_barrier
	s_add_i32 s55, s55, 2
	s_add_u32 s24, s24, 0x100
	s_addc_u32 s25, s25, 0
	s_add_u32 s53, s53, 0x100
	s_addc_u32 s54, s54, 0
	s_cmp_gt_u32 s55, 61
	s_cbranch_scc0 .LBB0_908
	s_and_b64 vcc, exec, s[0:1]
	s_cbranch_vccz .LBB0_911
	s_barrier

; #define PG8_STAGE(bufoff, gbase, voff) do { _Pragma("unroll") for (int _i = 0; _i < 2; ++_i) \
;         __builtin_amdgcn_global_load_lds((const unsigned*)((const char*)(gbase) + (voff)[_i]), (PG8_LAS unsigned*)(lds + (bufoff) + ldsw + _i * 8192), 16, 0, 0); } while (0)
; #define PG8_LDA(dst, b, h) do { _Pragma("unroll") for (int m = 0; m < 4; ++m) _Pragma("unroll") for (int k = 0; k < 2; ++k) dst[m][k] = *(const PG8_LAS bf16x8*)(lds + PG8_SA(b, h) + aoff + m * 2048 + k * 1024); } while (0)
; #define PG8_LDB(dst, b, h) do { _Pragma("unroll") for (int n = 0; n < 2; ++n) _Pragma("unroll") for (int k = 0; k < 2; ++k) dst[n][k] = *(const PG8_LAS bf16x8*)(lds + PG8_SB(b, h) + boff + n * 2048 + k * 1024); } while (0)
; #define PG8_MMA(ai, bj, At, Bt) do { __builtin_amdgcn_s_setprio(3); _Pragma("unroll") for (int m = 0; m < 4; ++m) _Pragma("unroll") for (int n = 0; n < 2; ++n) _Pragma("unroll") for (int k = 0; k < 2; ++k) \
;         acc[ai][bj][m][n] = __builtin_amdgcn_mfma_f32_16x16x32_bf16(Bt[n][k], At[m][k], acc[ai][bj][m][n], 0, 0, 0); __builtin_amdgcn_s_setprio(0); } while (0)
; #define PG8_BAR __builtin_amdgcn_s_barrier()
; template <class Epi, class Sched, bool ALIGN_EPI = false, bool SP2 = false>
; __device__ __forceinline__ void gemm_phase(PG8_LAS unsigned char* lds, const Gemm g, const Sched& S, const Epi& E) {
;     ...
;         for (int t = 0; t < nt; t += 2) {
;             const bool last = (t == nt - 2);
;             const char* a1 = cA + (size_t)(t + 1) * kstep;
;             const char* a2 = last ? nA : cA + (size_t)(t + 2) * kstep; const char* b2 = last ? nB : cB + (size_t)(t + 2) * kstep;
;             const char* a3 = a2 + kstep; const char* b3 = b2 + kstep;
;             if (last && has_next) S.a_ready(nxt);
;             if constexpr (Epi::MIDK) { if (t == E.midk_step(nt)) E.midk(acc, cur, wr, wc, fr, fq); }
;             if constexpr (SP2) {
;             PG8_LDB(B0, 0, 0); PG8_LDB(B1, 0, 1); PG8_SCHED; PG8_LDA(At, 0, 0); PG8_STAGE(PG8_SA(1, 1), a1 + hstepA, voffA);
;             PG8_WAIT_V(8); PG8_WAIT_L(0); PG8_BAR; PG8_MMA(0, 0, At, B0); PG8_MMA(0, 1, At, B1); PG8_BAR; PG8_SCHED;
;             PG8_LDA(At, 0, 1); PG8_STAGE(PG8_SB(0, 0), b2, voffB); PG8_STAGE(PG8_SB(0, 1), b2 + hstepB, voffB); PG8_STAGE(PG8_SA(0, 0), a2, voffA);
;             PG8_WAIT_V(8); PG8_WAIT_L(0); PG8_BAR; PG8_MMA(1, 0, At, B0); PG8_MMA(1, 1, At, B1); PG8_BAR; PG8_SCHED;
.LBB0_975:
	v_add_u32_e32 v144, s46, v206
	v_add_u32_e32 v160, s47, v206
	s_add_u32 s28, s2, s12
	ds_read_b128 v[132:135], v144
	ds_read_b128 v[136:139], v144 offset:1024
	ds_read_b128 v[140:143], v144 offset:2048
	ds_read_b128 v[144:147], v144 offset:3072
	ds_read_b128 v[148:151], v160
	ds_read_b128 v[152:155], v160 offset:1024
	ds_read_b128 v[156:159], v160 offset:2048
	ds_read_b128 v[160:163], v160 offset:3072
	s_addc_u32 s29, s3, s13
	s_add_u32 s28, s28, 0x21500100
	s_addc_u32 s29, s29, 0
	s_add_u32 s81, s44, s12
	s_addc_u32 s82, s45, s13
	s_cmpk_eq_i32 s12, 0x5500
	s_cselect_b32 s31, s1, s29
	s_cselect_b32 s30, s0, s28
	s_cselect_b32 s29, s11, s82
	s_cselect_b32 s28, s10, s81
	s_mov_b32 m0, s71
	v_lshl_add_u64 v[234:235], v[2:3], 0, s[12:13]
	ds_read_b128 v[164:167], v207
	ds_read_b128 v[168:171], v207 offset:1024
	ds_read_b128 v[210:213], v207 offset:2048
	ds_read_b128 v[214:217], v207 offset:3072
	ds_read_b128 v[218:221], v207 offset:4096
	ds_read_b128 v[222:225], v207 offset:5120
	ds_read_b128 v[226:229], v207 offset:6144
	ds_read_b128 v[230:233], v207 offset:7168
	global_load_lds_dwordx4 v[234:235], off
	v_lshl_add_u64 v[234:235], v[200:201], 0, s[12:13]
	s_mov_b32 m0, s72
	s_nop 0
	global_load_lds_dwordx4 v[234:235], off
	s_waitcnt vmcnt(8)
	s_waitcnt lgkmcnt(0)
	s_barrier
	s_setprio 3
	v_mfma_f32_16x16x32_bf16 v[128:131], v[132:135], v[164:167], v[128:131]
	v_mfma_f32_16x16x32_bf16 v[128:131], v[136:139], v[168:171], v[128:131]
	v_mfma_f32_16x16x32_bf16 v[124:127], v[140:143], v[164:167], v[124:127]
	v_mfma_f32_16x16x32_bf16 v[124:127], v[144:147], v[168:171], v[124:127]
	v_mfma_f32_16x16x32_bf16 v[96:99], v[140:143], v[210:213], v[96:99]
	v_mfma_f32_16x16x32_bf16 v[96:99], v[144:147], v[214:217], v[96:99]
	v_mfma_f32_16x16x32_bf16 v[100:103], v[132:135], v[210:213], v[100:103]
	v_mfma_f32_16x16x32_bf16 v[100:103], v[136:139], v[214:217], v[100:103]
	v_mfma_f32_16x16x32_bf16 v[112:115], v[132:135], v[218:221], v[112:115]
	v_mfma_f32_16x16x32_bf16 v[112:115], v[136:139], v[222:225], v[112:115]
	v_mfma_f32_16x16x32_bf16 v[108:111], v[140:143], v[218:221], v[108:111]
	v_mfma_f32_16x16x32_bf16 v[108:111], v[144:147], v[222:225], v[108:111]
	v_mfma_f32_16x16x32_bf16 v[76:79], v[140:143], v[226:229], v[76:79]
	v_mfma_f32_16x16x32_bf16 v[76:79], v[144:147], v[230:233], v[76:79]
	v_mfma_f32_16x16x32_bf16 v[80:83], v[132:135], v[226:229], v[80:83]
	v_mfma_f32_16x16x32_bf16 v[80:83], v[136:139], v[230:233], v[80:83]
	v_mfma_f32_16x16x32_bf16 v[120:123], v[148:151], v[164:167], v[120:123]
	v_mfma_f32_16x16x32_bf16 v[120:123], v[152:155], v[168:171], v[120:123]
	v_mfma_f32_16x16x32_bf16 v[116:119], v[156:159], v[164:167], v[116:119]
	v_mfma_f32_16x16x32_bf16 v[116:119], v[160:163], v[168:171], v[116:119]
	v_mfma_f32_16x16x32_bf16 v[88:91], v[156:159], v[210:213], v[88:91]
	v_mfma_f32_16x16x32_bf16 v[88:91], v[160:163], v[214:217], v[88:91]
	v_mfma_f32_16x16x32_bf16 v[92:95], v[148:151], v[210:213], v[92:95]
	v_mfma_f32_16x16x32_bf16 v[92:95], v[152:155], v[214:217], v[92:95]
	v_mfma_f32_16x16x32_bf16 v[104:107], v[148:151], v[218:221], v[104:107]
	v_mfma_f32_16x16x32_bf16 v[104:107], v[152:155], v[222:225], v[104:107]
	v_mfma_f32_16x16x32_bf16 v[84:87], v[156:159], v[218:221], v[84:87]
	v_mfma_f32_16x16x32_bf16 v[84:87], v[160:163], v[222:225], v[84:87]
	v_mfma_f32_16x16x32_bf16 v[68:71], v[156:159], v[226:229], v[68:71]
	v_mfma_f32_16x16x32_bf16 v[68:71], v[160:163], v[230:233], v[68:71]
	v_mfma_f32_16x16x32_bf16 v[72:75], v[148:151], v[226:229], v[72:75]
	v_mfma_f32_16x16x32_bf16 v[72:75], v[152:155], v[230:233], v[72:75]
	s_setprio 0
	s_barrier
	s_mov_b32 m0, s73
	v_lshl_add_u64 v[234:235], s[28:29], 0, v[174:175]
	s_add_u32 s82, s28, 0x2b0000
	ds_read_b128 v[164:167], v207 offset:16384
	ds_read_b128 v[168:171], v207 offset:17408
	ds_read_b128 v[210:213], v207 offset:18432
	ds_read_b128 v[214:217], v207 offset:19456
	ds_read_b128 v[218:221], v207 offset:20480
	ds_read_b128 v[222:225], v207 offset:21504
	ds_read_b128 v[226:229], v207 offset:22528
	ds_read_b128 v[230:233], v207 offset:23552
	global_load_lds_dwordx4 v[234:235], off
	v_lshl_add_u64 v[236:237], s[28:29], 0, v[178:179]
	s_mov_b32 m0, s74
	s_addc_u32 s83, s29, 0
	global_load_lds_dwordx4 v[236:237], off
	v_lshl_add_u64 v[238:239], s[82:83], 0, v[174:175]
	s_mov_b32 m0, s75
	v_lshl_add_u64 v[240:241], s[30:31], 0, v[176:177]
	global_load_lds_dwordx4 v[238:239], off
	v_lshl_add_u64 v[238:239], s[82:83], 0, v[178:179]
	s_mov_b32 m0, s76
	s_nop 0
	global_load_lds_dwordx4 v[238:239], off
	v_lshl_add_u64 v[238:239], s[30:31], 0, v[172:173]
	s_mov_b32 m0, s42
	s_nop 0
	global_load_lds_dwordx4 v[238:239], off
	s_mov_b32 m0, s54
	s_nop 0
	global_load_lds_dwordx4 v[240:241], off
	s_waitcnt vmcnt(8)
	s_waitcnt lgkmcnt(0)
	s_barrier
; #define PG8_STAGE(bufoff, gbase, voff) do { _Pragma("unroll") for (int _i = 0; _i < 2; ++_i) \
;         __builtin_amdgcn_global_load_lds((const unsigned*)((const char*)(gbase) + (voff)[_i]), (PG8_LAS unsigned*)(lds + (bufoff) + ldsw + _i * 8192), 16, 0, 0); } while (0)
; #define PG8_LDA(dst, b, h) do { _Pragma("unroll") for (int m = 0; m < 4; ++m) _Pragma("unroll") for (int k = 0; k < 2; ++k) dst[m][k] = *(const PG8_LAS bf16x8*)(lds + PG8_SA(b, h) + aoff + m * 2048 + k * 1024); } while (0)
; #define PG8_LDB(dst, b, h) do { _Pragma("unroll") for (int n = 0; n < 2; ++n) _Pragma("unroll") for (int k = 0; k < 2; ++k) dst[n][k] = *(const PG8_LAS bf16x8*)(lds + PG8_SB(b, h) + boff + n * 2048 + k * 1024); } while (0)
; #define PG8_MMA(ai, bj, At, Bt) do { __builtin_amdgcn_s_setprio(3); _Pragma("unroll") for (int m = 0; m < 4; ++m) _Pragma("unroll") for (int n = 0; n < 2; ++n) _Pragma("unroll") for (int k = 0; k < 2; ++k) \
;         acc[ai][bj][m][n] = __builtin_amdgcn_mfma_f32_16x16x32_bf16(Bt[n][k], At[m][k], acc[ai][bj][m][n], 0, 0, 0); __builtin_amdgcn_s_setprio(0); } while (0)
; #define PG8_WAIT_V(n) asm volatile("s_waitcnt vmcnt(" #n ")" ::: "memory")
; #define PG8_WAIT_L(n) asm volatile("s_waitcnt lgkmcnt(" #n ")" ::: "memory")
; #define PG8_BAR __builtin_amdgcn_s_barrier()
; #define PG8_SCHED __builtin_amdgcn_sched_barrier(0)
; template <class Epi, class Sched, bool ALIGN_EPI = false, bool SP2 = false>
; __device__ __forceinline__ void gemm_phase(PG8_LAS unsigned char* lds, const Gemm g, const Sched& S, const Epi& E) {
;     ...
;             PG8_WAIT_V(8); PG8_WAIT_L(0); PG8_BAR; PG8_MMA(1, 0, At, B0); PG8_MMA(1, 1, At, B1); PG8_BAR; PG8_SCHED;
;             PG8_LDB(B0, 1, 0); PG8_LDB(B1, 1, 1); PG8_SCHED; PG8_LDA(At, 1, 0); PG8_STAGE(PG8_SA(0, 1), a2 + hstepA, voffA);
;             PG8_WAIT_V(8); PG8_WAIT_L(0); PG8_BAR; PG8_MMA(0, 0, At, B0); PG8_MMA(0, 1, At, B1); PG8_BAR; PG8_SCHED;
	s_setprio 3
	v_mfma_f32_16x16x32_bf16 v[64:67], v[132:135], v[164:167], v[64:67]
	v_mfma_f32_16x16x32_bf16 v[64:67], v[136:139], v[168:171], v[64:67]
	v_mfma_f32_16x16x32_bf16 v[60:63], v[140:143], v[164:167], v[60:63]
	v_mfma_f32_16x16x32_bf16 v[60:63], v[144:147], v[168:171], v[60:63]
	v_mfma_f32_16x16x32_bf16 v[44:47], v[140:143], v[210:213], v[44:47]
	v_mfma_f32_16x16x32_bf16 v[44:47], v[144:147], v[214:217], v[44:47]
	v_mfma_f32_16x16x32_bf16 v[48:51], v[132:135], v[210:213], v[48:51]
	v_mfma_f32_16x16x32_bf16 v[48:51], v[136:139], v[214:217], v[48:51]
	v_mfma_f32_16x16x32_bf16 v[32:35], v[132:135], v[218:221], v[32:35]
	v_mfma_f32_16x16x32_bf16 v[32:35], v[136:139], v[222:225], v[32:35]
	v_mfma_f32_16x16x32_bf16 v[28:31], v[140:143], v[218:221], v[28:31]
	v_mfma_f32_16x16x32_bf16 v[28:31], v[144:147], v[222:225], v[28:31]
	v_mfma_f32_16x16x32_bf16 v[12:15], v[140:143], v[226:229], v[12:15]
	v_mfma_f32_16x16x32_bf16 v[12:15], v[144:147], v[230:233], v[12:15]
	v_mfma_f32_16x16x32_bf16 v[16:19], v[132:135], v[226:229], v[16:19]
	v_mfma_f32_16x16x32_bf16 v[16:19], v[136:139], v[230:233], v[16:19]
	v_mfma_f32_16x16x32_bf16 v[56:59], v[148:151], v[164:167], v[56:59]
	v_mfma_f32_16x16x32_bf16 v[56:59], v[152:155], v[168:171], v[56:59]
	v_mfma_f32_16x16x32_bf16 v[52:55], v[156:159], v[164:167], v[52:55]
	v_mfma_f32_16x16x32_bf16 v[52:55], v[160:163], v[168:171], v[52:55]
	v_mfma_f32_16x16x32_bf16 v[36:39], v[156:159], v[210:213], v[36:39]
	v_mfma_f32_16x16x32_bf16 v[36:39], v[160:163], v[214:217], v[36:39]
	v_mfma_f32_16x16x32_bf16 v[40:43], v[148:151], v[210:213], v[40:43]
	v_mfma_f32_16x16x32_bf16 v[40:43], v[152:155], v[214:217], v[40:43]
	v_mfma_f32_16x16x32_bf16 v[24:27], v[148:151], v[218:221], v[24:27]
	v_mfma_f32_16x16x32_bf16 v[24:27], v[152:155], v[222:225], v[24:27]
	v_mfma_f32_16x16x32_bf16 v[20:23], v[156:159], v[218:221], v[20:23]
	v_mfma_f32_16x16x32_bf16 v[20:23], v[160:163], v[222:225], v[20:23]
	v_mfma_f32_16x16x32_bf16 v[4:7], v[156:159], v[226:229], v[4:7]
	v_mfma_f32_16x16x32_bf16 v[4:7], v[160:163], v[230:233], v[4:7]
	v_mfma_f32_16x16x32_bf16 v[8:11], v[148:151], v[226:229], v[8:11]
	v_mfma_f32_16x16x32_bf16 v[8:11], v[152:155], v[230:233], v[8:11]
	s_setprio 0
	s_barrier
	v_add_u32_e32 v144, s52, v206
	v_add_u32_e32 v160, s53, v206
	ds_read_b128 v[132:135], v144
	ds_read_b128 v[136:139], v144 offset:1024
	ds_read_b128 v[140:143], v144 offset:2048
	ds_read_b128 v[144:147], v144 offset:3072
	ds_read_b128 v[148:151], v160
	ds_read_b128 v[152:155], v160 offset:1024
	ds_read_b128 v[156:159], v160 offset:2048
	ds_read_b128 v[160:163], v160 offset:3072
	s_add_u32 s30, s30, 0x2b0000
	s_addc_u32 s31, s31, 0
	s_mov_b32 m0, s55
	v_lshl_add_u64 v[242:243], s[30:31], 0, v[172:173]
	ds_read_b128 v[164:167], v207 offset:32768
	ds_read_b128 v[168:171], v207 offset:33792
	ds_read_b128 v[210:213], v207 offset:34816
	ds_read_b128 v[214:217], v207 offset:35840
	ds_read_b128 v[218:221], v207 offset:36864
	ds_read_b128 v[222:225], v207 offset:37888
	ds_read_b128 v[226:229], v207 offset:38912
	ds_read_b128 v[230:233], v207 offset:39936
	global_load_lds_dwordx4 v[242:243], off
	v_lshl_add_u64 v[242:243], s[30:31], 0, v[176:177]
	s_mov_b32 m0, s56
	s_nop 0
	global_load_lds_dwordx4 v[242:243], off
	s_waitcnt vmcnt(8)
	s_waitcnt lgkmcnt(0)
	s_barrier
	s_setprio 3
	v_mfma_f32_16x16x32_bf16 v[128:131], v[132:135], v[164:167], v[128:131]
	v_mfma_f32_16x16x32_bf16 v[128:131], v[136:139], v[168:171], v[128:131]
	v_mfma_f32_16x16x32_bf16 v[124:127], v[140:143], v[164:167], v[124:127]
	v_mfma_f32_16x16x32_bf16 v[124:127], v[144:147], v[168:171], v[124:127]
	v_mfma_f32_16x16x32_bf16 v[96:99], v[140:143], v[210:213], v[96:99]
	v_mfma_f32_16x16x32_bf16 v[96:99], v[144:147], v[214:217], v[96:99]
	v_mfma_f32_16x16x32_bf16 v[100:103], v[132:135], v[210:213], v[100:103]
	v_mfma_f32_16x16x32_bf16 v[100:103], v[136:139], v[214:217], v[100:103]
	v_mfma_f32_16x16x32_bf16 v[112:115], v[132:135], v[218:221], v[112:115]
	v_mfma_f32_16x16x32_bf16 v[112:115], v[136:139], v[222:225], v[112:115]
	v_mfma_f32_16x16x32_bf16 v[108:111], v[140:143], v[218:221], v[108:111]
	v_mfma_f32_16x16x32_bf16 v[108:111], v[144:147], v[222:225], v[108:111]
	v_mfma_f32_16x16x32_bf16 v[76:79], v[140:143], v[226:229], v[76:79]
	v_mfma_f32_16x16x32_bf16 v[76:79], v[144:147], v[230:233], v[76:79]
	v_mfma_f32_16x16x32_bf16 v[80:83], v[132:135], v[226:229], v[80:83]
	v_mfma_f32_16x16x32_bf16 v[80:83], v[136:139], v[230:233], v[80:83]
	v_mfma_f32_16x16x32_bf16 v[120:123], v[148:151], v[164:167], v[120:123]
	v_mfma_f32_16x16x32_bf16 v[120:123], v[152:155], v[168:171], v[120:123]
	v_mfma_f32_16x16x32_bf16 v[116:119], v[156:159], v[164:167], v[116:119]
	v_mfma_f32_16x16x32_bf16 v[116:119], v[160:163], v[168:171], v[116:119]
	v_mfma_f32_16x16x32_bf16 v[88:91], v[156:159], v[210:213], v[88:91]
	v_mfma_f32_16x16x32_bf16 v[88:91], v[160:163], v[214:217], v[88:91]
	v_mfma_f32_16x16x32_bf16 v[92:95], v[148:151], v[210:213], v[92:95]
	v_mfma_f32_16x16x32_bf16 v[92:95], v[152:155], v[214:217], v[92:95]
	v_mfma_f32_16x16x32_bf16 v[104:107], v[148:151], v[218:221], v[104:107]
	v_mfma_f32_16x16x32_bf16 v[104:107], v[152:155], v[222:225], v[104:107]
	v_mfma_f32_16x16x32_bf16 v[84:87], v[156:159], v[218:221], v[84:87]
	v_mfma_f32_16x16x32_bf16 v[84:87], v[160:163], v[222:225], v[84:87]
	v_mfma_f32_16x16x32_bf16 v[68:71], v[156:159], v[226:229], v[68:71]
	v_mfma_f32_16x16x32_bf16 v[68:71], v[160:163], v[230:233], v[68:71]
	v_mfma_f32_16x16x32_bf16 v[72:75], v[148:151], v[226:229], v[72:75]
	v_mfma_f32_16x16x32_bf16 v[72:75], v[152:155], v[230:233], v[72:75]
	s_setprio 0
	s_barrier
; #define PG8_STAGE(bufoff, gbase, voff) do { _Pragma("unroll") for (int _i = 0; _i < 2; ++_i) \
;         __builtin_amdgcn_global_load_lds((const unsigned*)((const char*)(gbase) + (voff)[_i]), (PG8_LAS unsigned*)(lds + (bufoff) + ldsw + _i * 8192), 16, 0, 0); } while (0)
; #define PG8_LDA(dst, b, h) do { _Pragma("unroll") for (int m = 0; m < 4; ++m) _Pragma("unroll") for (int k = 0; k < 2; ++k) dst[m][k] = *(const PG8_LAS bf16x8*)(lds + PG8_SA(b, h) + aoff + m * 2048 + k * 1024); } while (0)
; #define PG8_MMA(ai, bj, At, Bt) do { __builtin_amdgcn_s_setprio(3); _Pragma("unroll") for (int m = 0; m < 4; ++m) _Pragma("unroll") for (int n = 0; n < 2; ++n) _Pragma("unroll") for (int k = 0; k < 2; ++k) \
;         acc[ai][bj][m][n] = __builtin_amdgcn_mfma_f32_16x16x32_bf16(Bt[n][k], At[m][k], acc[ai][bj][m][n], 0, 0, 0); __builtin_amdgcn_s_setprio(0); } while (0)
; #define PG8_WAIT_V(n) asm volatile("s_waitcnt vmcnt(" #n ")" ::: "memory")
; #define PG8_WAIT_L(n) asm volatile("s_waitcnt lgkmcnt(" #n ")" ::: "memory")
; #define PG8_BAR __builtin_amdgcn_s_barrier()
; #define PG8_SCHED __builtin_amdgcn_sched_barrier(0)
; template <class Epi, class Sched, bool ALIGN_EPI = false, bool SP2 = false>
; __device__ __forceinline__ void gemm_phase(PG8_LAS unsigned char* lds, const Gemm g, const Sched& S, const Epi& E) {
;     ...
;             PG8_LDA(At, 1, 1); PG8_STAGE(PG8_SB(1, 0), b3, voffB); PG8_STAGE(PG8_SB(1, 1), b3 + hstepB, voffB); PG8_STAGE(PG8_SA(1, 0), a3, voffA);
;             PG8_WAIT_V(8); PG8_WAIT_L(0); PG8_BAR; PG8_MMA(1, 0, At, B0); PG8_MMA(1, 1, At, B1); PG8_BAR; PG8_SCHED;
	s_mov_b32 m0, s77
	v_lshl_add_u64 v[234:235], v[234:235], 0, s[4:5]
	s_add_u32 s28, s28, 0x2b0080
	ds_read_b128 v[164:167], v207 offset:49152
	ds_read_b128 v[168:171], v207 offset:50176
	ds_read_b128 v[210:213], v207 offset:51200
	ds_read_b128 v[214:217], v207 offset:52224
	ds_read_b128 v[218:221], v207 offset:53248
	ds_read_b128 v[222:225], v207 offset:54272
	ds_read_b128 v[226:229], v207 offset:55296
	ds_read_b128 v[230:233], v207 offset:56320
	global_load_lds_dwordx4 v[234:235], off
	v_lshl_add_u64 v[234:235], v[236:237], 0, s[4:5]
	s_mov_b32 m0, s78
	s_addc_u32 s29, s29, 0
	global_load_lds_dwordx4 v[234:235], off
	v_lshl_add_u64 v[234:235], s[28:29], 0, v[174:175]
	s_mov_b32 m0, s79
	s_nop 0
	global_load_lds_dwordx4 v[234:235], off
	v_lshl_add_u64 v[234:235], s[28:29], 0, v[178:179]
	s_mov_b32 m0, s80
	s_nop 0
	global_load_lds_dwordx4 v[234:235], off
	v_lshl_add_u64 v[234:235], v[238:239], 0, s[4:5]
	s_mov_b32 m0, s57
	s_nop 0
	global_load_lds_dwordx4 v[234:235], off
	v_lshl_add_u64 v[234:235], v[240:241], 0, s[4:5]
	s_mov_b32 m0, s58
	s_nop 0
	global_load_lds_dwordx4 v[234:235], off
	s_waitcnt vmcnt(8)
	s_waitcnt lgkmcnt(0)
	s_barrier
	s_setprio 3
	v_mfma_f32_16x16x32_bf16 v[64:67], v[132:135], v[164:167], v[64:67]
	v_mfma_f32_16x16x32_bf16 v[64:67], v[136:139], v[168:171], v[64:67]
	v_mfma_f32_16x16x32_bf16 v[60:63], v[140:143], v[164:167], v[60:63]
	v_mfma_f32_16x16x32_bf16 v[60:63], v[144:147], v[168:171], v[60:63]
	v_mfma_f32_16x16x32_bf16 v[44:47], v[140:143], v[210:213], v[44:47]
	v_mfma_f32_16x16x32_bf16 v[44:47], v[144:147], v[214:217], v[44:47]
	v_mfma_f32_16x16x32_bf16 v[48:51], v[132:135], v[210:213], v[48:51]
	v_mfma_f32_16x16x32_bf16 v[48:51], v[136:139], v[214:217], v[48:51]
	v_mfma_f32_16x16x32_bf16 v[32:35], v[132:135], v[218:221], v[32:35]
	v_mfma_f32_16x16x32_bf16 v[32:35], v[136:139], v[222:225], v[32:35]
	v_mfma_f32_16x16x32_bf16 v[28:31], v[140:143], v[218:221], v[28:31]
	v_mfma_f32_16x16x32_bf16 v[28:31], v[144:147], v[222:225], v[28:31]
	v_mfma_f32_16x16x32_bf16 v[12:15], v[140:143], v[226:229], v[12:15]
	v_mfma_f32_16x16x32_bf16 v[12:15], v[144:147], v[230:233], v[12:15]
	v_mfma_f32_16x16x32_bf16 v[16:19], v[132:135], v[226:229], v[16:19]
	v_mfma_f32_16x16x32_bf16 v[16:19], v[136:139], v[230:233], v[16:19]
	v_mfma_f32_16x16x32_bf16 v[56:59], v[148:151], v[164:167], v[56:59]
	v_mfma_f32_16x16x32_bf16 v[56:59], v[152:155], v[168:171], v[56:59]
	v_mfma_f32_16x16x32_bf16 v[52:55], v[156:159], v[164:167], v[52:55]
	v_mfma_f32_16x16x32_bf16 v[52:55], v[160:163], v[168:171], v[52:55]
	v_mfma_f32_16x16x32_bf16 v[36:39], v[156:159], v[210:213], v[36:39]
	v_mfma_f32_16x16x32_bf16 v[36:39], v[160:163], v[214:217], v[36:39]
	v_mfma_f32_16x16x32_bf16 v[40:43], v[148:151], v[210:213], v[40:43]
	v_mfma_f32_16x16x32_bf16 v[40:43], v[152:155], v[214:217], v[40:43]
	v_mfma_f32_16x16x32_bf16 v[24:27], v[148:151], v[218:221], v[24:27]
	v_mfma_f32_16x16x32_bf16 v[24:27], v[152:155], v[222:225], v[24:27]
	v_mfma_f32_16x16x32_bf16 v[20:23], v[156:159], v[218:221], v[20:23]
	v_mfma_f32_16x16x32_bf16 v[20:23], v[160:163], v[222:225], v[20:23]
	v_mfma_f32_16x16x32_bf16 v[4:7], v[156:159], v[226:229], v[4:7]
	v_mfma_f32_16x16x32_bf16 v[4:7], v[160:163], v[230:233], v[4:7]
	v_mfma_f32_16x16x32_bf16 v[8:11], v[148:151], v[226:229], v[8:11]
	v_mfma_f32_16x16x32_bf16 v[8:11], v[152:155], v[230:233], v[8:11]
	s_setprio 0
	s_barrier
	s_add_i32 s61, s61, 2
	s_add_u32 s12, s12, 0x100
	s_addc_u32 s13, s13, 0
	s_cmpk_gt_u32 s61, 0xa9
	s_cbranch_scc1 .LBB0_978

; #define PG8_STAGE(bufoff, gbase, voff) do { _Pragma("unroll") for (int _i = 0; _i < 2; ++_i) \
;         __builtin_amdgcn_global_load_lds((const unsigned*)((const char*)(gbase) + (voff)[_i]), (PG8_LAS unsigned*)(lds + (bufoff) + ldsw + _i * 8192), 16, 0, 0); } while (0)
; #define PG8_LDA(dst, b, h) do { _Pragma("unroll") for (int m = 0; m < 4; ++m) _Pragma("unroll") for (int k = 0; k < 2; ++k) dst[m][k] = *(const PG8_LAS bf16x8*)(lds + PG8_SA(b, h) + aoff + m * 2048 + k * 1024); } while (0)
; #define PG8_LDB(dst, b, h) do { _Pragma("unroll") for (int n = 0; n < 2; ++n) _Pragma("unroll") for (int k = 0; k < 2; ++k) dst[n][k] = *(const PG8_LAS bf16x8*)(lds + PG8_SB(b, h) + boff + n * 2048 + k * 1024); } while (0)
; #define PG8_MMA(ai, bj, At, Bt) do { __builtin_amdgcn_s_setprio(3); _Pragma("unroll") for (int m = 0; m < 4; ++m) _Pragma("unroll") for (int n = 0; n < 2; ++n) _Pragma("unroll") for (int k = 0; k < 2; ++k) \
;         acc[ai][bj][m][n] = __builtin_amdgcn_mfma_f32_16x16x32_bf16(Bt[n][k], At[m][k], acc[ai][bj][m][n], 0, 0, 0); __builtin_amdgcn_s_setprio(0); } while (0)
; #define PG8_BAR __builtin_amdgcn_s_barrier()
; template <class Epi, class Sched, bool ALIGN_EPI = false, bool SP2 = false>
; __device__ __forceinline__ void gemm_phase(PG8_LAS unsigned char* lds, const Gemm g, const Sched& S, const Epi& E) {
;     ...
;         for (int t = 0; t < nt; t += 2) {
;             const bool last = (t == nt - 2);
;             const char* a1 = cA + (size_t)(t + 1) * kstep;
;             const char* a2 = last ? nA : cA + (size_t)(t + 2) * kstep; const char* b2 = last ? nB : cB + (size_t)(t + 2) * kstep;
;             const char* a3 = a2 + kstep; const char* b3 = b2 + kstep;
;             if (last && has_next) S.a_ready(nxt);
;             if constexpr (Epi::MIDK) { if (t == E.midk_step(nt)) E.midk(acc, cur, wr, wc, fr, fq); }
;             if constexpr (SP2) {
;             PG8_LDB(B0, 0, 0); PG8_LDB(B1, 0, 1); PG8_SCHED; PG8_LDA(At, 0, 0); PG8_STAGE(PG8_SA(1, 1), a1 + hstepA, voffA);
;             PG8_WAIT_V(8); PG8_WAIT_L(0); PG8_BAR; PG8_MMA(0, 0, At, B0); PG8_MMA(0, 1, At, B1); PG8_BAR; PG8_SCHED;
;             PG8_LDA(At, 0, 1); PG8_STAGE(PG8_SB(0, 0), b2, voffB); PG8_STAGE(PG8_SB(0, 1), b2 + hstepB, voffB); PG8_STAGE(PG8_SA(0, 0), a2, voffA);
;             PG8_WAIT_V(8); PG8_WAIT_L(0); PG8_BAR; PG8_MMA(1, 0, At, B0); PG8_MMA(1, 1, At, B1); PG8_BAR; PG8_SCHED;
.LBB0_1018:
	v_add_u32_e32 v142, s46, v189
	v_add_u32_e32 v158, s47, v189
	s_add_u32 s40, s20, s22
	ds_read_b128 v[130:133], v142
	ds_read_b128 v[134:137], v142 offset:1024
	ds_read_b128 v[138:141], v142 offset:2048
	ds_read_b128 v[142:145], v142 offset:3072
	ds_read_b128 v[146:149], v158
	ds_read_b128 v[150:153], v158 offset:1024
	ds_read_b128 v[154:157], v158 offset:2048
	ds_read_b128 v[158:161], v158 offset:3072
	s_addc_u32 s41, s21, s23
	s_add_u32 s40, s40, 0x21500100
	s_addc_u32 s41, s41, 0
	s_add_u32 s87, s44, s22
	s_addc_u32 s88, s45, s23
	s_cmpk_eq_i32 s22, 0x5500
	s_cselect_b32 s43, s17, s41
	s_cselect_b32 s42, s16, s40
	s_cselect_b32 s41, s11, s88
	s_cselect_b32 s40, s10, s87
	s_mov_b32 m0, s77
	v_lshl_add_u64 v[186:187], v[0:1], 0, s[22:23]
	ds_read_b128 v[162:165], v180
	ds_read_b128 v[166:169], v180 offset:1024
	ds_read_b128 v[182:185], v180 offset:2048
	ds_read_b128 v[190:193], v180 offset:3072
	ds_read_b128 v[194:197], v180 offset:4096
	ds_read_b128 v[208:211], v180 offset:5120
	ds_read_b128 v[212:215], v180 offset:6144
	ds_read_b128 v[216:219], v180 offset:7168
	global_load_lds_dwordx4 v[186:187], off
	v_lshl_add_u64 v[186:187], v[170:171], 0, s[22:23]
	s_mov_b32 m0, s78
	s_nop 0
	global_load_lds_dwordx4 v[186:187], off
	s_waitcnt vmcnt(8)
	s_waitcnt lgkmcnt(0)
	s_barrier
	s_setprio 3
	v_mfma_f32_16x16x32_bf16 v[126:129], v[130:133], v[162:165], v[126:129]
	v_mfma_f32_16x16x32_bf16 v[126:129], v[134:137], v[166:169], v[126:129]
	v_mfma_f32_16x16x32_bf16 v[122:125], v[138:141], v[162:165], v[122:125]
	v_mfma_f32_16x16x32_bf16 v[122:125], v[142:145], v[166:169], v[122:125]
	v_mfma_f32_16x16x32_bf16 v[94:97], v[138:141], v[182:185], v[94:97]
	v_mfma_f32_16x16x32_bf16 v[94:97], v[142:145], v[190:193], v[94:97]
	v_mfma_f32_16x16x32_bf16 v[98:101], v[130:133], v[182:185], v[98:101]
	v_mfma_f32_16x16x32_bf16 v[98:101], v[134:137], v[190:193], v[98:101]
	v_mfma_f32_16x16x32_bf16 v[110:113], v[130:133], v[194:197], v[110:113]
	v_mfma_f32_16x16x32_bf16 v[110:113], v[134:137], v[208:211], v[110:113]
	v_mfma_f32_16x16x32_bf16 v[106:109], v[138:141], v[194:197], v[106:109]
	v_mfma_f32_16x16x32_bf16 v[106:109], v[142:145], v[208:211], v[106:109]
	v_mfma_f32_16x16x32_bf16 v[74:77], v[138:141], v[212:215], v[74:77]
	v_mfma_f32_16x16x32_bf16 v[74:77], v[142:145], v[216:219], v[74:77]
	v_mfma_f32_16x16x32_bf16 v[78:81], v[130:133], v[212:215], v[78:81]
	v_mfma_f32_16x16x32_bf16 v[78:81], v[134:137], v[216:219], v[78:81]
	v_mfma_f32_16x16x32_bf16 v[118:121], v[146:149], v[162:165], v[118:121]
	v_mfma_f32_16x16x32_bf16 v[118:121], v[150:153], v[166:169], v[118:121]
	v_mfma_f32_16x16x32_bf16 v[114:117], v[154:157], v[162:165], v[114:117]
	v_mfma_f32_16x16x32_bf16 v[114:117], v[158:161], v[166:169], v[114:117]
	v_mfma_f32_16x16x32_bf16 v[86:89], v[154:157], v[182:185], v[86:89]
	v_mfma_f32_16x16x32_bf16 v[86:89], v[158:161], v[190:193], v[86:89]
	v_mfma_f32_16x16x32_bf16 v[90:93], v[146:149], v[182:185], v[90:93]
	v_mfma_f32_16x16x32_bf16 v[90:93], v[150:153], v[190:193], v[90:93]
	v_mfma_f32_16x16x32_bf16 v[102:105], v[146:149], v[194:197], v[102:105]
	v_mfma_f32_16x16x32_bf16 v[102:105], v[150:153], v[208:211], v[102:105]
	v_mfma_f32_16x16x32_bf16 v[82:85], v[154:157], v[194:197], v[82:85]
	v_mfma_f32_16x16x32_bf16 v[82:85], v[158:161], v[208:211], v[82:85]
	v_mfma_f32_16x16x32_bf16 v[66:69], v[154:157], v[212:215], v[66:69]
	v_mfma_f32_16x16x32_bf16 v[66:69], v[158:161], v[216:219], v[66:69]
	v_mfma_f32_16x16x32_bf16 v[70:73], v[146:149], v[212:215], v[70:73]
	v_mfma_f32_16x16x32_bf16 v[70:73], v[150:153], v[216:219], v[70:73]
	s_setprio 0
	s_barrier
	s_mov_b32 m0, s79
	v_lshl_add_u64 v[186:187], s[40:41], 0, v[174:175]
	s_add_u32 s88, s40, 0x2b0000
	ds_read_b128 v[162:165], v180 offset:16384
	ds_read_b128 v[166:169], v180 offset:17408
	ds_read_b128 v[182:185], v180 offset:18432
	ds_read_b128 v[190:193], v180 offset:19456
	ds_read_b128 v[194:197], v180 offset:20480
	ds_read_b128 v[208:211], v180 offset:21504
	ds_read_b128 v[212:215], v180 offset:22528
	ds_read_b128 v[216:219], v180 offset:23552
	global_load_lds_dwordx4 v[186:187], off
	v_lshl_add_u64 v[198:199], s[40:41], 0, v[178:179]
	s_mov_b32 m0, s80
	s_addc_u32 s89, s41, 0
	global_load_lds_dwordx4 v[198:199], off
	v_lshl_add_u64 v[204:205], s[88:89], 0, v[174:175]
	s_mov_b32 m0, s81
	v_lshl_add_u64 v[220:221], s[42:43], 0, v[176:177]
	global_load_lds_dwordx4 v[204:205], off
	v_lshl_add_u64 v[204:205], s[88:89], 0, v[178:179]
	s_mov_b32 m0, s82
	s_nop 0
	global_load_lds_dwordx4 v[204:205], off
	v_lshl_add_u64 v[204:205], s[42:43], 0, v[172:173]
	s_mov_b32 m0, s58
	s_nop 0
	global_load_lds_dwordx4 v[204:205], off
	s_mov_b32 m0, s60
	s_nop 0
	global_load_lds_dwordx4 v[220:221], off
	s_waitcnt vmcnt(8)
	s_waitcnt lgkmcnt(0)
	s_barrier
; #define PG8_STAGE(bufoff, gbase, voff) do { _Pragma("unroll") for (int _i = 0; _i < 2; ++_i) \
;         __builtin_amdgcn_global_load_lds((const unsigned*)((const char*)(gbase) + (voff)[_i]), (PG8_LAS unsigned*)(lds + (bufoff) + ldsw + _i * 8192), 16, 0, 0); } while (0)
; #define PG8_LDA(dst, b, h) do { _Pragma("unroll") for (int m = 0; m < 4; ++m) _Pragma("unroll") for (int k = 0; k < 2; ++k) dst[m][k] = *(const PG8_LAS bf16x8*)(lds + PG8_SA(b, h) + aoff + m * 2048 + k * 1024); } while (0)
; #define PG8_LDB(dst, b, h) do { _Pragma("unroll") for (int n = 0; n < 2; ++n) _Pragma("unroll") for (int k = 0; k < 2; ++k) dst[n][k] = *(const PG8_LAS bf16x8*)(lds + PG8_SB(b, h) + boff + n * 2048 + k * 1024); } while (0)
; #define PG8_MMA(ai, bj, At, Bt) do { __builtin_amdgcn_s_setprio(3); _Pragma("unroll") for (int m = 0; m < 4; ++m) _Pragma("unroll") for (int n = 0; n < 2; ++n) _Pragma("unroll") for (int k = 0; k < 2; ++k) \
;         acc[ai][bj][m][n] = __builtin_amdgcn_mfma_f32_16x16x32_bf16(Bt[n][k], At[m][k], acc[ai][bj][m][n], 0, 0, 0); __builtin_amdgcn_s_setprio(0); } while (0)
; #define PG8_WAIT_V(n) asm volatile("s_waitcnt vmcnt(" #n ")" ::: "memory")
; #define PG8_WAIT_L(n) asm volatile("s_waitcnt lgkmcnt(" #n ")" ::: "memory")
; #define PG8_BAR __builtin_amdgcn_s_barrier()
; #define PG8_SCHED __builtin_amdgcn_sched_barrier(0)
; template <class Epi, class Sched, bool ALIGN_EPI = false, bool SP2 = false>
; __device__ __forceinline__ void gemm_phase(PG8_LAS unsigned char* lds, const Gemm g, const Sched& S, const Epi& E) {
;     ...
;             PG8_WAIT_V(8); PG8_WAIT_L(0); PG8_BAR; PG8_MMA(1, 0, At, B0); PG8_MMA(1, 1, At, B1); PG8_BAR; PG8_SCHED;
;             PG8_LDB(B0, 1, 0); PG8_LDB(B1, 1, 1); PG8_SCHED; PG8_LDA(At, 1, 0); PG8_STAGE(PG8_SA(0, 1), a2 + hstepA, voffA);
;             PG8_WAIT_V(8); PG8_WAIT_L(0); PG8_BAR; PG8_MMA(0, 0, At, B0); PG8_MMA(0, 1, At, B1); PG8_BAR; PG8_SCHED;
	s_setprio 3
	v_mfma_f32_16x16x32_bf16 v[62:65], v[130:133], v[162:165], v[62:65]
	v_mfma_f32_16x16x32_bf16 v[62:65], v[134:137], v[166:169], v[62:65]
	v_mfma_f32_16x16x32_bf16 v[58:61], v[138:141], v[162:165], v[58:61]
	v_mfma_f32_16x16x32_bf16 v[58:61], v[142:145], v[166:169], v[58:61]
	v_mfma_f32_16x16x32_bf16 v[42:45], v[138:141], v[182:185], v[42:45]
	v_mfma_f32_16x16x32_bf16 v[42:45], v[142:145], v[190:193], v[42:45]
	v_mfma_f32_16x16x32_bf16 v[46:49], v[130:133], v[182:185], v[46:49]
	v_mfma_f32_16x16x32_bf16 v[46:49], v[134:137], v[190:193], v[46:49]
	v_mfma_f32_16x16x32_bf16 v[30:33], v[130:133], v[194:197], v[30:33]
	v_mfma_f32_16x16x32_bf16 v[30:33], v[134:137], v[208:211], v[30:33]
	v_mfma_f32_16x16x32_bf16 v[26:29], v[138:141], v[194:197], v[26:29]
	v_mfma_f32_16x16x32_bf16 v[26:29], v[142:145], v[208:211], v[26:29]
	v_mfma_f32_16x16x32_bf16 v[10:13], v[138:141], v[212:215], v[10:13]
	v_mfma_f32_16x16x32_bf16 v[10:13], v[142:145], v[216:219], v[10:13]
	v_mfma_f32_16x16x32_bf16 v[14:17], v[130:133], v[212:215], v[14:17]
	v_mfma_f32_16x16x32_bf16 v[14:17], v[134:137], v[216:219], v[14:17]
	v_mfma_f32_16x16x32_bf16 v[54:57], v[146:149], v[162:165], v[54:57]
	v_mfma_f32_16x16x32_bf16 v[54:57], v[150:153], v[166:169], v[54:57]
	v_mfma_f32_16x16x32_bf16 v[50:53], v[154:157], v[162:165], v[50:53]
	v_mfma_f32_16x16x32_bf16 v[50:53], v[158:161], v[166:169], v[50:53]
	v_mfma_f32_16x16x32_bf16 v[34:37], v[154:157], v[182:185], v[34:37]
	v_mfma_f32_16x16x32_bf16 v[34:37], v[158:161], v[190:193], v[34:37]
	v_mfma_f32_16x16x32_bf16 v[38:41], v[146:149], v[182:185], v[38:41]
	v_mfma_f32_16x16x32_bf16 v[38:41], v[150:153], v[190:193], v[38:41]
	v_mfma_f32_16x16x32_bf16 v[22:25], v[146:149], v[194:197], v[22:25]
	v_mfma_f32_16x16x32_bf16 v[22:25], v[150:153], v[208:211], v[22:25]
	v_mfma_f32_16x16x32_bf16 v[18:21], v[154:157], v[194:197], v[18:21]
	v_mfma_f32_16x16x32_bf16 v[18:21], v[158:161], v[208:211], v[18:21]
	v_mfma_f32_16x16x32_bf16 v[2:5], v[154:157], v[212:215], v[2:5]
	v_mfma_f32_16x16x32_bf16 v[2:5], v[158:161], v[216:219], v[2:5]
	v_mfma_f32_16x16x32_bf16 v[6:9], v[146:149], v[212:215], v[6:9]
	v_mfma_f32_16x16x32_bf16 v[6:9], v[150:153], v[216:219], v[6:9]
	s_setprio 0
	s_barrier
	v_add_u32_e32 v142, s52, v189
	v_add_u32_e32 v158, s53, v189
	ds_read_b128 v[130:133], v142
	ds_read_b128 v[134:137], v142 offset:1024
	ds_read_b128 v[138:141], v142 offset:2048
	ds_read_b128 v[142:145], v142 offset:3072
	ds_read_b128 v[146:149], v158
	ds_read_b128 v[150:153], v158 offset:1024
	ds_read_b128 v[154:157], v158 offset:2048
	ds_read_b128 v[158:161], v158 offset:3072
	s_add_u32 s42, s42, 0x2b0000
	s_addc_u32 s43, s43, 0
	s_mov_b32 m0, s61
	v_lshl_add_u64 v[222:223], s[42:43], 0, v[172:173]
	ds_read_b128 v[162:165], v180 offset:32768
	ds_read_b128 v[166:169], v180 offset:33792
	ds_read_b128 v[182:185], v180 offset:34816
	ds_read_b128 v[190:193], v180 offset:35840
	ds_read_b128 v[194:197], v180 offset:36864
	ds_read_b128 v[208:211], v180 offset:37888
	ds_read_b128 v[212:215], v180 offset:38912
	ds_read_b128 v[216:219], v180 offset:39936
	global_load_lds_dwordx4 v[222:223], off
	v_lshl_add_u64 v[222:223], s[42:43], 0, v[176:177]
	s_mov_b32 m0, s62
	s_nop 0
	global_load_lds_dwordx4 v[222:223], off
	s_waitcnt vmcnt(8)
	s_waitcnt lgkmcnt(0)
	s_barrier
	s_setprio 3
	v_mfma_f32_16x16x32_bf16 v[126:129], v[130:133], v[162:165], v[126:129]
	v_mfma_f32_16x16x32_bf16 v[126:129], v[134:137], v[166:169], v[126:129]
	v_mfma_f32_16x16x32_bf16 v[122:125], v[138:141], v[162:165], v[122:125]
	v_mfma_f32_16x16x32_bf16 v[122:125], v[142:145], v[166:169], v[122:125]
	v_mfma_f32_16x16x32_bf16 v[94:97], v[138:141], v[182:185], v[94:97]
	v_mfma_f32_16x16x32_bf16 v[94:97], v[142:145], v[190:193], v[94:97]
	v_mfma_f32_16x16x32_bf16 v[98:101], v[130:133], v[182:185], v[98:101]
	v_mfma_f32_16x16x32_bf16 v[98:101], v[134:137], v[190:193], v[98:101]
	v_mfma_f32_16x16x32_bf16 v[110:113], v[130:133], v[194:197], v[110:113]
	v_mfma_f32_16x16x32_bf16 v[110:113], v[134:137], v[208:211], v[110:113]
	v_mfma_f32_16x16x32_bf16 v[106:109], v[138:141], v[194:197], v[106:109]
	v_mfma_f32_16x16x32_bf16 v[106:109], v[142:145], v[208:211], v[106:109]
	v_mfma_f32_16x16x32_bf16 v[74:77], v[138:141], v[212:215], v[74:77]
	v_mfma_f32_16x16x32_bf16 v[74:77], v[142:145], v[216:219], v[74:77]
	v_mfma_f32_16x16x32_bf16 v[78:81], v[130:133], v[212:215], v[78:81]
	v_mfma_f32_16x16x32_bf16 v[78:81], v[134:137], v[216:219], v[78:81]
	v_mfma_f32_16x16x32_bf16 v[118:121], v[146:149], v[162:165], v[118:121]
	v_mfma_f32_16x16x32_bf16 v[118:121], v[150:153], v[166:169], v[118:121]
	v_mfma_f32_16x16x32_bf16 v[114:117], v[154:157], v[162:165], v[114:117]
	v_mfma_f32_16x16x32_bf16 v[114:117], v[158:161], v[166:169], v[114:117]
	v_mfma_f32_16x16x32_bf16 v[86:89], v[154:157], v[182:185], v[86:89]
	v_mfma_f32_16x16x32_bf16 v[86:89], v[158:161], v[190:193], v[86:89]
	v_mfma_f32_16x16x32_bf16 v[90:93], v[146:149], v[182:185], v[90:93]
	v_mfma_f32_16x16x32_bf16 v[90:93], v[150:153], v[190:193], v[90:93]
	v_mfma_f32_16x16x32_bf16 v[102:105], v[146:149], v[194:197], v[102:105]
	v_mfma_f32_16x16x32_bf16 v[102:105], v[150:153], v[208:211], v[102:105]
	v_mfma_f32_16x16x32_bf16 v[82:85], v[154:157], v[194:197], v[82:85]
	v_mfma_f32_16x16x32_bf16 v[82:85], v[158:161], v[208:211], v[82:85]
	v_mfma_f32_16x16x32_bf16 v[66:69], v[154:157], v[212:215], v[66:69]
	v_mfma_f32_16x16x32_bf16 v[66:69], v[158:161], v[216:219], v[66:69]
	v_mfma_f32_16x16x32_bf16 v[70:73], v[146:149], v[212:215], v[70:73]
	v_mfma_f32_16x16x32_bf16 v[70:73], v[150:153], v[216:219], v[70:73]
	s_setprio 0
	s_barrier
; #define PG8_STAGE(bufoff, gbase, voff) do { _Pragma("unroll") for (int _i = 0; _i < 2; ++_i) \
;         __builtin_amdgcn_global_load_lds((const unsigned*)((const char*)(gbase) + (voff)[_i]), (PG8_LAS unsigned*)(lds + (bufoff) + ldsw + _i * 8192), 16, 0, 0); } while (0)
; #define PG8_LDA(dst, b, h) do { _Pragma("unroll") for (int m = 0; m < 4; ++m) _Pragma("unroll") for (int k = 0; k < 2; ++k) dst[m][k] = *(const PG8_LAS bf16x8*)(lds + PG8_SA(b, h) + aoff + m * 2048 + k * 1024); } while (0)
; #define PG8_MMA(ai, bj, At, Bt) do { __builtin_amdgcn_s_setprio(3); _Pragma("unroll") for (int m = 0; m < 4; ++m) _Pragma("unroll") for (int n = 0; n < 2; ++n) _Pragma("unroll") for (int k = 0; k < 2; ++k) \
;         acc[ai][bj][m][n] = __builtin_amdgcn_mfma_f32_16x16x32_bf16(Bt[n][k], At[m][k], acc[ai][bj][m][n], 0, 0, 0); __builtin_amdgcn_s_setprio(0); } while (0)
; #define PG8_WAIT_V(n) asm volatile("s_waitcnt vmcnt(" #n ")" ::: "memory")
; #define PG8_WAIT_L(n) asm volatile("s_waitcnt lgkmcnt(" #n ")" ::: "memory")
; #define PG8_BAR __builtin_amdgcn_s_barrier()
; #define PG8_SCHED __builtin_amdgcn_sched_barrier(0)
; template <class Epi, class Sched, bool ALIGN_EPI = false, bool SP2 = false>
; __device__ __forceinline__ void gemm_phase(PG8_LAS unsigned char* lds, const Gemm g, const Sched& S, const Epi& E) {
;     ...
;             PG8_LDA(At, 1, 1); PG8_STAGE(PG8_SB(1, 0), b3, voffB); PG8_STAGE(PG8_SB(1, 1), b3 + hstepB, voffB); PG8_STAGE(PG8_SA(1, 0), a3, voffA);
;             PG8_WAIT_V(8); PG8_WAIT_L(0); PG8_BAR; PG8_MMA(1, 0, At, B0); PG8_MMA(1, 1, At, B1); PG8_BAR; PG8_SCHED;
	s_mov_b32 m0, s83
	v_lshl_add_u64 v[186:187], v[186:187], 0, s[18:19]
	s_add_u32 s40, s40, 0x2b0080
	ds_read_b128 v[162:165], v180 offset:49152
	ds_read_b128 v[166:169], v180 offset:50176
	ds_read_b128 v[182:185], v180 offset:51200
	ds_read_b128 v[190:193], v180 offset:52224
	ds_read_b128 v[194:197], v180 offset:53248
	ds_read_b128 v[208:211], v180 offset:54272
	ds_read_b128 v[212:215], v180 offset:55296
	ds_read_b128 v[216:219], v180 offset:56320
	global_load_lds_dwordx4 v[186:187], off
	v_lshl_add_u64 v[186:187], v[198:199], 0, s[18:19]
	s_mov_b32 m0, s84
	s_addc_u32 s41, s41, 0
	global_load_lds_dwordx4 v[186:187], off
	v_lshl_add_u64 v[186:187], s[40:41], 0, v[174:175]
	s_mov_b32 m0, s85
	s_nop 0
	global_load_lds_dwordx4 v[186:187], off
	v_lshl_add_u64 v[186:187], s[40:41], 0, v[178:179]
	s_mov_b32 m0, s86
	s_nop 0
	global_load_lds_dwordx4 v[186:187], off
	v_lshl_add_u64 v[186:187], v[204:205], 0, s[18:19]
	s_mov_b32 m0, s63
	s_nop 0
	global_load_lds_dwordx4 v[186:187], off
	v_lshl_add_u64 v[186:187], v[220:221], 0, s[18:19]
	s_mov_b32 m0, s64
	s_nop 0
	global_load_lds_dwordx4 v[186:187], off
	s_waitcnt vmcnt(8)
	s_waitcnt lgkmcnt(0)
	s_barrier
	s_setprio 3
	v_mfma_f32_16x16x32_bf16 v[62:65], v[130:133], v[162:165], v[62:65]
	v_mfma_f32_16x16x32_bf16 v[62:65], v[134:137], v[166:169], v[62:65]
	v_mfma_f32_16x16x32_bf16 v[58:61], v[138:141], v[162:165], v[58:61]
	v_mfma_f32_16x16x32_bf16 v[58:61], v[142:145], v[166:169], v[58:61]
	v_mfma_f32_16x16x32_bf16 v[42:45], v[138:141], v[182:185], v[42:45]
	v_mfma_f32_16x16x32_bf16 v[42:45], v[142:145], v[190:193], v[42:45]
	v_mfma_f32_16x16x32_bf16 v[46:49], v[130:133], v[182:185], v[46:49]
	v_mfma_f32_16x16x32_bf16 v[46:49], v[134:137], v[190:193], v[46:49]
	v_mfma_f32_16x16x32_bf16 v[30:33], v[130:133], v[194:197], v[30:33]
	v_mfma_f32_16x16x32_bf16 v[30:33], v[134:137], v[208:211], v[30:33]
	v_mfma_f32_16x16x32_bf16 v[26:29], v[138:141], v[194:197], v[26:29]
	v_mfma_f32_16x16x32_bf16 v[26:29], v[142:145], v[208:211], v[26:29]
	v_mfma_f32_16x16x32_bf16 v[10:13], v[138:141], v[212:215], v[10:13]
	v_mfma_f32_16x16x32_bf16 v[10:13], v[142:145], v[216:219], v[10:13]
	v_mfma_f32_16x16x32_bf16 v[14:17], v[130:133], v[212:215], v[14:17]
	v_mfma_f32_16x16x32_bf16 v[14:17], v[134:137], v[216:219], v[14:17]
	v_mfma_f32_16x16x32_bf16 v[54:57], v[146:149], v[162:165], v[54:57]
	v_mfma_f32_16x16x32_bf16 v[54:57], v[150:153], v[166:169], v[54:57]
	v_mfma_f32_16x16x32_bf16 v[50:53], v[154:157], v[162:165], v[50:53]
	v_mfma_f32_16x16x32_bf16 v[50:53], v[158:161], v[166:169], v[50:53]
	v_mfma_f32_16x16x32_bf16 v[34:37], v[154:157], v[182:185], v[34:37]
	v_mfma_f32_16x16x32_bf16 v[34:37], v[158:161], v[190:193], v[34:37]
	v_mfma_f32_16x16x32_bf16 v[38:41], v[146:149], v[182:185], v[38:41]
	v_mfma_f32_16x16x32_bf16 v[38:41], v[150:153], v[190:193], v[38:41]
	v_mfma_f32_16x16x32_bf16 v[22:25], v[146:149], v[194:197], v[22:25]
	v_mfma_f32_16x16x32_bf16 v[22:25], v[150:153], v[208:211], v[22:25]
	v_mfma_f32_16x16x32_bf16 v[18:21], v[154:157], v[194:197], v[18:21]
	v_mfma_f32_16x16x32_bf16 v[18:21], v[158:161], v[208:211], v[18:21]
	v_mfma_f32_16x16x32_bf16 v[2:5], v[154:157], v[212:215], v[2:5]
	v_mfma_f32_16x16x32_bf16 v[2:5], v[158:161], v[216:219], v[2:5]
	v_mfma_f32_16x16x32_bf16 v[6:9], v[146:149], v[212:215], v[6:9]
	v_mfma_f32_16x16x32_bf16 v[6:9], v[150:153], v[216:219], v[6:9]
	s_setprio 0
	s_barrier
	s_add_i32 s67, s67, 2
	s_add_u32 s22, s22, 0x100
	s_addc_u32 s23, s23, 0
	s_cmpk_gt_u32 s67, 0xa9
	s_cbranch_scc1 .LBB0_1021
